# indexer pass 0: first head's weighted relu as fma(w, r, +0) so an all-zero score keeps the +0 sign exactly like the baseline (tie order among zero scores)
# speedup vs baseline: 1.0044x; 1.0044x over previous
; #define LAS __attribute__((address_space(3)))
; __device__ __forceinline__ void sel_unit(LAS char* lds, int b, int u, const bf16_t* QI, const bf16_t* KIDX, const float* WIDX, unsigned long long* MASK) {
;     ...
;     const LAS float* wl = (const LAS float*)(lds + L_W) + q16;
;     __syncthreads();
;     const int nj = (c - wid + 8) >> 3;
;     u32x4 sc[8][4];
; #pragma unroll
;     for (int j = 0; j < 8; ++j) {
;         if (j < nj) {
;             int t = wid + 8 * j; asm volatile("" : "+s"(t));
; #pragma unroll
;             for (int kh = 0; kh < 2; ++kh) {
;             bf16x8 kf[2][2];
; #pragma unroll
;             for (int kb = 0; kb < 2; ++kb)
; #pragma unroll
;                 for (int ks = 0; ks < 2; ++ks) kf[kb][ks] = *(const bf16x8*)(KIDX + (rowbase + 64 * t + 32 * kh + 16 * kb + q16) * 64 + 32 * ks + 8 * kg);
; #pragma unroll
;             for (int kb = 0; kb < 2; ++kb) {
;                 f32x4 s = (f32x4){0.f, 0.f, 0.f, 0.f};
; #pragma unroll
;                 for (int hh = 0; hh < 8; ++hh) {
;                     f32x4 a = (f32x4){0.f, 0.f, 0.f, 0.f};
; #pragma unroll
;                     for (int ks = 0; ks < 2; ++ks) {
;                         const bf16x8 qv = *(const LAS bf16x8*)(lds + L_QI + q16 * 1024 + (((hh * 8 + 4 * ks + kg) ^ q16) << 4));
;                         a = __builtin_amdgcn_mfma_f32_16x16x32_bf16(kf[kb][ks], qv, a, 0, 0, 0);
;                     }
;                     const float wh = wl[hh * 16];
; #pragma unroll
;                     for (int i = 0; i < 4; ++i) s[i] += wh * fmaxf(a[i], 0.f);
.LBB0_656:
	s_or_b64 exec, exec, s[2:3]
	s_ashr_i32 s46, s47, 6
	s_sub_i32 s2, s34, s46
	s_add_i32 s2, s2, 8
	s_ashr_i32 s4, s2, 3
	v_bfe_u32 v2, v2, 4, 2
	v_lshl_add_u32 v60, v59, 2, 0
	v_or_b32_e32 v18, s0, v59
	s_movk_i32 s0, 0x3fc
	s_cmp_gt_i32 s4, 0
	v_lshlrev_b32_e32 v0, 4, v2
	v_mad_u32_u24 v150, v59, s0, v60
	s_movk_i32 s0, 0xfc04
	s_cselect_b64 s[22:23], -1, 0
	v_mov_b32_e32 v19, s1
	v_lshl_add_u64 v[20:21], s[62:63], 0, v[0:1]
	v_mad_i32_i24 v0, v59, s0, v150
	s_and_b64 vcc, exec, s[22:23]
	v_xor_b32_e32 v182, v2, v59
	v_bitop3_b32 v183, v2, v59, 4 bitop3:0x36
	v_add_u32_e32 v137, 0x8800, v60
	v_bitop3_b32 v184, v2, v59, 8 bitop3:0x36
	v_bitop3_b32 v185, v2, v59, 12 bitop3:0x36
	v_bitop3_b32 v179, v2, v59, 16 bitop3:0x36
	v_bitop3_b32 v180, v2, v59, 20 bitop3:0x36
	v_bitop3_b32 v176, v2, v59, 24 bitop3:0x36
	v_bitop3_b32 v159, v2, v59, 28 bitop3:0x36
	v_bitop3_b32 v158, v2, v59, 32 bitop3:0x36
	v_bitop3_b32 v157, v2, v59, 36 bitop3:0x36
	v_bitop3_b32 v156, v2, v59, 40 bitop3:0x36
	v_bitop3_b32 v155, v2, v59, 44 bitop3:0x36
	v_bitop3_b32 v154, v2, v59, 48 bitop3:0x36
	v_bitop3_b32 v153, v2, v59, 52 bitop3:0x36
	v_bitop3_b32 v152, v2, v59, 56 bitop3:0x36
	v_bitop3_b32 v151, v2, v59, 60 bitop3:0x36
	v_lshl_add_u32 v182, v182, 4, v150
	v_lshl_add_u32 v183, v183, 4, v150
	v_lshl_add_u32 v184, v184, 4, v150
	v_lshl_add_u32 v185, v185, 4, v150
	v_lshl_add_u32 v179, v179, 4, v150
	v_lshl_add_u32 v180, v180, 4, v150
	v_lshl_add_u32 v176, v176, 4, v150
	v_lshl_add_u32 v159, v159, 4, v150
	v_lshl_add_u32 v158, v158, 4, v150
	v_lshl_add_u32 v157, v157, 4, v150
	v_lshl_add_u32 v156, v156, 4, v150
	v_lshl_add_u32 v155, v155, 4, v150
	v_lshl_add_u32 v154, v154, 4, v150
	v_lshl_add_u32 v153, v153, 4, v150
	v_lshl_add_u32 v152, v152, 4, v150
	v_lshl_add_u32 v151, v151, 4, v150
	s_mov_b32 s0, s46
	s_lshl_b32 s0, s0, 6
	s_ashr_i32 s1, s0, 31
	v_lshl_add_u64 v[2:3], v[18:19], 0, s[0:1]
	v_lshlrev_b64 v[2:3], 7, v[2:3]
	v_lshl_add_u64 v[22:23], v[20:21], 0, v[2:3]
	v_bfrev_b32_e32 v8, 1
	global_load_dwordx4 v[26:29], v[22:23], off
	global_load_dwordx4 v[30:33], v[22:23], off offset:64
	global_load_dwordx4 v[34:37], v[22:23], off offset:2048
	global_load_dwordx4 v[38:41], v[22:23], off offset:2112
	s_waitcnt lgkmcnt(0)
	s_barrier
	s_cbranch_vccz .LBB0_658
	ds_read_b128 v[230:233], v182
	ds_read_b128 v[234:237], v183
	ds_read_b32 v6, v137 offset:320
	s_waitcnt vmcnt(0)
	v_add_co_u32_e32 v22, vcc, s96, v22
	s_nop 1
	v_addc_co_u32_e32 v23, vcc, 0, v23, vcc
	global_load_dwordx4 v[42:45], v[22:23], off
	global_load_dwordx4 v[46:49], v[22:23], off offset:64
	global_load_dwordx4 v[50:53], v[22:23], off offset:2048
	global_load_dwordx4 v[2:5], v[22:23], off offset:2112
	s_waitcnt lgkmcnt(1)
	v_mfma_f32_16x16x32_bf16 v[246:249], v[26:29], v[230:233], 0
	v_mfma_f32_16x16x32_bf16 v[250:253], v[34:37], v[230:233], 0
	v_mfma_f32_16x16x32_bf16 v[246:249], v[30:33], v[234:237], v[246:249]
	v_mfma_f32_16x16x32_bf16 v[250:253], v[38:41], v[234:237], v[250:253]
	ds_read_b128 v[238:241], v184
	ds_read_b128 v[242:245], v185
	ds_read_b32 v7, v137 offset:384
	s_waitcnt lgkmcnt(1)
	v_mfma_f32_16x16x32_bf16 v[206:209], v[26:29], v[238:241], 0
	v_mfma_f32_16x16x32_bf16 v[210:213], v[34:37], v[238:241], 0
	v_mfma_f32_16x16x32_bf16 v[206:209], v[30:33], v[242:245], v[206:209]
	v_mfma_f32_16x16x32_bf16 v[210:213], v[38:41], v[242:245], v[210:213]
	ds_read_b128 v[230:233], v179
	ds_read_b128 v[234:237], v180
	ds_read_b32 v217, v137 offset:448
	v_max_f32_e32 v9, 0, v246
	v_max_f32_e32 v200, 0, v247
	v_max_f32_e32 v201, 0, v248
	v_max_f32_e32 v216, 0, v249
	v_fma_f32 v62, v6, v9, 0
	v_fma_f32 v61, v6, v200, 0
	v_fma_f32 v64, v6, v201, 0
	v_fma_f32 v63, v6, v216, 0
	v_max_f32_e32 v9, 0, v250
	v_max_f32_e32 v200, 0, v251
	v_max_f32_e32 v201, 0, v252
	v_max_f32_e32 v216, 0, v253
	v_fma_f32 v66, v6, v9, 0
	v_fma_f32 v65, v6, v200, 0
	v_fma_f32 v68, v6, v201, 0
	v_fma_f32 v67, v6, v216, 0
	s_waitcnt lgkmcnt(1)
	v_mfma_f32_16x16x32_bf16 v[246:249], v[26:29], v[230:233], 0
	v_mfma_f32_16x16x32_bf16 v[250:253], v[34:37], v[230:233], 0
	v_mfma_f32_16x16x32_bf16 v[246:249], v[30:33], v[234:237], v[246:249]
	v_mfma_f32_16x16x32_bf16 v[250:253], v[38:41], v[234:237], v[250:253]
	ds_read_b128 v[238:241], v176
	ds_read_b128 v[242:245], v159
	ds_read_b32 v6, v137 offset:512
	v_max_f32_e32 v9, 0, v206
	v_max_f32_e32 v200, 0, v207
	v_max_f32_e32 v201, 0, v208
	v_max_f32_e32 v216, 0, v209
	v_fmac_f32_e32 v62, v7, v9
	v_fmac_f32_e32 v61, v7, v200
	v_fmac_f32_e32 v64, v7, v201
	v_fmac_f32_e32 v63, v7, v216
	v_max_f32_e32 v9, 0, v210
	v_max_f32_e32 v200, 0, v211
	v_max_f32_e32 v201, 0, v212
	v_max_f32_e32 v216, 0, v213
	v_fmac_f32_e32 v66, v7, v9
	v_fmac_f32_e32 v65, v7, v200
	v_fmac_f32_e32 v68, v7, v201
	v_fmac_f32_e32 v67, v7, v216
	s_waitcnt lgkmcnt(1)
	v_mfma_f32_16x16x32_bf16 v[206:209], v[26:29], v[238:241], 0
	v_mfma_f32_16x16x32_bf16 v[210:213], v[34:37], v[238:241], 0
	v_mfma_f32_16x16x32_bf16 v[206:209], v[30:33], v[242:245], v[206:209]
	v_mfma_f32_16x16x32_bf16 v[210:213], v[38:41], v[242:245], v[210:213]
	ds_read_b128 v[230:233], v158
	ds_read_b128 v[234:237], v157
	ds_read_b32 v7, v137 offset:576
	v_max_f32_e32 v9, 0, v246
	v_max_f32_e32 v200, 0, v247
	v_max_f32_e32 v201, 0, v248
	v_max_f32_e32 v216, 0, v249
	v_fmac_f32_e32 v62, v217, v9
	v_fmac_f32_e32 v61, v217, v200
	v_fmac_f32_e32 v64, v217, v201
	v_fmac_f32_e32 v63, v217, v216
	v_max_f32_e32 v9, 0, v250
	v_max_f32_e32 v200, 0, v251
	v_max_f32_e32 v201, 0, v252
	v_max_f32_e32 v216, 0, v253
	v_fmac_f32_e32 v66, v217, v9
	v_fmac_f32_e32 v65, v217, v200
	v_fmac_f32_e32 v68, v217, v201
	v_fmac_f32_e32 v67, v217, v216
	s_waitcnt lgkmcnt(1)
; #define LAS __attribute__((address_space(3)))
; __device__ __forceinline__ unsigned fkey(float f) { const unsigned u = __float_as_uint(f); return (u & 0x80000000u) ? ~u : (u | 0x80000000u); }
; #define SEL_HADD(idx_) __hip_atomic_fetch_add(&hist[(idx_)], 1u, __ATOMIC_RELAXED, __HIP_MEMORY_SCOPE_WORKGROUP)
; __device__ __forceinline__ void sel_unit(LAS char* lds, int b, int u, const bf16_t* QI, const bf16_t* KIDX, const float* WIDX, unsigned long long* MASK) {
;     ...
;             for (int kb = 0; kb < 2; ++kb) {
;                 f32x4 s = (f32x4){0.f, 0.f, 0.f, 0.f};
; #pragma unroll
;                 for (int hh = 0; hh < 8; ++hh) {
;                     f32x4 a = (f32x4){0.f, 0.f, 0.f, 0.f};
; #pragma unroll
;                     for (int ks = 0; ks < 2; ++ks) {
;                         const bf16x8 qv = *(const LAS bf16x8*)(lds + L_QI + q16 * 1024 + (((hh * 8 + 4 * ks + kg) ^ q16) << 4));
;                         a = __builtin_amdgcn_mfma_f32_16x16x32_bf16(kf[kb][ks], qv, a, 0, 0, 0);
;                     }
;                     const float wh = wl[hh * 16];
; #pragma unroll
;                     for (int i = 0; i < 4; ++i) s[i] += wh * fmaxf(a[i], 0.f);
;                 }
;                 u32x4 kk; kk.x = fkey(s[0]); kk.y = fkey(s[1]); kk.z = fkey(s[2]); kk.w = fkey(s[3]);
;                 sc[j][2 * kh + kb] = kk;
; #pragma unroll
;                 for (int i = 0; i < 4; ++i) SEL_HADD((kk[i] >> 24) * 16 + q16);
;                 __builtin_amdgcn_sched_barrier(0);
	v_mfma_f32_16x16x32_bf16 v[246:249], v[26:29], v[230:233], 0
	v_mfma_f32_16x16x32_bf16 v[250:253], v[34:37], v[230:233], 0
	v_mfma_f32_16x16x32_bf16 v[246:249], v[30:33], v[234:237], v[246:249]
	v_mfma_f32_16x16x32_bf16 v[250:253], v[38:41], v[234:237], v[250:253]
	ds_read_b128 v[238:241], v156
	ds_read_b128 v[242:245], v155
	ds_read_b32 v217, v137 offset:640
	v_max_f32_e32 v9, 0, v206
	v_max_f32_e32 v200, 0, v207
	v_max_f32_e32 v201, 0, v208
	v_max_f32_e32 v216, 0, v209
	v_fmac_f32_e32 v62, v6, v9
	v_fmac_f32_e32 v61, v6, v200
	v_fmac_f32_e32 v64, v6, v201
	v_fmac_f32_e32 v63, v6, v216
	v_max_f32_e32 v9, 0, v210
	v_max_f32_e32 v200, 0, v211
	v_max_f32_e32 v201, 0, v212
	v_max_f32_e32 v216, 0, v213
	v_fmac_f32_e32 v66, v6, v9
	v_fmac_f32_e32 v65, v6, v200
	v_fmac_f32_e32 v68, v6, v201
	v_fmac_f32_e32 v67, v6, v216
	s_waitcnt lgkmcnt(1)
	v_mfma_f32_16x16x32_bf16 v[206:209], v[26:29], v[238:241], 0
	v_mfma_f32_16x16x32_bf16 v[210:213], v[34:37], v[238:241], 0
	v_mfma_f32_16x16x32_bf16 v[206:209], v[30:33], v[242:245], v[206:209]
	v_mfma_f32_16x16x32_bf16 v[210:213], v[38:41], v[242:245], v[210:213]
	ds_read_b128 v[230:233], v154
	ds_read_b128 v[234:237], v153
	ds_read_b32 v6, v137 offset:704
	v_max_f32_e32 v9, 0, v246
	v_max_f32_e32 v200, 0, v247
	v_max_f32_e32 v201, 0, v248
	v_max_f32_e32 v216, 0, v249
	v_fmac_f32_e32 v62, v7, v9
	v_fmac_f32_e32 v61, v7, v200
	v_fmac_f32_e32 v64, v7, v201
	v_fmac_f32_e32 v63, v7, v216
	v_max_f32_e32 v9, 0, v250
	v_max_f32_e32 v200, 0, v251
	v_max_f32_e32 v201, 0, v252
	v_max_f32_e32 v216, 0, v253
	v_fmac_f32_e32 v66, v7, v9
	v_fmac_f32_e32 v65, v7, v200
	v_fmac_f32_e32 v68, v7, v201
	v_fmac_f32_e32 v67, v7, v216
	s_waitcnt lgkmcnt(1)
	v_mfma_f32_16x16x32_bf16 v[246:249], v[26:29], v[230:233], 0
	v_mfma_f32_16x16x32_bf16 v[250:253], v[34:37], v[230:233], 0
	v_mfma_f32_16x16x32_bf16 v[246:249], v[30:33], v[234:237], v[246:249]
	v_mfma_f32_16x16x32_bf16 v[250:253], v[38:41], v[234:237], v[250:253]
	ds_read_b128 v[238:241], v152
	ds_read_b128 v[242:245], v151
	ds_read_b32 v7, v137 offset:768
	v_max_f32_e32 v9, 0, v206
	v_max_f32_e32 v200, 0, v207
	v_max_f32_e32 v201, 0, v208
	v_max_f32_e32 v216, 0, v209
	v_fmac_f32_e32 v62, v217, v9
	v_fmac_f32_e32 v61, v217, v200
	v_fmac_f32_e32 v64, v217, v201
	v_fmac_f32_e32 v63, v217, v216
	v_max_f32_e32 v9, 0, v210
	v_max_f32_e32 v200, 0, v211
	v_max_f32_e32 v201, 0, v212
	v_max_f32_e32 v216, 0, v213
	v_fmac_f32_e32 v66, v217, v9
	v_fmac_f32_e32 v65, v217, v200
	v_fmac_f32_e32 v68, v217, v201
	v_fmac_f32_e32 v67, v217, v216
	s_waitcnt lgkmcnt(1)
	v_mfma_f32_16x16x32_bf16 v[206:209], v[26:29], v[238:241], 0
	v_mfma_f32_16x16x32_bf16 v[210:213], v[34:37], v[238:241], 0
	v_mfma_f32_16x16x32_bf16 v[206:209], v[30:33], v[242:245], v[206:209]
	v_mfma_f32_16x16x32_bf16 v[210:213], v[38:41], v[242:245], v[210:213]
	v_max_f32_e32 v9, 0, v246
	v_max_f32_e32 v200, 0, v247
	v_max_f32_e32 v201, 0, v248
	v_max_f32_e32 v216, 0, v249
	v_fmac_f32_e32 v62, v6, v9
	v_fmac_f32_e32 v61, v6, v200
	v_fmac_f32_e32 v64, v6, v201
	v_fmac_f32_e32 v63, v6, v216
	v_max_f32_e32 v9, 0, v250
	v_max_f32_e32 v200, 0, v251
	v_max_f32_e32 v201, 0, v252
	v_max_f32_e32 v216, 0, v253
	v_fmac_f32_e32 v66, v6, v9
	v_fmac_f32_e32 v65, v6, v200
	v_fmac_f32_e32 v68, v6, v201
	v_fmac_f32_e32 v67, v6, v216
	s_waitcnt lgkmcnt(0)
	v_max_f32_e32 v9, 0, v206
	v_max_f32_e32 v200, 0, v207
	v_max_f32_e32 v201, 0, v208
	v_max_f32_e32 v216, 0, v209
	v_fmac_f32_e32 v62, v7, v9
	v_fmac_f32_e32 v61, v7, v200
	v_fmac_f32_e32 v64, v7, v201
	v_fmac_f32_e32 v63, v7, v216
	v_max_f32_e32 v9, 0, v210
	v_max_f32_e32 v200, 0, v211
	v_max_f32_e32 v201, 0, v212
	v_max_f32_e32 v216, 0, v213
	v_fmac_f32_e32 v66, v7, v9
	v_fmac_f32_e32 v65, v7, v200
	v_fmac_f32_e32 v68, v7, v201
	v_fmac_f32_e32 v67, v7, v216
	v_ashrrev_i32_e32 v9, 31, v62
	v_bitop3_b32 v62, v9, v62, v8 bitop3:0x36
	v_ashrrev_i32_e32 v200, 31, v61
	v_bitop3_b32 v61, v200, v61, v8 bitop3:0x36
	v_ashrrev_i32_e32 v201, 31, v64
	v_bitop3_b32 v64, v201, v64, v8 bitop3:0x36
	v_ashrrev_i32_e32 v216, 31, v63
	v_bitop3_b32 v63, v216, v63, v8 bitop3:0x36
	v_ashrrev_i32_e32 v9, 31, v66
	v_bitop3_b32 v66, v9, v66, v8 bitop3:0x36
	v_ashrrev_i32_e32 v200, 31, v65
	v_bitop3_b32 v65, v200, v65, v8 bitop3:0x36
	v_ashrrev_i32_e32 v201, 31, v68
	v_bitop3_b32 v68, v201, v68, v8 bitop3:0x36
	v_ashrrev_i32_e32 v216, 31, v67
	v_bitop3_b32 v67, v216, v67, v8 bitop3:0x36
	v_lshrrev_b32_e32 v9, 24, v62
	v_lshl_add_u32 v9, v9, 6, v0
	ds_add_u32 v9, v205 offset:16384
	v_lshrrev_b32_e32 v200, 24, v61
	v_lshl_add_u32 v200, v200, 6, v0
	ds_add_u32 v200, v205 offset:16384
	v_lshrrev_b32_e32 v201, 24, v64
	v_lshl_add_u32 v201, v201, 6, v0
	ds_add_u32 v201, v205 offset:16384
	v_lshrrev_b32_e32 v216, 24, v63
	v_lshl_add_u32 v216, v216, 6, v0
	ds_add_u32 v216, v205 offset:16384
	v_lshrrev_b32_e32 v9, 24, v66
	v_lshl_add_u32 v9, v9, 6, v0
	ds_add_u32 v9, v205 offset:16384
	v_lshrrev_b32_e32 v200, 24, v65
	v_lshl_add_u32 v200, v200, 6, v0
	ds_add_u32 v200, v205 offset:16384
	v_lshrrev_b32_e32 v201, 24, v68
	v_lshl_add_u32 v201, v201, 6, v0
	ds_add_u32 v201, v205 offset:16384
	v_lshrrev_b32_e32 v216, 24, v67
	v_lshl_add_u32 v216, v216, 6, v0
	ds_add_u32 v216, v205 offset:16384
	ds_read_b128 v[230:233], v182
	ds_read_b128 v[234:237], v183
	ds_read_b32 v6, v137 offset:320
	s_waitcnt vmcnt(0)
	s_cmp_lt_i32 s4, 2
	s_cbranch_scc1 .Lp0_nopf_0
	v_add_co_u32_e32 v22, vcc, 0xf000, v22
	s_nop 1
	v_addc_co_u32_e32 v23, vcc, 0, v23, vcc
	global_load_dwordx4 v[26:29], v[22:23], off
	global_load_dwordx4 v[30:33], v[22:23], off offset:64
	global_load_dwordx4 v[34:37], v[22:23], off offset:2048
	global_load_dwordx4 v[38:41], v[22:23], off offset:2112
; #define LAS __attribute__((address_space(3)))
; __device__ __forceinline__ unsigned fkey(float f) { const unsigned u = __float_as_uint(f); return (u & 0x80000000u) ? ~u : (u | 0x80000000u); }
; __device__ __forceinline__ void sel_unit(LAS char* lds, int b, int u, const bf16_t* QI, const bf16_t* KIDX, const float* WIDX, unsigned long long* MASK) {
;     ...
;             for (int kb = 0; kb < 2; ++kb) {
;                 f32x4 s = (f32x4){0.f, 0.f, 0.f, 0.f};
; #pragma unroll
;                 for (int hh = 0; hh < 8; ++hh) {
;                     f32x4 a = (f32x4){0.f, 0.f, 0.f, 0.f};
; #pragma unroll
;                     for (int ks = 0; ks < 2; ++ks) {
;                         const bf16x8 qv = *(const LAS bf16x8*)(lds + L_QI + q16 * 1024 + (((hh * 8 + 4 * ks + kg) ^ q16) << 4));
;                         a = __builtin_amdgcn_mfma_f32_16x16x32_bf16(kf[kb][ks], qv, a, 0, 0, 0);
;                     }
;                     const float wh = wl[hh * 16];
; #pragma unroll
;                     for (int i = 0; i < 4; ++i) s[i] += wh * fmaxf(a[i], 0.f);
;                 }
;                 u32x4 kk; kk.x = fkey(s[0]); kk.y = fkey(s[1]); kk.z = fkey(s[2]); kk.w = fkey(s[3]);
;                 sc[j][2 * kh + kb] = kk;
.Lp0_nopf_0:
	s_waitcnt lgkmcnt(1)
	v_mfma_f32_16x16x32_bf16 v[246:249], v[42:45], v[230:233], 0
	v_mfma_f32_16x16x32_bf16 v[250:253], v[50:53], v[230:233], 0
	v_mfma_f32_16x16x32_bf16 v[246:249], v[46:49], v[234:237], v[246:249]
	v_mfma_f32_16x16x32_bf16 v[250:253], v[2:5], v[234:237], v[250:253]
	ds_read_b128 v[238:241], v184
	ds_read_b128 v[242:245], v185
	ds_read_b32 v7, v137 offset:384
	s_waitcnt lgkmcnt(1)
	v_mfma_f32_16x16x32_bf16 v[206:209], v[42:45], v[238:241], 0
	v_mfma_f32_16x16x32_bf16 v[210:213], v[50:53], v[238:241], 0
	v_mfma_f32_16x16x32_bf16 v[206:209], v[46:49], v[242:245], v[206:209]
	v_mfma_f32_16x16x32_bf16 v[210:213], v[2:5], v[242:245], v[210:213]
	ds_read_b128 v[230:233], v179
	ds_read_b128 v[234:237], v180
	ds_read_b32 v217, v137 offset:448
	v_max_f32_e32 v9, 0, v246
	v_max_f32_e32 v200, 0, v247
	v_max_f32_e32 v201, 0, v248
	v_max_f32_e32 v216, 0, v249
	v_fma_f32 v70, v6, v9, 0
	v_fma_f32 v69, v6, v200, 0
	v_fma_f32 v72, v6, v201, 0
	v_fma_f32 v71, v6, v216, 0
	v_max_f32_e32 v9, 0, v250
	v_max_f32_e32 v200, 0, v251
	v_max_f32_e32 v201, 0, v252
	v_max_f32_e32 v216, 0, v253
	v_fma_f32 v74, v6, v9, 0
	v_fma_f32 v73, v6, v200, 0
	v_fma_f32 v76, v6, v201, 0
	v_fma_f32 v75, v6, v216, 0
	s_waitcnt lgkmcnt(1)
	v_mfma_f32_16x16x32_bf16 v[246:249], v[42:45], v[230:233], 0
	v_mfma_f32_16x16x32_bf16 v[250:253], v[50:53], v[230:233], 0
	v_mfma_f32_16x16x32_bf16 v[246:249], v[46:49], v[234:237], v[246:249]
	v_mfma_f32_16x16x32_bf16 v[250:253], v[2:5], v[234:237], v[250:253]
	ds_read_b128 v[238:241], v176
	ds_read_b128 v[242:245], v159
	ds_read_b32 v6, v137 offset:512
	v_max_f32_e32 v9, 0, v206
	v_max_f32_e32 v200, 0, v207
	v_max_f32_e32 v201, 0, v208
	v_max_f32_e32 v216, 0, v209
	v_fmac_f32_e32 v70, v7, v9
	v_fmac_f32_e32 v69, v7, v200
	v_fmac_f32_e32 v72, v7, v201
	v_fmac_f32_e32 v71, v7, v216
	v_max_f32_e32 v9, 0, v210
	v_max_f32_e32 v200, 0, v211
	v_max_f32_e32 v201, 0, v212
	v_max_f32_e32 v216, 0, v213
	v_fmac_f32_e32 v74, v7, v9
	v_fmac_f32_e32 v73, v7, v200
	v_fmac_f32_e32 v76, v7, v201
	v_fmac_f32_e32 v75, v7, v216
	s_waitcnt lgkmcnt(1)
	v_mfma_f32_16x16x32_bf16 v[206:209], v[42:45], v[238:241], 0
	v_mfma_f32_16x16x32_bf16 v[210:213], v[50:53], v[238:241], 0
	v_mfma_f32_16x16x32_bf16 v[206:209], v[46:49], v[242:245], v[206:209]
	v_mfma_f32_16x16x32_bf16 v[210:213], v[2:5], v[242:245], v[210:213]
	ds_read_b128 v[230:233], v158
	ds_read_b128 v[234:237], v157
	ds_read_b32 v7, v137 offset:576
	v_max_f32_e32 v9, 0, v246
	v_max_f32_e32 v200, 0, v247
	v_max_f32_e32 v201, 0, v248
	v_max_f32_e32 v216, 0, v249
	v_fmac_f32_e32 v70, v217, v9
	v_fmac_f32_e32 v69, v217, v200
	v_fmac_f32_e32 v72, v217, v201
	v_fmac_f32_e32 v71, v217, v216
	v_max_f32_e32 v9, 0, v250
	v_max_f32_e32 v200, 0, v251
	v_max_f32_e32 v201, 0, v252
	v_max_f32_e32 v216, 0, v253
	v_fmac_f32_e32 v74, v217, v9
	v_fmac_f32_e32 v73, v217, v200
	v_fmac_f32_e32 v76, v217, v201
	v_fmac_f32_e32 v75, v217, v216
	s_waitcnt lgkmcnt(1)
	v_mfma_f32_16x16x32_bf16 v[246:249], v[42:45], v[230:233], 0
	v_mfma_f32_16x16x32_bf16 v[250:253], v[50:53], v[230:233], 0
	v_mfma_f32_16x16x32_bf16 v[246:249], v[46:49], v[234:237], v[246:249]
	v_mfma_f32_16x16x32_bf16 v[250:253], v[2:5], v[234:237], v[250:253]
	ds_read_b128 v[238:241], v156
	ds_read_b128 v[242:245], v155
	ds_read_b32 v217, v137 offset:640
	v_max_f32_e32 v9, 0, v206
	v_max_f32_e32 v200, 0, v207
	v_max_f32_e32 v201, 0, v208
	v_max_f32_e32 v216, 0, v209
	v_fmac_f32_e32 v70, v6, v9
	v_fmac_f32_e32 v69, v6, v200
	v_fmac_f32_e32 v72, v6, v201
	v_fmac_f32_e32 v71, v6, v216
	v_max_f32_e32 v9, 0, v210
	v_max_f32_e32 v200, 0, v211
	v_max_f32_e32 v201, 0, v212
	v_max_f32_e32 v216, 0, v213
	v_fmac_f32_e32 v74, v6, v9
	v_fmac_f32_e32 v73, v6, v200
	v_fmac_f32_e32 v76, v6, v201
	v_fmac_f32_e32 v75, v6, v216
	s_waitcnt lgkmcnt(1)
	v_mfma_f32_16x16x32_bf16 v[206:209], v[42:45], v[238:241], 0
	v_mfma_f32_16x16x32_bf16 v[210:213], v[50:53], v[238:241], 0
	v_mfma_f32_16x16x32_bf16 v[206:209], v[46:49], v[242:245], v[206:209]
	v_mfma_f32_16x16x32_bf16 v[210:213], v[2:5], v[242:245], v[210:213]
	ds_read_b128 v[230:233], v154
	ds_read_b128 v[234:237], v153
	ds_read_b32 v6, v137 offset:704
	v_max_f32_e32 v9, 0, v246
	v_max_f32_e32 v200, 0, v247
	v_max_f32_e32 v201, 0, v248
	v_max_f32_e32 v216, 0, v249
	v_fmac_f32_e32 v70, v7, v9
	v_fmac_f32_e32 v69, v7, v200
	v_fmac_f32_e32 v72, v7, v201
	v_fmac_f32_e32 v71, v7, v216
	v_max_f32_e32 v9, 0, v250
	v_max_f32_e32 v200, 0, v251
	v_max_f32_e32 v201, 0, v252
	v_max_f32_e32 v216, 0, v253
	v_fmac_f32_e32 v74, v7, v9
	v_fmac_f32_e32 v73, v7, v200
	v_fmac_f32_e32 v76, v7, v201
	v_fmac_f32_e32 v75, v7, v216
	s_waitcnt lgkmcnt(1)
	v_mfma_f32_16x16x32_bf16 v[246:249], v[42:45], v[230:233], 0
	v_mfma_f32_16x16x32_bf16 v[250:253], v[50:53], v[230:233], 0
	v_mfma_f32_16x16x32_bf16 v[246:249], v[46:49], v[234:237], v[246:249]
	v_mfma_f32_16x16x32_bf16 v[250:253], v[2:5], v[234:237], v[250:253]
	ds_read_b128 v[238:241], v152
	ds_read_b128 v[242:245], v151
	ds_read_b32 v7, v137 offset:768
	v_max_f32_e32 v9, 0, v206
	v_max_f32_e32 v200, 0, v207
	v_max_f32_e32 v201, 0, v208
	v_max_f32_e32 v216, 0, v209
	v_fmac_f32_e32 v70, v217, v9
	v_fmac_f32_e32 v69, v217, v200
	v_fmac_f32_e32 v72, v217, v201
	v_fmac_f32_e32 v71, v217, v216
	v_max_f32_e32 v9, 0, v210
	v_max_f32_e32 v200, 0, v211
	v_max_f32_e32 v201, 0, v212
	v_max_f32_e32 v216, 0, v213
	v_fmac_f32_e32 v74, v217, v9
	v_fmac_f32_e32 v73, v217, v200
	v_fmac_f32_e32 v76, v217, v201
	v_fmac_f32_e32 v75, v217, v216
	s_waitcnt lgkmcnt(1)
; #define LAS __attribute__((address_space(3)))
; __device__ __forceinline__ unsigned fkey(float f) { const unsigned u = __float_as_uint(f); return (u & 0x80000000u) ? ~u : (u | 0x80000000u); }
; #define SEL_HADD(idx_) __hip_atomic_fetch_add(&hist[(idx_)], 1u, __ATOMIC_RELAXED, __HIP_MEMORY_SCOPE_WORKGROUP)
; __device__ __forceinline__ void sel_unit(LAS char* lds, int b, int u, const bf16_t* QI, const bf16_t* KIDX, const float* WIDX, unsigned long long* MASK) {
;     ...
;     for (int j = 0; j < 8; ++j) {
;         if (j < nj) {
;             int t = wid + 8 * j; asm volatile("" : "+s"(t));
; #pragma unroll
;             for (int kh = 0; kh < 2; ++kh) {
;             bf16x8 kf[2][2];
; #pragma unroll
;             for (int kb = 0; kb < 2; ++kb)
; #pragma unroll
;                 for (int ks = 0; ks < 2; ++ks) kf[kb][ks] = *(const bf16x8*)(KIDX + (rowbase + 64 * t + 32 * kh + 16 * kb + q16) * 64 + 32 * ks + 8 * kg);
; #pragma unroll
;             for (int kb = 0; kb < 2; ++kb) {
;                 f32x4 s = (f32x4){0.f, 0.f, 0.f, 0.f};
; #pragma unroll
;                 for (int hh = 0; hh < 8; ++hh) {
;                     f32x4 a = (f32x4){0.f, 0.f, 0.f, 0.f};
; #pragma unroll
;                     for (int ks = 0; ks < 2; ++ks) {
;                         const bf16x8 qv = *(const LAS bf16x8*)(lds + L_QI + q16 * 1024 + (((hh * 8 + 4 * ks + kg) ^ q16) << 4));
;                         a = __builtin_amdgcn_mfma_f32_16x16x32_bf16(kf[kb][ks], qv, a, 0, 0, 0);
;                     }
;                     const float wh = wl[hh * 16];
; #pragma unroll
;                     for (int i = 0; i < 4; ++i) s[i] += wh * fmaxf(a[i], 0.f);
;                 }
;                 u32x4 kk; kk.x = fkey(s[0]); kk.y = fkey(s[1]); kk.z = fkey(s[2]); kk.w = fkey(s[3]);
;                 sc[j][2 * kh + kb] = kk;
; #pragma unroll
;                 for (int i = 0; i < 4; ++i) SEL_HADD((kk[i] >> 24) * 16 + q16);
;                 __builtin_amdgcn_sched_barrier(0);
	v_mfma_f32_16x16x32_bf16 v[206:209], v[42:45], v[238:241], 0
	v_mfma_f32_16x16x32_bf16 v[210:213], v[50:53], v[238:241], 0
	v_mfma_f32_16x16x32_bf16 v[206:209], v[46:49], v[242:245], v[206:209]
	v_mfma_f32_16x16x32_bf16 v[210:213], v[2:5], v[242:245], v[210:213]
	v_max_f32_e32 v9, 0, v246
	v_max_f32_e32 v200, 0, v247
	v_max_f32_e32 v201, 0, v248
	v_max_f32_e32 v216, 0, v249
	v_fmac_f32_e32 v70, v6, v9
	v_fmac_f32_e32 v69, v6, v200
	v_fmac_f32_e32 v72, v6, v201
	v_fmac_f32_e32 v71, v6, v216
	v_max_f32_e32 v9, 0, v250
	v_max_f32_e32 v200, 0, v251
	v_max_f32_e32 v201, 0, v252
	v_max_f32_e32 v216, 0, v253
	v_fmac_f32_e32 v74, v6, v9
	v_fmac_f32_e32 v73, v6, v200
	v_fmac_f32_e32 v76, v6, v201
	v_fmac_f32_e32 v75, v6, v216
	s_waitcnt lgkmcnt(0)
	v_max_f32_e32 v9, 0, v206
	v_max_f32_e32 v200, 0, v207
	v_max_f32_e32 v201, 0, v208
	v_max_f32_e32 v216, 0, v209
	v_fmac_f32_e32 v70, v7, v9
	v_fmac_f32_e32 v69, v7, v200
	v_fmac_f32_e32 v72, v7, v201
	v_fmac_f32_e32 v71, v7, v216
	v_max_f32_e32 v9, 0, v210
	v_max_f32_e32 v200, 0, v211
	v_max_f32_e32 v201, 0, v212
	v_max_f32_e32 v216, 0, v213
	v_fmac_f32_e32 v74, v7, v9
	v_fmac_f32_e32 v73, v7, v200
	v_fmac_f32_e32 v76, v7, v201
	v_fmac_f32_e32 v75, v7, v216
	v_ashrrev_i32_e32 v9, 31, v70
	v_bitop3_b32 v70, v9, v70, v8 bitop3:0x36
	v_ashrrev_i32_e32 v200, 31, v69
	v_bitop3_b32 v69, v200, v69, v8 bitop3:0x36
	v_ashrrev_i32_e32 v201, 31, v72
	v_bitop3_b32 v72, v201, v72, v8 bitop3:0x36
	v_ashrrev_i32_e32 v216, 31, v71
	v_bitop3_b32 v71, v216, v71, v8 bitop3:0x36
	v_ashrrev_i32_e32 v9, 31, v74
	v_bitop3_b32 v74, v9, v74, v8 bitop3:0x36
	v_ashrrev_i32_e32 v200, 31, v73
	v_bitop3_b32 v73, v200, v73, v8 bitop3:0x36
	v_ashrrev_i32_e32 v201, 31, v76
	v_bitop3_b32 v76, v201, v76, v8 bitop3:0x36
	v_ashrrev_i32_e32 v216, 31, v75
	v_bitop3_b32 v75, v216, v75, v8 bitop3:0x36
	v_lshrrev_b32_e32 v9, 24, v70
	v_lshl_add_u32 v9, v9, 6, v0
	ds_add_u32 v9, v205 offset:16384
	v_lshrrev_b32_e32 v200, 24, v69
	v_lshl_add_u32 v200, v200, 6, v0
	ds_add_u32 v200, v205 offset:16384
	v_lshrrev_b32_e32 v201, 24, v72
	v_lshl_add_u32 v201, v201, 6, v0
	ds_add_u32 v201, v205 offset:16384
	v_lshrrev_b32_e32 v216, 24, v71
	v_lshl_add_u32 v216, v216, 6, v0
	ds_add_u32 v216, v205 offset:16384
	v_lshrrev_b32_e32 v9, 24, v74
	v_lshl_add_u32 v9, v9, 6, v0
	ds_add_u32 v9, v205 offset:16384
	v_lshrrev_b32_e32 v200, 24, v73
	v_lshl_add_u32 v200, v200, 6, v0
	ds_add_u32 v200, v205 offset:16384
	v_lshrrev_b32_e32 v201, 24, v76
	v_lshl_add_u32 v201, v201, 6, v0
	ds_add_u32 v201, v205 offset:16384
	v_lshrrev_b32_e32 v216, 24, v75
	v_lshl_add_u32 v216, v216, 6, v0
	ds_add_u32 v216, v205 offset:16384
.LBB0_658:
	s_cmp_gt_i32 s4, 1
	s_cselect_b64 s[18:19], -1, 0
	s_cmp_lt_i32 s4, 2
	s_cbranch_scc1 .LBB0_660
	ds_read_b128 v[230:233], v182
	ds_read_b128 v[234:237], v183
	ds_read_b32 v6, v137 offset:320
	s_waitcnt vmcnt(0)
	v_add_co_u32_e32 v22, vcc, s96, v22
	s_nop 1
	v_addc_co_u32_e32 v23, vcc, 0, v23, vcc
	global_load_dwordx4 v[42:45], v[22:23], off
	global_load_dwordx4 v[46:49], v[22:23], off offset:64
	global_load_dwordx4 v[50:53], v[22:23], off offset:2048
	global_load_dwordx4 v[2:5], v[22:23], off offset:2112
	s_waitcnt lgkmcnt(1)
	v_mfma_f32_16x16x32_bf16 v[246:249], v[26:29], v[230:233], 0
	v_mfma_f32_16x16x32_bf16 v[250:253], v[34:37], v[230:233], 0
	v_mfma_f32_16x16x32_bf16 v[246:249], v[30:33], v[234:237], v[246:249]
	v_mfma_f32_16x16x32_bf16 v[250:253], v[38:41], v[234:237], v[250:253]
	ds_read_b128 v[238:241], v184
	ds_read_b128 v[242:245], v185
	ds_read_b32 v7, v137 offset:384
	s_waitcnt lgkmcnt(1)
	v_mfma_f32_16x16x32_bf16 v[206:209], v[26:29], v[238:241], 0
	v_mfma_f32_16x16x32_bf16 v[210:213], v[34:37], v[238:241], 0
	v_mfma_f32_16x16x32_bf16 v[206:209], v[30:33], v[242:245], v[206:209]
	v_mfma_f32_16x16x32_bf16 v[210:213], v[38:41], v[242:245], v[210:213]
	ds_read_b128 v[230:233], v179
	ds_read_b128 v[234:237], v180
	ds_read_b32 v217, v137 offset:448
	v_max_f32_e32 v9, 0, v246
	v_max_f32_e32 v200, 0, v247
	v_max_f32_e32 v201, 0, v248
	v_max_f32_e32 v216, 0, v249
	v_fma_f32 v78, v6, v9, 0
	v_fma_f32 v77, v6, v200, 0
	v_fma_f32 v80, v6, v201, 0
	v_fma_f32 v79, v6, v216, 0
	v_max_f32_e32 v9, 0, v250
	v_max_f32_e32 v200, 0, v251
	v_max_f32_e32 v201, 0, v252
	v_max_f32_e32 v216, 0, v253
	v_fma_f32 v82, v6, v9, 0
	v_fma_f32 v81, v6, v200, 0
	v_fma_f32 v84, v6, v201, 0
	v_fma_f32 v83, v6, v216, 0
	s_waitcnt lgkmcnt(1)
	v_mfma_f32_16x16x32_bf16 v[246:249], v[26:29], v[230:233], 0
	v_mfma_f32_16x16x32_bf16 v[250:253], v[34:37], v[230:233], 0
	v_mfma_f32_16x16x32_bf16 v[246:249], v[30:33], v[234:237], v[246:249]
	v_mfma_f32_16x16x32_bf16 v[250:253], v[38:41], v[234:237], v[250:253]
	ds_read_b128 v[238:241], v176
	ds_read_b128 v[242:245], v159
	ds_read_b32 v6, v137 offset:512
	v_max_f32_e32 v9, 0, v206
	v_max_f32_e32 v200, 0, v207
	v_max_f32_e32 v201, 0, v208
	v_max_f32_e32 v216, 0, v209
	v_fmac_f32_e32 v78, v7, v9
	v_fmac_f32_e32 v77, v7, v200
	v_fmac_f32_e32 v80, v7, v201
	v_fmac_f32_e32 v79, v7, v216
	v_max_f32_e32 v9, 0, v210
	v_max_f32_e32 v200, 0, v211
	v_max_f32_e32 v201, 0, v212
	v_max_f32_e32 v216, 0, v213
	v_fmac_f32_e32 v82, v7, v9
	v_fmac_f32_e32 v81, v7, v200
	v_fmac_f32_e32 v84, v7, v201
	v_fmac_f32_e32 v83, v7, v216
	s_waitcnt lgkmcnt(1)
; #define LAS __attribute__((address_space(3)))
; __device__ __forceinline__ unsigned fkey(float f) { const unsigned u = __float_as_uint(f); return (u & 0x80000000u) ? ~u : (u | 0x80000000u); }
; #define SEL_HADD(idx_) __hip_atomic_fetch_add(&hist[(idx_)], 1u, __ATOMIC_RELAXED, __HIP_MEMORY_SCOPE_WORKGROUP)
; __device__ __forceinline__ void sel_unit(LAS char* lds, int b, int u, const bf16_t* QI, const bf16_t* KIDX, const float* WIDX, unsigned long long* MASK) {
;     ...
;             for (int kb = 0; kb < 2; ++kb) {
;                 f32x4 s = (f32x4){0.f, 0.f, 0.f, 0.f};
; #pragma unroll
;                 for (int hh = 0; hh < 8; ++hh) {
;                     f32x4 a = (f32x4){0.f, 0.f, 0.f, 0.f};
; #pragma unroll
;                     for (int ks = 0; ks < 2; ++ks) {
;                         const bf16x8 qv = *(const LAS bf16x8*)(lds + L_QI + q16 * 1024 + (((hh * 8 + 4 * ks + kg) ^ q16) << 4));
;                         a = __builtin_amdgcn_mfma_f32_16x16x32_bf16(kf[kb][ks], qv, a, 0, 0, 0);
;                     }
;                     const float wh = wl[hh * 16];
; #pragma unroll
;                     for (int i = 0; i < 4; ++i) s[i] += wh * fmaxf(a[i], 0.f);
;                 }
;                 u32x4 kk; kk.x = fkey(s[0]); kk.y = fkey(s[1]); kk.z = fkey(s[2]); kk.w = fkey(s[3]);
;                 sc[j][2 * kh + kb] = kk;
; #pragma unroll
;                 for (int i = 0; i < 4; ++i) SEL_HADD((kk[i] >> 24) * 16 + q16);
;                 __builtin_amdgcn_sched_barrier(0);
	v_mfma_f32_16x16x32_bf16 v[206:209], v[26:29], v[238:241], 0
	v_mfma_f32_16x16x32_bf16 v[210:213], v[34:37], v[238:241], 0
	v_mfma_f32_16x16x32_bf16 v[206:209], v[30:33], v[242:245], v[206:209]
	v_mfma_f32_16x16x32_bf16 v[210:213], v[38:41], v[242:245], v[210:213]
	ds_read_b128 v[230:233], v158
	ds_read_b128 v[234:237], v157
	ds_read_b32 v7, v137 offset:576
	v_max_f32_e32 v9, 0, v246
	v_max_f32_e32 v200, 0, v247
	v_max_f32_e32 v201, 0, v248
	v_max_f32_e32 v216, 0, v249
	v_fmac_f32_e32 v78, v217, v9
	v_fmac_f32_e32 v77, v217, v200
	v_fmac_f32_e32 v80, v217, v201
	v_fmac_f32_e32 v79, v217, v216
	v_max_f32_e32 v9, 0, v250
	v_max_f32_e32 v200, 0, v251
	v_max_f32_e32 v201, 0, v252
	v_max_f32_e32 v216, 0, v253
	v_fmac_f32_e32 v82, v217, v9
	v_fmac_f32_e32 v81, v217, v200
	v_fmac_f32_e32 v84, v217, v201
	v_fmac_f32_e32 v83, v217, v216
	s_waitcnt lgkmcnt(1)
	v_mfma_f32_16x16x32_bf16 v[246:249], v[26:29], v[230:233], 0
	v_mfma_f32_16x16x32_bf16 v[250:253], v[34:37], v[230:233], 0
	v_mfma_f32_16x16x32_bf16 v[246:249], v[30:33], v[234:237], v[246:249]
	v_mfma_f32_16x16x32_bf16 v[250:253], v[38:41], v[234:237], v[250:253]
	ds_read_b128 v[238:241], v156
	ds_read_b128 v[242:245], v155
	ds_read_b32 v217, v137 offset:640
	v_max_f32_e32 v9, 0, v206
	v_max_f32_e32 v200, 0, v207
	v_max_f32_e32 v201, 0, v208
	v_max_f32_e32 v216, 0, v209
	v_fmac_f32_e32 v78, v6, v9
	v_fmac_f32_e32 v77, v6, v200
	v_fmac_f32_e32 v80, v6, v201
	v_fmac_f32_e32 v79, v6, v216
	v_max_f32_e32 v9, 0, v210
	v_max_f32_e32 v200, 0, v211
	v_max_f32_e32 v201, 0, v212
	v_max_f32_e32 v216, 0, v213
	v_fmac_f32_e32 v82, v6, v9
	v_fmac_f32_e32 v81, v6, v200
	v_fmac_f32_e32 v84, v6, v201
	v_fmac_f32_e32 v83, v6, v216
	s_waitcnt lgkmcnt(1)
	v_mfma_f32_16x16x32_bf16 v[206:209], v[26:29], v[238:241], 0
	v_mfma_f32_16x16x32_bf16 v[210:213], v[34:37], v[238:241], 0
	v_mfma_f32_16x16x32_bf16 v[206:209], v[30:33], v[242:245], v[206:209]
	v_mfma_f32_16x16x32_bf16 v[210:213], v[38:41], v[242:245], v[210:213]
	ds_read_b128 v[230:233], v154
	ds_read_b128 v[234:237], v153
	ds_read_b32 v6, v137 offset:704
	v_max_f32_e32 v9, 0, v246
	v_max_f32_e32 v200, 0, v247
	v_max_f32_e32 v201, 0, v248
	v_max_f32_e32 v216, 0, v249
	v_fmac_f32_e32 v78, v7, v9
	v_fmac_f32_e32 v77, v7, v200
	v_fmac_f32_e32 v80, v7, v201
	v_fmac_f32_e32 v79, v7, v216
	v_max_f32_e32 v9, 0, v250
	v_max_f32_e32 v200, 0, v251
	v_max_f32_e32 v201, 0, v252
	v_max_f32_e32 v216, 0, v253
	v_fmac_f32_e32 v82, v7, v9
	v_fmac_f32_e32 v81, v7, v200
	v_fmac_f32_e32 v84, v7, v201
	v_fmac_f32_e32 v83, v7, v216
	s_waitcnt lgkmcnt(1)
	v_mfma_f32_16x16x32_bf16 v[246:249], v[26:29], v[230:233], 0
	v_mfma_f32_16x16x32_bf16 v[250:253], v[34:37], v[230:233], 0
	v_mfma_f32_16x16x32_bf16 v[246:249], v[30:33], v[234:237], v[246:249]
	v_mfma_f32_16x16x32_bf16 v[250:253], v[38:41], v[234:237], v[250:253]
	ds_read_b128 v[238:241], v152
	ds_read_b128 v[242:245], v151
	ds_read_b32 v7, v137 offset:768
	v_max_f32_e32 v9, 0, v206
	v_max_f32_e32 v200, 0, v207
	v_max_f32_e32 v201, 0, v208
	v_max_f32_e32 v216, 0, v209
	v_fmac_f32_e32 v78, v217, v9
	v_fmac_f32_e32 v77, v217, v200
	v_fmac_f32_e32 v80, v217, v201
	v_fmac_f32_e32 v79, v217, v216
	v_max_f32_e32 v9, 0, v210
	v_max_f32_e32 v200, 0, v211
	v_max_f32_e32 v201, 0, v212
	v_max_f32_e32 v216, 0, v213
	v_fmac_f32_e32 v82, v217, v9
	v_fmac_f32_e32 v81, v217, v200
	v_fmac_f32_e32 v84, v217, v201
	v_fmac_f32_e32 v83, v217, v216
	s_waitcnt lgkmcnt(1)
	v_mfma_f32_16x16x32_bf16 v[206:209], v[26:29], v[238:241], 0
	v_mfma_f32_16x16x32_bf16 v[210:213], v[34:37], v[238:241], 0
	v_mfma_f32_16x16x32_bf16 v[206:209], v[30:33], v[242:245], v[206:209]
	v_mfma_f32_16x16x32_bf16 v[210:213], v[38:41], v[242:245], v[210:213]
	v_max_f32_e32 v9, 0, v246
	v_max_f32_e32 v200, 0, v247
	v_max_f32_e32 v201, 0, v248
	v_max_f32_e32 v216, 0, v249
	v_fmac_f32_e32 v78, v6, v9
	v_fmac_f32_e32 v77, v6, v200
	v_fmac_f32_e32 v80, v6, v201
	v_fmac_f32_e32 v79, v6, v216
	v_max_f32_e32 v9, 0, v250
	v_max_f32_e32 v200, 0, v251
	v_max_f32_e32 v201, 0, v252
	v_max_f32_e32 v216, 0, v253
	v_fmac_f32_e32 v82, v6, v9
	v_fmac_f32_e32 v81, v6, v200
	v_fmac_f32_e32 v84, v6, v201
	v_fmac_f32_e32 v83, v6, v216
	s_waitcnt lgkmcnt(0)
	v_max_f32_e32 v9, 0, v206
	v_max_f32_e32 v200, 0, v207
	v_max_f32_e32 v201, 0, v208
	v_max_f32_e32 v216, 0, v209
	v_fmac_f32_e32 v78, v7, v9
	v_fmac_f32_e32 v77, v7, v200
	v_fmac_f32_e32 v80, v7, v201
	v_fmac_f32_e32 v79, v7, v216
	v_max_f32_e32 v9, 0, v210
	v_max_f32_e32 v200, 0, v211
	v_max_f32_e32 v201, 0, v212
	v_max_f32_e32 v216, 0, v213
	v_fmac_f32_e32 v82, v7, v9
	v_fmac_f32_e32 v81, v7, v200
	v_fmac_f32_e32 v84, v7, v201
	v_fmac_f32_e32 v83, v7, v216
	v_ashrrev_i32_e32 v9, 31, v78
	v_bitop3_b32 v78, v9, v78, v8 bitop3:0x36
	v_ashrrev_i32_e32 v200, 31, v77
	v_bitop3_b32 v77, v200, v77, v8 bitop3:0x36
	v_ashrrev_i32_e32 v201, 31, v80
	v_bitop3_b32 v80, v201, v80, v8 bitop3:0x36
	v_ashrrev_i32_e32 v216, 31, v79
	v_bitop3_b32 v79, v216, v79, v8 bitop3:0x36
	v_ashrrev_i32_e32 v9, 31, v82
	v_bitop3_b32 v82, v9, v82, v8 bitop3:0x36
	v_ashrrev_i32_e32 v200, 31, v81
	v_bitop3_b32 v81, v200, v81, v8 bitop3:0x36
	v_ashrrev_i32_e32 v201, 31, v84
	v_bitop3_b32 v84, v201, v84, v8 bitop3:0x36
	v_ashrrev_i32_e32 v216, 31, v83
	v_bitop3_b32 v83, v216, v83, v8 bitop3:0x36
	v_lshrrev_b32_e32 v9, 24, v78
	v_lshl_add_u32 v9, v9, 6, v0
	ds_add_u32 v9, v205 offset:16384
	v_lshrrev_b32_e32 v200, 24, v77
	v_lshl_add_u32 v200, v200, 6, v0
	ds_add_u32 v200, v205 offset:16384
	v_lshrrev_b32_e32 v201, 24, v80
	v_lshl_add_u32 v201, v201, 6, v0
	ds_add_u32 v201, v205 offset:16384
	v_lshrrev_b32_e32 v216, 24, v79
	v_lshl_add_u32 v216, v216, 6, v0
	ds_add_u32 v216, v205 offset:16384
	v_lshrrev_b32_e32 v9, 24, v82
	v_lshl_add_u32 v9, v9, 6, v0
	ds_add_u32 v9, v205 offset:16384
	v_lshrrev_b32_e32 v200, 24, v81
	v_lshl_add_u32 v200, v200, 6, v0
	ds_add_u32 v200, v205 offset:16384
	v_lshrrev_b32_e32 v201, 24, v84
	v_lshl_add_u32 v201, v201, 6, v0
	ds_add_u32 v201, v205 offset:16384
	v_lshrrev_b32_e32 v216, 24, v83
	v_lshl_add_u32 v216, v216, 6, v0
	ds_add_u32 v216, v205 offset:16384
	ds_read_b128 v[230:233], v182
	ds_read_b128 v[234:237], v183
	ds_read_b32 v6, v137 offset:320
	s_waitcnt vmcnt(0)
	s_cmp_lt_i32 s4, 3
	s_cbranch_scc1 .Lp0_nopf_1
	v_add_co_u32_e32 v22, vcc, 0xf000, v22
	s_nop 1
	v_addc_co_u32_e32 v23, vcc, 0, v23, vcc
	global_load_dwordx4 v[26:29], v[22:23], off
	global_load_dwordx4 v[30:33], v[22:23], off offset:64
	global_load_dwordx4 v[34:37], v[22:23], off offset:2048
	global_load_dwordx4 v[38:41], v[22:23], off offset:2112
; #define LAS __attribute__((address_space(3)))
; __device__ __forceinline__ unsigned fkey(float f) { const unsigned u = __float_as_uint(f); return (u & 0x80000000u) ? ~u : (u | 0x80000000u); }
; __device__ __forceinline__ void sel_unit(LAS char* lds, int b, int u, const bf16_t* QI, const bf16_t* KIDX, const float* WIDX, unsigned long long* MASK) {
;     ...
;             for (int kb = 0; kb < 2; ++kb) {
;                 f32x4 s = (f32x4){0.f, 0.f, 0.f, 0.f};
; #pragma unroll
;                 for (int hh = 0; hh < 8; ++hh) {
;                     f32x4 a = (f32x4){0.f, 0.f, 0.f, 0.f};
; #pragma unroll
;                     for (int ks = 0; ks < 2; ++ks) {
;                         const bf16x8 qv = *(const LAS bf16x8*)(lds + L_QI + q16 * 1024 + (((hh * 8 + 4 * ks + kg) ^ q16) << 4));
;                         a = __builtin_amdgcn_mfma_f32_16x16x32_bf16(kf[kb][ks], qv, a, 0, 0, 0);
;                     }
;                     const float wh = wl[hh * 16];
; #pragma unroll
;                     for (int i = 0; i < 4; ++i) s[i] += wh * fmaxf(a[i], 0.f);
;                 }
;                 u32x4 kk; kk.x = fkey(s[0]); kk.y = fkey(s[1]); kk.z = fkey(s[2]); kk.w = fkey(s[3]);
;                 sc[j][2 * kh + kb] = kk;
.Lp0_nopf_1:
	s_waitcnt lgkmcnt(1)
	v_mfma_f32_16x16x32_bf16 v[246:249], v[42:45], v[230:233], 0
	v_mfma_f32_16x16x32_bf16 v[250:253], v[50:53], v[230:233], 0
	v_mfma_f32_16x16x32_bf16 v[246:249], v[46:49], v[234:237], v[246:249]
	v_mfma_f32_16x16x32_bf16 v[250:253], v[2:5], v[234:237], v[250:253]
	ds_read_b128 v[238:241], v184
	ds_read_b128 v[242:245], v185
	ds_read_b32 v7, v137 offset:384
	s_waitcnt lgkmcnt(1)
	v_mfma_f32_16x16x32_bf16 v[206:209], v[42:45], v[238:241], 0
	v_mfma_f32_16x16x32_bf16 v[210:213], v[50:53], v[238:241], 0
	v_mfma_f32_16x16x32_bf16 v[206:209], v[46:49], v[242:245], v[206:209]
	v_mfma_f32_16x16x32_bf16 v[210:213], v[2:5], v[242:245], v[210:213]
	ds_read_b128 v[230:233], v179
	ds_read_b128 v[234:237], v180
	ds_read_b32 v217, v137 offset:448
	v_max_f32_e32 v9, 0, v246
	v_max_f32_e32 v200, 0, v247
	v_max_f32_e32 v201, 0, v248
	v_max_f32_e32 v216, 0, v249
	v_fma_f32 v86, v6, v9, 0
	v_fma_f32 v85, v6, v200, 0
	v_fma_f32 v88, v6, v201, 0
	v_fma_f32 v87, v6, v216, 0
	v_max_f32_e32 v9, 0, v250
	v_max_f32_e32 v200, 0, v251
	v_max_f32_e32 v201, 0, v252
	v_max_f32_e32 v216, 0, v253
	v_fma_f32 v90, v6, v9, 0
	v_fma_f32 v89, v6, v200, 0
	v_fma_f32 v92, v6, v201, 0
	v_fma_f32 v91, v6, v216, 0
	s_waitcnt lgkmcnt(1)
	v_mfma_f32_16x16x32_bf16 v[246:249], v[42:45], v[230:233], 0
	v_mfma_f32_16x16x32_bf16 v[250:253], v[50:53], v[230:233], 0
	v_mfma_f32_16x16x32_bf16 v[246:249], v[46:49], v[234:237], v[246:249]
	v_mfma_f32_16x16x32_bf16 v[250:253], v[2:5], v[234:237], v[250:253]
	ds_read_b128 v[238:241], v176
	ds_read_b128 v[242:245], v159
	ds_read_b32 v6, v137 offset:512
	v_max_f32_e32 v9, 0, v206
	v_max_f32_e32 v200, 0, v207
	v_max_f32_e32 v201, 0, v208
	v_max_f32_e32 v216, 0, v209
	v_fmac_f32_e32 v86, v7, v9
	v_fmac_f32_e32 v85, v7, v200
	v_fmac_f32_e32 v88, v7, v201
	v_fmac_f32_e32 v87, v7, v216
	v_max_f32_e32 v9, 0, v210
	v_max_f32_e32 v200, 0, v211
	v_max_f32_e32 v201, 0, v212
	v_max_f32_e32 v216, 0, v213
	v_fmac_f32_e32 v90, v7, v9
	v_fmac_f32_e32 v89, v7, v200
	v_fmac_f32_e32 v92, v7, v201
	v_fmac_f32_e32 v91, v7, v216
	s_waitcnt lgkmcnt(1)
	v_mfma_f32_16x16x32_bf16 v[206:209], v[42:45], v[238:241], 0
	v_mfma_f32_16x16x32_bf16 v[210:213], v[50:53], v[238:241], 0
	v_mfma_f32_16x16x32_bf16 v[206:209], v[46:49], v[242:245], v[206:209]
	v_mfma_f32_16x16x32_bf16 v[210:213], v[2:5], v[242:245], v[210:213]
	ds_read_b128 v[230:233], v158
	ds_read_b128 v[234:237], v157
	ds_read_b32 v7, v137 offset:576
	v_max_f32_e32 v9, 0, v246
	v_max_f32_e32 v200, 0, v247
	v_max_f32_e32 v201, 0, v248
	v_max_f32_e32 v216, 0, v249
	v_fmac_f32_e32 v86, v217, v9
	v_fmac_f32_e32 v85, v217, v200
	v_fmac_f32_e32 v88, v217, v201
	v_fmac_f32_e32 v87, v217, v216
	v_max_f32_e32 v9, 0, v250
	v_max_f32_e32 v200, 0, v251
	v_max_f32_e32 v201, 0, v252
	v_max_f32_e32 v216, 0, v253
	v_fmac_f32_e32 v90, v217, v9
	v_fmac_f32_e32 v89, v217, v200
	v_fmac_f32_e32 v92, v217, v201
	v_fmac_f32_e32 v91, v217, v216
	s_waitcnt lgkmcnt(1)
	v_mfma_f32_16x16x32_bf16 v[246:249], v[42:45], v[230:233], 0
	v_mfma_f32_16x16x32_bf16 v[250:253], v[50:53], v[230:233], 0
	v_mfma_f32_16x16x32_bf16 v[246:249], v[46:49], v[234:237], v[246:249]
	v_mfma_f32_16x16x32_bf16 v[250:253], v[2:5], v[234:237], v[250:253]
	ds_read_b128 v[238:241], v156
	ds_read_b128 v[242:245], v155
	ds_read_b32 v217, v137 offset:640
	v_max_f32_e32 v9, 0, v206
	v_max_f32_e32 v200, 0, v207
	v_max_f32_e32 v201, 0, v208
	v_max_f32_e32 v216, 0, v209
	v_fmac_f32_e32 v86, v6, v9
	v_fmac_f32_e32 v85, v6, v200
	v_fmac_f32_e32 v88, v6, v201
	v_fmac_f32_e32 v87, v6, v216
	v_max_f32_e32 v9, 0, v210
	v_max_f32_e32 v200, 0, v211
	v_max_f32_e32 v201, 0, v212
	v_max_f32_e32 v216, 0, v213
	v_fmac_f32_e32 v90, v6, v9
	v_fmac_f32_e32 v89, v6, v200
	v_fmac_f32_e32 v92, v6, v201
	v_fmac_f32_e32 v91, v6, v216
	s_waitcnt lgkmcnt(1)
	v_mfma_f32_16x16x32_bf16 v[206:209], v[42:45], v[238:241], 0
	v_mfma_f32_16x16x32_bf16 v[210:213], v[50:53], v[238:241], 0
	v_mfma_f32_16x16x32_bf16 v[206:209], v[46:49], v[242:245], v[206:209]
	v_mfma_f32_16x16x32_bf16 v[210:213], v[2:5], v[242:245], v[210:213]
	ds_read_b128 v[230:233], v154
	ds_read_b128 v[234:237], v153
	ds_read_b32 v6, v137 offset:704
	v_max_f32_e32 v9, 0, v246
	v_max_f32_e32 v200, 0, v247
	v_max_f32_e32 v201, 0, v248
	v_max_f32_e32 v216, 0, v249
	v_fmac_f32_e32 v86, v7, v9
	v_fmac_f32_e32 v85, v7, v200
	v_fmac_f32_e32 v88, v7, v201
	v_fmac_f32_e32 v87, v7, v216
	v_max_f32_e32 v9, 0, v250
	v_max_f32_e32 v200, 0, v251
	v_max_f32_e32 v201, 0, v252
	v_max_f32_e32 v216, 0, v253
	v_fmac_f32_e32 v90, v7, v9
	v_fmac_f32_e32 v89, v7, v200
	v_fmac_f32_e32 v92, v7, v201
	v_fmac_f32_e32 v91, v7, v216
	s_waitcnt lgkmcnt(1)
	v_mfma_f32_16x16x32_bf16 v[246:249], v[42:45], v[230:233], 0
	v_mfma_f32_16x16x32_bf16 v[250:253], v[50:53], v[230:233], 0
	v_mfma_f32_16x16x32_bf16 v[246:249], v[46:49], v[234:237], v[246:249]
	v_mfma_f32_16x16x32_bf16 v[250:253], v[2:5], v[234:237], v[250:253]
	ds_read_b128 v[238:241], v152
	ds_read_b128 v[242:245], v151
	ds_read_b32 v7, v137 offset:768
	v_max_f32_e32 v9, 0, v206
	v_max_f32_e32 v200, 0, v207
	v_max_f32_e32 v201, 0, v208
	v_max_f32_e32 v216, 0, v209
	v_fmac_f32_e32 v86, v217, v9
	v_fmac_f32_e32 v85, v217, v200
	v_fmac_f32_e32 v88, v217, v201
	v_fmac_f32_e32 v87, v217, v216
	v_max_f32_e32 v9, 0, v210
	v_max_f32_e32 v200, 0, v211
	v_max_f32_e32 v201, 0, v212
	v_max_f32_e32 v216, 0, v213
	v_fmac_f32_e32 v90, v217, v9
	v_fmac_f32_e32 v89, v217, v200
	v_fmac_f32_e32 v92, v217, v201
	v_fmac_f32_e32 v91, v217, v216
	s_waitcnt lgkmcnt(1)
; #define LAS __attribute__((address_space(3)))
; __device__ __forceinline__ unsigned fkey(float f) { const unsigned u = __float_as_uint(f); return (u & 0x80000000u) ? ~u : (u | 0x80000000u); }
; #define SEL_HADD(idx_) __hip_atomic_fetch_add(&hist[(idx_)], 1u, __ATOMIC_RELAXED, __HIP_MEMORY_SCOPE_WORKGROUP)
; __device__ __forceinline__ void sel_unit(LAS char* lds, int b, int u, const bf16_t* QI, const bf16_t* KIDX, const float* WIDX, unsigned long long* MASK) {
;     ...
;     for (int j = 0; j < 8; ++j) {
;         if (j < nj) {
;             int t = wid + 8 * j; asm volatile("" : "+s"(t));
; #pragma unroll
;             for (int kh = 0; kh < 2; ++kh) {
;             bf16x8 kf[2][2];
; #pragma unroll
;             for (int kb = 0; kb < 2; ++kb)
; #pragma unroll
;                 for (int ks = 0; ks < 2; ++ks) kf[kb][ks] = *(const bf16x8*)(KIDX + (rowbase + 64 * t + 32 * kh + 16 * kb + q16) * 64 + 32 * ks + 8 * kg);
; #pragma unroll
;             for (int kb = 0; kb < 2; ++kb) {
;                 f32x4 s = (f32x4){0.f, 0.f, 0.f, 0.f};
; #pragma unroll
;                 for (int hh = 0; hh < 8; ++hh) {
;                     f32x4 a = (f32x4){0.f, 0.f, 0.f, 0.f};
; #pragma unroll
;                     for (int ks = 0; ks < 2; ++ks) {
;                         const bf16x8 qv = *(const LAS bf16x8*)(lds + L_QI + q16 * 1024 + (((hh * 8 + 4 * ks + kg) ^ q16) << 4));
;                         a = __builtin_amdgcn_mfma_f32_16x16x32_bf16(kf[kb][ks], qv, a, 0, 0, 0);
;                     }
;                     const float wh = wl[hh * 16];
; #pragma unroll
;                     for (int i = 0; i < 4; ++i) s[i] += wh * fmaxf(a[i], 0.f);
;                 }
;                 u32x4 kk; kk.x = fkey(s[0]); kk.y = fkey(s[1]); kk.z = fkey(s[2]); kk.w = fkey(s[3]);
;                 sc[j][2 * kh + kb] = kk;
; #pragma unroll
;                 for (int i = 0; i < 4; ++i) SEL_HADD((kk[i] >> 24) * 16 + q16);
;                 __builtin_amdgcn_sched_barrier(0);
	v_mfma_f32_16x16x32_bf16 v[206:209], v[42:45], v[238:241], 0
	v_mfma_f32_16x16x32_bf16 v[210:213], v[50:53], v[238:241], 0
	v_mfma_f32_16x16x32_bf16 v[206:209], v[46:49], v[242:245], v[206:209]
	v_mfma_f32_16x16x32_bf16 v[210:213], v[2:5], v[242:245], v[210:213]
	v_max_f32_e32 v9, 0, v246
	v_max_f32_e32 v200, 0, v247
	v_max_f32_e32 v201, 0, v248
	v_max_f32_e32 v216, 0, v249
	v_fmac_f32_e32 v86, v6, v9
	v_fmac_f32_e32 v85, v6, v200
	v_fmac_f32_e32 v88, v6, v201
	v_fmac_f32_e32 v87, v6, v216
	v_max_f32_e32 v9, 0, v250
	v_max_f32_e32 v200, 0, v251
	v_max_f32_e32 v201, 0, v252
	v_max_f32_e32 v216, 0, v253
	v_fmac_f32_e32 v90, v6, v9
	v_fmac_f32_e32 v89, v6, v200
	v_fmac_f32_e32 v92, v6, v201
	v_fmac_f32_e32 v91, v6, v216
	s_waitcnt lgkmcnt(0)
	v_max_f32_e32 v9, 0, v206
	v_max_f32_e32 v200, 0, v207
	v_max_f32_e32 v201, 0, v208
	v_max_f32_e32 v216, 0, v209
	v_fmac_f32_e32 v86, v7, v9
	v_fmac_f32_e32 v85, v7, v200
	v_fmac_f32_e32 v88, v7, v201
	v_fmac_f32_e32 v87, v7, v216
	v_max_f32_e32 v9, 0, v210
	v_max_f32_e32 v200, 0, v211
	v_max_f32_e32 v201, 0, v212
	v_max_f32_e32 v216, 0, v213
	v_fmac_f32_e32 v90, v7, v9
	v_fmac_f32_e32 v89, v7, v200
	v_fmac_f32_e32 v92, v7, v201
	v_fmac_f32_e32 v91, v7, v216
	v_ashrrev_i32_e32 v9, 31, v86
	v_bitop3_b32 v86, v9, v86, v8 bitop3:0x36
	v_ashrrev_i32_e32 v200, 31, v85
	v_bitop3_b32 v85, v200, v85, v8 bitop3:0x36
	v_ashrrev_i32_e32 v201, 31, v88
	v_bitop3_b32 v88, v201, v88, v8 bitop3:0x36
	v_ashrrev_i32_e32 v216, 31, v87
	v_bitop3_b32 v87, v216, v87, v8 bitop3:0x36
	v_ashrrev_i32_e32 v9, 31, v90
	v_bitop3_b32 v90, v9, v90, v8 bitop3:0x36
	v_ashrrev_i32_e32 v200, 31, v89
	v_bitop3_b32 v89, v200, v89, v8 bitop3:0x36
	v_ashrrev_i32_e32 v201, 31, v92
	v_bitop3_b32 v92, v201, v92, v8 bitop3:0x36
	v_ashrrev_i32_e32 v216, 31, v91
	v_bitop3_b32 v91, v216, v91, v8 bitop3:0x36
	v_lshrrev_b32_e32 v9, 24, v86
	v_lshl_add_u32 v9, v9, 6, v0
	ds_add_u32 v9, v205 offset:16384
	v_lshrrev_b32_e32 v200, 24, v85
	v_lshl_add_u32 v200, v200, 6, v0
	ds_add_u32 v200, v205 offset:16384
	v_lshrrev_b32_e32 v201, 24, v88
	v_lshl_add_u32 v201, v201, 6, v0
	ds_add_u32 v201, v205 offset:16384
	v_lshrrev_b32_e32 v216, 24, v87
	v_lshl_add_u32 v216, v216, 6, v0
	ds_add_u32 v216, v205 offset:16384
	v_lshrrev_b32_e32 v9, 24, v90
	v_lshl_add_u32 v9, v9, 6, v0
	ds_add_u32 v9, v205 offset:16384
	v_lshrrev_b32_e32 v200, 24, v89
	v_lshl_add_u32 v200, v200, 6, v0
	ds_add_u32 v200, v205 offset:16384
	v_lshrrev_b32_e32 v201, 24, v92
	v_lshl_add_u32 v201, v201, 6, v0
	ds_add_u32 v201, v205 offset:16384
	v_lshrrev_b32_e32 v216, 24, v91
	v_lshl_add_u32 v216, v216, 6, v0
	ds_add_u32 v216, v205 offset:16384
.LBB0_660:
	s_cmp_gt_i32 s4, 2
	s_cselect_b64 s[54:55], -1, 0
	s_cmp_lt_i32 s4, 3
	s_cbranch_scc1 .LBB0_662
	ds_read_b128 v[230:233], v182
	ds_read_b128 v[234:237], v183
	ds_read_b32 v6, v137 offset:320
	s_waitcnt vmcnt(0)
	v_add_co_u32_e32 v22, vcc, s96, v22
	s_nop 1
	v_addc_co_u32_e32 v23, vcc, 0, v23, vcc
	global_load_dwordx4 v[42:45], v[22:23], off
	global_load_dwordx4 v[46:49], v[22:23], off offset:64
	global_load_dwordx4 v[50:53], v[22:23], off offset:2048
	global_load_dwordx4 v[2:5], v[22:23], off offset:2112
	s_waitcnt lgkmcnt(1)
	v_mfma_f32_16x16x32_bf16 v[246:249], v[26:29], v[230:233], 0
	v_mfma_f32_16x16x32_bf16 v[250:253], v[34:37], v[230:233], 0
	v_mfma_f32_16x16x32_bf16 v[246:249], v[30:33], v[234:237], v[246:249]
	v_mfma_f32_16x16x32_bf16 v[250:253], v[38:41], v[234:237], v[250:253]
	ds_read_b128 v[238:241], v184
	ds_read_b128 v[242:245], v185
	ds_read_b32 v7, v137 offset:384
	s_waitcnt lgkmcnt(1)
	v_mfma_f32_16x16x32_bf16 v[206:209], v[26:29], v[238:241], 0
	v_mfma_f32_16x16x32_bf16 v[210:213], v[34:37], v[238:241], 0
	v_mfma_f32_16x16x32_bf16 v[206:209], v[30:33], v[242:245], v[206:209]
	v_mfma_f32_16x16x32_bf16 v[210:213], v[38:41], v[242:245], v[210:213]
	ds_read_b128 v[230:233], v179
	ds_read_b128 v[234:237], v180
	ds_read_b32 v217, v137 offset:448
	v_max_f32_e32 v9, 0, v246
	v_max_f32_e32 v200, 0, v247
	v_max_f32_e32 v201, 0, v248
	v_max_f32_e32 v216, 0, v249
	v_fma_f32 v94, v6, v9, 0
	v_fma_f32 v93, v6, v200, 0
	v_fma_f32 v96, v6, v201, 0
	v_fma_f32 v95, v6, v216, 0
	v_max_f32_e32 v9, 0, v250
	v_max_f32_e32 v200, 0, v251
	v_max_f32_e32 v201, 0, v252
	v_max_f32_e32 v216, 0, v253
	v_fma_f32 v98, v6, v9, 0
	v_fma_f32 v97, v6, v200, 0
	v_fma_f32 v100, v6, v201, 0
	v_fma_f32 v99, v6, v216, 0
	s_waitcnt lgkmcnt(1)
	v_mfma_f32_16x16x32_bf16 v[246:249], v[26:29], v[230:233], 0
	v_mfma_f32_16x16x32_bf16 v[250:253], v[34:37], v[230:233], 0
	v_mfma_f32_16x16x32_bf16 v[246:249], v[30:33], v[234:237], v[246:249]
	v_mfma_f32_16x16x32_bf16 v[250:253], v[38:41], v[234:237], v[250:253]
	ds_read_b128 v[238:241], v176
	ds_read_b128 v[242:245], v159
	ds_read_b32 v6, v137 offset:512
	v_max_f32_e32 v9, 0, v206
	v_max_f32_e32 v200, 0, v207
	v_max_f32_e32 v201, 0, v208
	v_max_f32_e32 v216, 0, v209
	v_fmac_f32_e32 v94, v7, v9
	v_fmac_f32_e32 v93, v7, v200
	v_fmac_f32_e32 v96, v7, v201
	v_fmac_f32_e32 v95, v7, v216
	v_max_f32_e32 v9, 0, v210
	v_max_f32_e32 v200, 0, v211
	v_max_f32_e32 v201, 0, v212
	v_max_f32_e32 v216, 0, v213
	v_fmac_f32_e32 v98, v7, v9
	v_fmac_f32_e32 v97, v7, v200
	v_fmac_f32_e32 v100, v7, v201
	v_fmac_f32_e32 v99, v7, v216
	s_waitcnt lgkmcnt(1)
; #define LAS __attribute__((address_space(3)))
; __device__ __forceinline__ unsigned fkey(float f) { const unsigned u = __float_as_uint(f); return (u & 0x80000000u) ? ~u : (u | 0x80000000u); }
; #define SEL_HADD(idx_) __hip_atomic_fetch_add(&hist[(idx_)], 1u, __ATOMIC_RELAXED, __HIP_MEMORY_SCOPE_WORKGROUP)
; __device__ __forceinline__ void sel_unit(LAS char* lds, int b, int u, const bf16_t* QI, const bf16_t* KIDX, const float* WIDX, unsigned long long* MASK) {
;     ...
;             for (int kb = 0; kb < 2; ++kb) {
;                 f32x4 s = (f32x4){0.f, 0.f, 0.f, 0.f};
; #pragma unroll
;                 for (int hh = 0; hh < 8; ++hh) {
;                     f32x4 a = (f32x4){0.f, 0.f, 0.f, 0.f};
; #pragma unroll
;                     for (int ks = 0; ks < 2; ++ks) {
;                         const bf16x8 qv = *(const LAS bf16x8*)(lds + L_QI + q16 * 1024 + (((hh * 8 + 4 * ks + kg) ^ q16) << 4));
;                         a = __builtin_amdgcn_mfma_f32_16x16x32_bf16(kf[kb][ks], qv, a, 0, 0, 0);
;                     }
;                     const float wh = wl[hh * 16];
; #pragma unroll
;                     for (int i = 0; i < 4; ++i) s[i] += wh * fmaxf(a[i], 0.f);
;                 }
;                 u32x4 kk; kk.x = fkey(s[0]); kk.y = fkey(s[1]); kk.z = fkey(s[2]); kk.w = fkey(s[3]);
;                 sc[j][2 * kh + kb] = kk;
; #pragma unroll
;                 for (int i = 0; i < 4; ++i) SEL_HADD((kk[i] >> 24) * 16 + q16);
;                 __builtin_amdgcn_sched_barrier(0);
	v_mfma_f32_16x16x32_bf16 v[206:209], v[26:29], v[238:241], 0
	v_mfma_f32_16x16x32_bf16 v[210:213], v[34:37], v[238:241], 0
	v_mfma_f32_16x16x32_bf16 v[206:209], v[30:33], v[242:245], v[206:209]
	v_mfma_f32_16x16x32_bf16 v[210:213], v[38:41], v[242:245], v[210:213]
	ds_read_b128 v[230:233], v158
	ds_read_b128 v[234:237], v157
	ds_read_b32 v7, v137 offset:576
	v_max_f32_e32 v9, 0, v246
	v_max_f32_e32 v200, 0, v247
	v_max_f32_e32 v201, 0, v248
	v_max_f32_e32 v216, 0, v249
	v_fmac_f32_e32 v94, v217, v9
	v_fmac_f32_e32 v93, v217, v200
	v_fmac_f32_e32 v96, v217, v201
	v_fmac_f32_e32 v95, v217, v216
	v_max_f32_e32 v9, 0, v250
	v_max_f32_e32 v200, 0, v251
	v_max_f32_e32 v201, 0, v252
	v_max_f32_e32 v216, 0, v253
	v_fmac_f32_e32 v98, v217, v9
	v_fmac_f32_e32 v97, v217, v200
	v_fmac_f32_e32 v100, v217, v201
	v_fmac_f32_e32 v99, v217, v216
	s_waitcnt lgkmcnt(1)
	v_mfma_f32_16x16x32_bf16 v[246:249], v[26:29], v[230:233], 0
	v_mfma_f32_16x16x32_bf16 v[250:253], v[34:37], v[230:233], 0
	v_mfma_f32_16x16x32_bf16 v[246:249], v[30:33], v[234:237], v[246:249]
	v_mfma_f32_16x16x32_bf16 v[250:253], v[38:41], v[234:237], v[250:253]
	ds_read_b128 v[238:241], v156
	ds_read_b128 v[242:245], v155
	ds_read_b32 v217, v137 offset:640
	v_max_f32_e32 v9, 0, v206
	v_max_f32_e32 v200, 0, v207
	v_max_f32_e32 v201, 0, v208
	v_max_f32_e32 v216, 0, v209
	v_fmac_f32_e32 v94, v6, v9
	v_fmac_f32_e32 v93, v6, v200
	v_fmac_f32_e32 v96, v6, v201
	v_fmac_f32_e32 v95, v6, v216
	v_max_f32_e32 v9, 0, v210
	v_max_f32_e32 v200, 0, v211
	v_max_f32_e32 v201, 0, v212
	v_max_f32_e32 v216, 0, v213
	v_fmac_f32_e32 v98, v6, v9
	v_fmac_f32_e32 v97, v6, v200
	v_fmac_f32_e32 v100, v6, v201
	v_fmac_f32_e32 v99, v6, v216
	s_waitcnt lgkmcnt(1)
	v_mfma_f32_16x16x32_bf16 v[206:209], v[26:29], v[238:241], 0
	v_mfma_f32_16x16x32_bf16 v[210:213], v[34:37], v[238:241], 0
	v_mfma_f32_16x16x32_bf16 v[206:209], v[30:33], v[242:245], v[206:209]
	v_mfma_f32_16x16x32_bf16 v[210:213], v[38:41], v[242:245], v[210:213]
	ds_read_b128 v[230:233], v154
	ds_read_b128 v[234:237], v153
	ds_read_b32 v6, v137 offset:704
	v_max_f32_e32 v9, 0, v246
	v_max_f32_e32 v200, 0, v247
	v_max_f32_e32 v201, 0, v248
	v_max_f32_e32 v216, 0, v249
	v_fmac_f32_e32 v94, v7, v9
	v_fmac_f32_e32 v93, v7, v200
	v_fmac_f32_e32 v96, v7, v201
	v_fmac_f32_e32 v95, v7, v216
	v_max_f32_e32 v9, 0, v250
	v_max_f32_e32 v200, 0, v251
	v_max_f32_e32 v201, 0, v252
	v_max_f32_e32 v216, 0, v253
	v_fmac_f32_e32 v98, v7, v9
	v_fmac_f32_e32 v97, v7, v200
	v_fmac_f32_e32 v100, v7, v201
	v_fmac_f32_e32 v99, v7, v216
	s_waitcnt lgkmcnt(1)
	v_mfma_f32_16x16x32_bf16 v[246:249], v[26:29], v[230:233], 0
	v_mfma_f32_16x16x32_bf16 v[250:253], v[34:37], v[230:233], 0
	v_mfma_f32_16x16x32_bf16 v[246:249], v[30:33], v[234:237], v[246:249]
	v_mfma_f32_16x16x32_bf16 v[250:253], v[38:41], v[234:237], v[250:253]
	ds_read_b128 v[238:241], v152
	ds_read_b128 v[242:245], v151
	ds_read_b32 v7, v137 offset:768
	v_max_f32_e32 v9, 0, v206
	v_max_f32_e32 v200, 0, v207
	v_max_f32_e32 v201, 0, v208
	v_max_f32_e32 v216, 0, v209
	v_fmac_f32_e32 v94, v217, v9
	v_fmac_f32_e32 v93, v217, v200
	v_fmac_f32_e32 v96, v217, v201
	v_fmac_f32_e32 v95, v217, v216
	v_max_f32_e32 v9, 0, v210
	v_max_f32_e32 v200, 0, v211
	v_max_f32_e32 v201, 0, v212
	v_max_f32_e32 v216, 0, v213
	v_fmac_f32_e32 v98, v217, v9
	v_fmac_f32_e32 v97, v217, v200
	v_fmac_f32_e32 v100, v217, v201
	v_fmac_f32_e32 v99, v217, v216
	s_waitcnt lgkmcnt(1)
	v_mfma_f32_16x16x32_bf16 v[206:209], v[26:29], v[238:241], 0
	v_mfma_f32_16x16x32_bf16 v[210:213], v[34:37], v[238:241], 0
	v_mfma_f32_16x16x32_bf16 v[206:209], v[30:33], v[242:245], v[206:209]
	v_mfma_f32_16x16x32_bf16 v[210:213], v[38:41], v[242:245], v[210:213]
	v_max_f32_e32 v9, 0, v246
	v_max_f32_e32 v200, 0, v247
	v_max_f32_e32 v201, 0, v248
	v_max_f32_e32 v216, 0, v249
	v_fmac_f32_e32 v94, v6, v9
	v_fmac_f32_e32 v93, v6, v200
	v_fmac_f32_e32 v96, v6, v201
	v_fmac_f32_e32 v95, v6, v216
	v_max_f32_e32 v9, 0, v250
	v_max_f32_e32 v200, 0, v251
	v_max_f32_e32 v201, 0, v252
	v_max_f32_e32 v216, 0, v253
	v_fmac_f32_e32 v98, v6, v9
	v_fmac_f32_e32 v97, v6, v200
	v_fmac_f32_e32 v100, v6, v201
	v_fmac_f32_e32 v99, v6, v216
	s_waitcnt lgkmcnt(0)
	v_max_f32_e32 v9, 0, v206
	v_max_f32_e32 v200, 0, v207
	v_max_f32_e32 v201, 0, v208
	v_max_f32_e32 v216, 0, v209
	v_fmac_f32_e32 v94, v7, v9
	v_fmac_f32_e32 v93, v7, v200
	v_fmac_f32_e32 v96, v7, v201
	v_fmac_f32_e32 v95, v7, v216
	v_max_f32_e32 v9, 0, v210
	v_max_f32_e32 v200, 0, v211
	v_max_f32_e32 v201, 0, v212
	v_max_f32_e32 v216, 0, v213
	v_fmac_f32_e32 v98, v7, v9
	v_fmac_f32_e32 v97, v7, v200
	v_fmac_f32_e32 v100, v7, v201
	v_fmac_f32_e32 v99, v7, v216
	v_ashrrev_i32_e32 v9, 31, v94
	v_bitop3_b32 v94, v9, v94, v8 bitop3:0x36
	v_ashrrev_i32_e32 v200, 31, v93
	v_bitop3_b32 v93, v200, v93, v8 bitop3:0x36
	v_ashrrev_i32_e32 v201, 31, v96
	v_bitop3_b32 v96, v201, v96, v8 bitop3:0x36
	v_ashrrev_i32_e32 v216, 31, v95
	v_bitop3_b32 v95, v216, v95, v8 bitop3:0x36
	v_ashrrev_i32_e32 v9, 31, v98
	v_bitop3_b32 v98, v9, v98, v8 bitop3:0x36
	v_ashrrev_i32_e32 v200, 31, v97
	v_bitop3_b32 v97, v200, v97, v8 bitop3:0x36
	v_ashrrev_i32_e32 v201, 31, v100
	v_bitop3_b32 v100, v201, v100, v8 bitop3:0x36
	v_ashrrev_i32_e32 v216, 31, v99
	v_bitop3_b32 v99, v216, v99, v8 bitop3:0x36
	v_lshrrev_b32_e32 v9, 24, v94
	v_lshl_add_u32 v9, v9, 6, v0
	ds_add_u32 v9, v205 offset:16384
	v_lshrrev_b32_e32 v200, 24, v93
	v_lshl_add_u32 v200, v200, 6, v0
	ds_add_u32 v200, v205 offset:16384
	v_lshrrev_b32_e32 v201, 24, v96
	v_lshl_add_u32 v201, v201, 6, v0
	ds_add_u32 v201, v205 offset:16384
	v_lshrrev_b32_e32 v216, 24, v95
	v_lshl_add_u32 v216, v216, 6, v0
	ds_add_u32 v216, v205 offset:16384
	v_lshrrev_b32_e32 v9, 24, v98
	v_lshl_add_u32 v9, v9, 6, v0
	ds_add_u32 v9, v205 offset:16384
	v_lshrrev_b32_e32 v200, 24, v97
	v_lshl_add_u32 v200, v200, 6, v0
	ds_add_u32 v200, v205 offset:16384
	v_lshrrev_b32_e32 v201, 24, v100
	v_lshl_add_u32 v201, v201, 6, v0
	ds_add_u32 v201, v205 offset:16384
	v_lshrrev_b32_e32 v216, 24, v99
	v_lshl_add_u32 v216, v216, 6, v0
	ds_add_u32 v216, v205 offset:16384
	ds_read_b128 v[230:233], v182
	ds_read_b128 v[234:237], v183
	ds_read_b32 v6, v137 offset:320
	s_waitcnt vmcnt(0)
	s_cmp_lt_i32 s4, 4
	s_cbranch_scc1 .Lp0_nopf_2
	v_add_co_u32_e32 v22, vcc, 0xf000, v22
	s_nop 1
	v_addc_co_u32_e32 v23, vcc, 0, v23, vcc
	global_load_dwordx4 v[26:29], v[22:23], off
	global_load_dwordx4 v[30:33], v[22:23], off offset:64
	global_load_dwordx4 v[34:37], v[22:23], off offset:2048
	global_load_dwordx4 v[38:41], v[22:23], off offset:2112
; #define LAS __attribute__((address_space(3)))
; __device__ __forceinline__ unsigned fkey(float f) { const unsigned u = __float_as_uint(f); return (u & 0x80000000u) ? ~u : (u | 0x80000000u); }
; #define SEL_HADD(idx_) __hip_atomic_fetch_add(&hist[(idx_)], 1u, __ATOMIC_RELAXED, __HIP_MEMORY_SCOPE_WORKGROUP)
; __device__ __forceinline__ void sel_unit(LAS char* lds, int b, int u, const bf16_t* QI, const bf16_t* KIDX, const float* WIDX, unsigned long long* MASK) {
;     ...
;     for (int j = 0; j < 8; ++j) {
;         if (j < nj) {
;             int t = wid + 8 * j; asm volatile("" : "+s"(t));
; #pragma unroll
;             for (int kh = 0; kh < 2; ++kh) {
;             bf16x8 kf[2][2];
; #pragma unroll
;             for (int kb = 0; kb < 2; ++kb)
; #pragma unroll
;                 for (int ks = 0; ks < 2; ++ks) kf[kb][ks] = *(const bf16x8*)(KIDX + (rowbase + 64 * t + 32 * kh + 16 * kb + q16) * 64 + 32 * ks + 8 * kg);
; #pragma unroll
;             for (int kb = 0; kb < 2; ++kb) {
;                 f32x4 s = (f32x4){0.f, 0.f, 0.f, 0.f};
; #pragma unroll
;                 for (int hh = 0; hh < 8; ++hh) {
;                     f32x4 a = (f32x4){0.f, 0.f, 0.f, 0.f};
; #pragma unroll
;                     for (int ks = 0; ks < 2; ++ks) {
;                         const bf16x8 qv = *(const LAS bf16x8*)(lds + L_QI + q16 * 1024 + (((hh * 8 + 4 * ks + kg) ^ q16) << 4));
;                         a = __builtin_amdgcn_mfma_f32_16x16x32_bf16(kf[kb][ks], qv, a, 0, 0, 0);
;                     }
;                     const float wh = wl[hh * 16];
; #pragma unroll
;                     for (int i = 0; i < 4; ++i) s[i] += wh * fmaxf(a[i], 0.f);
;                 }
;                 u32x4 kk; kk.x = fkey(s[0]); kk.y = fkey(s[1]); kk.z = fkey(s[2]); kk.w = fkey(s[3]);
;                 sc[j][2 * kh + kb] = kk;
; #pragma unroll
;                 for (int i = 0; i < 4; ++i) SEL_HADD((kk[i] >> 24) * 16 + q16);
;                 __builtin_amdgcn_sched_barrier(0);
.Lp0_nopf_2:
	s_waitcnt lgkmcnt(1)
	v_mfma_f32_16x16x32_bf16 v[246:249], v[42:45], v[230:233], 0
	v_mfma_f32_16x16x32_bf16 v[250:253], v[50:53], v[230:233], 0
	v_mfma_f32_16x16x32_bf16 v[246:249], v[46:49], v[234:237], v[246:249]
	v_mfma_f32_16x16x32_bf16 v[250:253], v[2:5], v[234:237], v[250:253]
	ds_read_b128 v[238:241], v184
	ds_read_b128 v[242:245], v185
	ds_read_b32 v7, v137 offset:384
	s_waitcnt lgkmcnt(1)
	v_mfma_f32_16x16x32_bf16 v[206:209], v[42:45], v[238:241], 0
	v_mfma_f32_16x16x32_bf16 v[210:213], v[50:53], v[238:241], 0
	v_mfma_f32_16x16x32_bf16 v[206:209], v[46:49], v[242:245], v[206:209]
	v_mfma_f32_16x16x32_bf16 v[210:213], v[2:5], v[242:245], v[210:213]
	ds_read_b128 v[230:233], v179
	ds_read_b128 v[234:237], v180
	ds_read_b32 v217, v137 offset:448
	v_max_f32_e32 v9, 0, v246
	v_max_f32_e32 v200, 0, v247
	v_max_f32_e32 v201, 0, v248
	v_max_f32_e32 v216, 0, v249
	v_fma_f32 v102, v6, v9, 0
	v_fma_f32 v101, v6, v200, 0
	v_fma_f32 v104, v6, v201, 0
	v_fma_f32 v103, v6, v216, 0
	v_max_f32_e32 v9, 0, v250
	v_max_f32_e32 v200, 0, v251
	v_max_f32_e32 v201, 0, v252
	v_max_f32_e32 v216, 0, v253
	v_fma_f32 v106, v6, v9, 0
	v_fma_f32 v105, v6, v200, 0
	v_fma_f32 v108, v6, v201, 0
	v_fma_f32 v107, v6, v216, 0
	s_waitcnt lgkmcnt(1)
	v_mfma_f32_16x16x32_bf16 v[246:249], v[42:45], v[230:233], 0
	v_mfma_f32_16x16x32_bf16 v[250:253], v[50:53], v[230:233], 0
	v_mfma_f32_16x16x32_bf16 v[246:249], v[46:49], v[234:237], v[246:249]
	v_mfma_f32_16x16x32_bf16 v[250:253], v[2:5], v[234:237], v[250:253]
	ds_read_b128 v[238:241], v176
	ds_read_b128 v[242:245], v159
	ds_read_b32 v6, v137 offset:512
	v_max_f32_e32 v9, 0, v206
	v_max_f32_e32 v200, 0, v207
	v_max_f32_e32 v201, 0, v208
	v_max_f32_e32 v216, 0, v209
	v_fmac_f32_e32 v102, v7, v9
	v_fmac_f32_e32 v101, v7, v200
	v_fmac_f32_e32 v104, v7, v201
	v_fmac_f32_e32 v103, v7, v216
	v_max_f32_e32 v9, 0, v210
	v_max_f32_e32 v200, 0, v211
	v_max_f32_e32 v201, 0, v212
	v_max_f32_e32 v216, 0, v213
	v_fmac_f32_e32 v106, v7, v9
	v_fmac_f32_e32 v105, v7, v200
	v_fmac_f32_e32 v108, v7, v201
	v_fmac_f32_e32 v107, v7, v216
	s_waitcnt lgkmcnt(1)
	v_mfma_f32_16x16x32_bf16 v[206:209], v[42:45], v[238:241], 0
	v_mfma_f32_16x16x32_bf16 v[210:213], v[50:53], v[238:241], 0
	v_mfma_f32_16x16x32_bf16 v[206:209], v[46:49], v[242:245], v[206:209]
	v_mfma_f32_16x16x32_bf16 v[210:213], v[2:5], v[242:245], v[210:213]
	ds_read_b128 v[230:233], v158
	ds_read_b128 v[234:237], v157
	ds_read_b32 v7, v137 offset:576
	v_max_f32_e32 v9, 0, v246
	v_max_f32_e32 v200, 0, v247
	v_max_f32_e32 v201, 0, v248
	v_max_f32_e32 v216, 0, v249
	v_fmac_f32_e32 v102, v217, v9
	v_fmac_f32_e32 v101, v217, v200
	v_fmac_f32_e32 v104, v217, v201
	v_fmac_f32_e32 v103, v217, v216
	v_max_f32_e32 v9, 0, v250
	v_max_f32_e32 v200, 0, v251
	v_max_f32_e32 v201, 0, v252
	v_max_f32_e32 v216, 0, v253
	v_fmac_f32_e32 v106, v217, v9
	v_fmac_f32_e32 v105, v217, v200
	v_fmac_f32_e32 v108, v217, v201
	v_fmac_f32_e32 v107, v217, v216
	s_waitcnt lgkmcnt(1)
	v_mfma_f32_16x16x32_bf16 v[246:249], v[42:45], v[230:233], 0
	v_mfma_f32_16x16x32_bf16 v[250:253], v[50:53], v[230:233], 0
	v_mfma_f32_16x16x32_bf16 v[246:249], v[46:49], v[234:237], v[246:249]
	v_mfma_f32_16x16x32_bf16 v[250:253], v[2:5], v[234:237], v[250:253]
	ds_read_b128 v[238:241], v156
	ds_read_b128 v[242:245], v155
	ds_read_b32 v217, v137 offset:640
	v_max_f32_e32 v9, 0, v206
	v_max_f32_e32 v200, 0, v207
	v_max_f32_e32 v201, 0, v208
	v_max_f32_e32 v216, 0, v209
	v_fmac_f32_e32 v102, v6, v9
	v_fmac_f32_e32 v101, v6, v200
	v_fmac_f32_e32 v104, v6, v201
	v_fmac_f32_e32 v103, v6, v216
	v_max_f32_e32 v9, 0, v210
	v_max_f32_e32 v200, 0, v211
	v_max_f32_e32 v201, 0, v212
	v_max_f32_e32 v216, 0, v213
	v_fmac_f32_e32 v106, v6, v9
	v_fmac_f32_e32 v105, v6, v200
	v_fmac_f32_e32 v108, v6, v201
	v_fmac_f32_e32 v107, v6, v216
	s_waitcnt lgkmcnt(1)
	v_mfma_f32_16x16x32_bf16 v[206:209], v[42:45], v[238:241], 0
	v_mfma_f32_16x16x32_bf16 v[210:213], v[50:53], v[238:241], 0
	v_mfma_f32_16x16x32_bf16 v[206:209], v[46:49], v[242:245], v[206:209]
	v_mfma_f32_16x16x32_bf16 v[210:213], v[2:5], v[242:245], v[210:213]
	ds_read_b128 v[230:233], v154
	ds_read_b128 v[234:237], v153
	ds_read_b32 v6, v137 offset:704
	v_max_f32_e32 v9, 0, v246
	v_max_f32_e32 v200, 0, v247
	v_max_f32_e32 v201, 0, v248
	v_max_f32_e32 v216, 0, v249
	v_fmac_f32_e32 v102, v7, v9
	v_fmac_f32_e32 v101, v7, v200
	v_fmac_f32_e32 v104, v7, v201
	v_fmac_f32_e32 v103, v7, v216
	v_max_f32_e32 v9, 0, v250
	v_max_f32_e32 v200, 0, v251
	v_max_f32_e32 v201, 0, v252
	v_max_f32_e32 v216, 0, v253
	v_fmac_f32_e32 v106, v7, v9
	v_fmac_f32_e32 v105, v7, v200
	v_fmac_f32_e32 v108, v7, v201
	v_fmac_f32_e32 v107, v7, v216
	s_waitcnt lgkmcnt(1)
	v_mfma_f32_16x16x32_bf16 v[246:249], v[42:45], v[230:233], 0
	v_mfma_f32_16x16x32_bf16 v[250:253], v[50:53], v[230:233], 0
	v_mfma_f32_16x16x32_bf16 v[246:249], v[46:49], v[234:237], v[246:249]
	v_mfma_f32_16x16x32_bf16 v[250:253], v[2:5], v[234:237], v[250:253]
	ds_read_b128 v[238:241], v152
	ds_read_b128 v[242:245], v151
	ds_read_b32 v7, v137 offset:768
	v_max_f32_e32 v9, 0, v206
	v_max_f32_e32 v200, 0, v207
	v_max_f32_e32 v201, 0, v208
	v_max_f32_e32 v216, 0, v209
	v_fmac_f32_e32 v102, v217, v9
	v_fmac_f32_e32 v101, v217, v200
	v_fmac_f32_e32 v104, v217, v201
	v_fmac_f32_e32 v103, v217, v216
	v_max_f32_e32 v9, 0, v210
	v_max_f32_e32 v200, 0, v211
	v_max_f32_e32 v201, 0, v212
	v_max_f32_e32 v216, 0, v213
	v_fmac_f32_e32 v106, v217, v9
	v_fmac_f32_e32 v105, v217, v200
	v_fmac_f32_e32 v108, v217, v201
	v_fmac_f32_e32 v107, v217, v216
	s_waitcnt lgkmcnt(1)
; #define LAS __attribute__((address_space(3)))
; __device__ __forceinline__ unsigned fkey(float f) { const unsigned u = __float_as_uint(f); return (u & 0x80000000u) ? ~u : (u | 0x80000000u); }
; #define SEL_HADD(idx_) __hip_atomic_fetch_add(&hist[(idx_)], 1u, __ATOMIC_RELAXED, __HIP_MEMORY_SCOPE_WORKGROUP)
; __device__ __forceinline__ void sel_unit(LAS char* lds, int b, int u, const bf16_t* QI, const bf16_t* KIDX, const float* WIDX, unsigned long long* MASK) {
;     ...
;     for (int j = 0; j < 8; ++j) {
;         if (j < nj) {
;             int t = wid + 8 * j; asm volatile("" : "+s"(t));
; #pragma unroll
;             for (int kh = 0; kh < 2; ++kh) {
;             bf16x8 kf[2][2];
; #pragma unroll
;             for (int kb = 0; kb < 2; ++kb)
; #pragma unroll
;                 for (int ks = 0; ks < 2; ++ks) kf[kb][ks] = *(const bf16x8*)(KIDX + (rowbase + 64 * t + 32 * kh + 16 * kb + q16) * 64 + 32 * ks + 8 * kg);
; #pragma unroll
;             for (int kb = 0; kb < 2; ++kb) {
;                 f32x4 s = (f32x4){0.f, 0.f, 0.f, 0.f};
; #pragma unroll
;                 for (int hh = 0; hh < 8; ++hh) {
;                     f32x4 a = (f32x4){0.f, 0.f, 0.f, 0.f};
; #pragma unroll
;                     for (int ks = 0; ks < 2; ++ks) {
;                         const bf16x8 qv = *(const LAS bf16x8*)(lds + L_QI + q16 * 1024 + (((hh * 8 + 4 * ks + kg) ^ q16) << 4));
;                         a = __builtin_amdgcn_mfma_f32_16x16x32_bf16(kf[kb][ks], qv, a, 0, 0, 0);
;                     }
;                     const float wh = wl[hh * 16];
; #pragma unroll
;                     for (int i = 0; i < 4; ++i) s[i] += wh * fmaxf(a[i], 0.f);
;                 }
;                 u32x4 kk; kk.x = fkey(s[0]); kk.y = fkey(s[1]); kk.z = fkey(s[2]); kk.w = fkey(s[3]);
;                 sc[j][2 * kh + kb] = kk;
; #pragma unroll
;                 for (int i = 0; i < 4; ++i) SEL_HADD((kk[i] >> 24) * 16 + q16);
;                 __builtin_amdgcn_sched_barrier(0);
	v_mfma_f32_16x16x32_bf16 v[206:209], v[42:45], v[238:241], 0
	v_mfma_f32_16x16x32_bf16 v[210:213], v[50:53], v[238:241], 0
	v_mfma_f32_16x16x32_bf16 v[206:209], v[46:49], v[242:245], v[206:209]
	v_mfma_f32_16x16x32_bf16 v[210:213], v[2:5], v[242:245], v[210:213]
	v_max_f32_e32 v9, 0, v246
	v_max_f32_e32 v200, 0, v247
	v_max_f32_e32 v201, 0, v248
	v_max_f32_e32 v216, 0, v249
	v_fmac_f32_e32 v102, v6, v9
	v_fmac_f32_e32 v101, v6, v200
	v_fmac_f32_e32 v104, v6, v201
	v_fmac_f32_e32 v103, v6, v216
	v_max_f32_e32 v9, 0, v250
	v_max_f32_e32 v200, 0, v251
	v_max_f32_e32 v201, 0, v252
	v_max_f32_e32 v216, 0, v253
	v_fmac_f32_e32 v106, v6, v9
	v_fmac_f32_e32 v105, v6, v200
	v_fmac_f32_e32 v108, v6, v201
	v_fmac_f32_e32 v107, v6, v216
	s_waitcnt lgkmcnt(0)
	v_max_f32_e32 v9, 0, v206
	v_max_f32_e32 v200, 0, v207
	v_max_f32_e32 v201, 0, v208
	v_max_f32_e32 v216, 0, v209
	v_fmac_f32_e32 v102, v7, v9
	v_fmac_f32_e32 v101, v7, v200
	v_fmac_f32_e32 v104, v7, v201
	v_fmac_f32_e32 v103, v7, v216
	v_max_f32_e32 v9, 0, v210
	v_max_f32_e32 v200, 0, v211
	v_max_f32_e32 v201, 0, v212
	v_max_f32_e32 v216, 0, v213
	v_fmac_f32_e32 v106, v7, v9
	v_fmac_f32_e32 v105, v7, v200
	v_fmac_f32_e32 v108, v7, v201
	v_fmac_f32_e32 v107, v7, v216
	v_ashrrev_i32_e32 v9, 31, v102
	v_bitop3_b32 v102, v9, v102, v8 bitop3:0x36
	v_ashrrev_i32_e32 v200, 31, v101
	v_bitop3_b32 v101, v200, v101, v8 bitop3:0x36
	v_ashrrev_i32_e32 v201, 31, v104
	v_bitop3_b32 v104, v201, v104, v8 bitop3:0x36
	v_ashrrev_i32_e32 v216, 31, v103
	v_bitop3_b32 v103, v216, v103, v8 bitop3:0x36
	v_ashrrev_i32_e32 v9, 31, v106
	v_bitop3_b32 v106, v9, v106, v8 bitop3:0x36
	v_ashrrev_i32_e32 v200, 31, v105
	v_bitop3_b32 v105, v200, v105, v8 bitop3:0x36
	v_ashrrev_i32_e32 v201, 31, v108
	v_bitop3_b32 v108, v201, v108, v8 bitop3:0x36
	v_ashrrev_i32_e32 v216, 31, v107
	v_bitop3_b32 v107, v216, v107, v8 bitop3:0x36
	v_lshrrev_b32_e32 v9, 24, v102
	v_lshl_add_u32 v9, v9, 6, v0
	ds_add_u32 v9, v205 offset:16384
	v_lshrrev_b32_e32 v200, 24, v101
	v_lshl_add_u32 v200, v200, 6, v0
	ds_add_u32 v200, v205 offset:16384
	v_lshrrev_b32_e32 v201, 24, v104
	v_lshl_add_u32 v201, v201, 6, v0
	ds_add_u32 v201, v205 offset:16384
	v_lshrrev_b32_e32 v216, 24, v103
	v_lshl_add_u32 v216, v216, 6, v0
	ds_add_u32 v216, v205 offset:16384
	v_lshrrev_b32_e32 v9, 24, v106
	v_lshl_add_u32 v9, v9, 6, v0
	ds_add_u32 v9, v205 offset:16384
	v_lshrrev_b32_e32 v200, 24, v105
	v_lshl_add_u32 v200, v200, 6, v0
	ds_add_u32 v200, v205 offset:16384
	v_lshrrev_b32_e32 v201, 24, v108
	v_lshl_add_u32 v201, v201, 6, v0
	ds_add_u32 v201, v205 offset:16384
	v_lshrrev_b32_e32 v216, 24, v107
	v_lshl_add_u32 v216, v216, 6, v0
	ds_add_u32 v216, v205 offset:16384
.LBB0_662:
	s_cmp_gt_i32 s4, 3
	s_cselect_b64 s[56:57], -1, 0
	s_cmp_lt_i32 s4, 4
	s_cbranch_scc1 .LBB0_664
	ds_read_b128 v[230:233], v182
	ds_read_b128 v[234:237], v183
	ds_read_b32 v6, v137 offset:320
	s_waitcnt vmcnt(0)
	v_add_co_u32_e32 v22, vcc, s96, v22
	s_nop 1
	v_addc_co_u32_e32 v23, vcc, 0, v23, vcc
	global_load_dwordx4 v[42:45], v[22:23], off
	global_load_dwordx4 v[46:49], v[22:23], off offset:64
	global_load_dwordx4 v[50:53], v[22:23], off offset:2048
	global_load_dwordx4 v[2:5], v[22:23], off offset:2112
	s_waitcnt lgkmcnt(1)
	v_mfma_f32_16x16x32_bf16 v[246:249], v[26:29], v[230:233], 0
	v_mfma_f32_16x16x32_bf16 v[250:253], v[34:37], v[230:233], 0
	v_mfma_f32_16x16x32_bf16 v[246:249], v[30:33], v[234:237], v[246:249]
	v_mfma_f32_16x16x32_bf16 v[250:253], v[38:41], v[234:237], v[250:253]
	ds_read_b128 v[238:241], v184
	ds_read_b128 v[242:245], v185
	ds_read_b32 v7, v137 offset:384
	s_waitcnt lgkmcnt(1)
	v_mfma_f32_16x16x32_bf16 v[206:209], v[26:29], v[238:241], 0
	v_mfma_f32_16x16x32_bf16 v[210:213], v[34:37], v[238:241], 0
	v_mfma_f32_16x16x32_bf16 v[206:209], v[30:33], v[242:245], v[206:209]
	v_mfma_f32_16x16x32_bf16 v[210:213], v[38:41], v[242:245], v[210:213]
	ds_read_b128 v[230:233], v179
	ds_read_b128 v[234:237], v180
	ds_read_b32 v217, v137 offset:448
	v_max_f32_e32 v9, 0, v246
	v_max_f32_e32 v200, 0, v247
	v_max_f32_e32 v201, 0, v248
	v_max_f32_e32 v216, 0, v249
	v_fma_f32 v110, v6, v9, 0
	v_fma_f32 v109, v6, v200, 0
	v_fma_f32 v112, v6, v201, 0
	v_fma_f32 v111, v6, v216, 0
	v_max_f32_e32 v9, 0, v250
	v_max_f32_e32 v200, 0, v251
	v_max_f32_e32 v201, 0, v252
	v_max_f32_e32 v216, 0, v253
	v_fma_f32 v114, v6, v9, 0
	v_fma_f32 v113, v6, v200, 0
	v_fma_f32 v116, v6, v201, 0
	v_fma_f32 v115, v6, v216, 0
	s_waitcnt lgkmcnt(1)
	v_mfma_f32_16x16x32_bf16 v[246:249], v[26:29], v[230:233], 0
	v_mfma_f32_16x16x32_bf16 v[250:253], v[34:37], v[230:233], 0
	v_mfma_f32_16x16x32_bf16 v[246:249], v[30:33], v[234:237], v[246:249]
	v_mfma_f32_16x16x32_bf16 v[250:253], v[38:41], v[234:237], v[250:253]
	ds_read_b128 v[238:241], v176
	ds_read_b128 v[242:245], v159
	ds_read_b32 v6, v137 offset:512
	v_max_f32_e32 v9, 0, v206
	v_max_f32_e32 v200, 0, v207
	v_max_f32_e32 v201, 0, v208
	v_max_f32_e32 v216, 0, v209
	v_fmac_f32_e32 v110, v7, v9
	v_fmac_f32_e32 v109, v7, v200
	v_fmac_f32_e32 v112, v7, v201
	v_fmac_f32_e32 v111, v7, v216
	v_max_f32_e32 v9, 0, v210
	v_max_f32_e32 v200, 0, v211
	v_max_f32_e32 v201, 0, v212
	v_max_f32_e32 v216, 0, v213
	v_fmac_f32_e32 v114, v7, v9
	v_fmac_f32_e32 v113, v7, v200
	v_fmac_f32_e32 v116, v7, v201
	v_fmac_f32_e32 v115, v7, v216
	s_waitcnt lgkmcnt(1)
; #define LAS __attribute__((address_space(3)))
; __device__ __forceinline__ unsigned fkey(float f) { const unsigned u = __float_as_uint(f); return (u & 0x80000000u) ? ~u : (u | 0x80000000u); }
; #define SEL_HADD(idx_) __hip_atomic_fetch_add(&hist[(idx_)], 1u, __ATOMIC_RELAXED, __HIP_MEMORY_SCOPE_WORKGROUP)
; __device__ __forceinline__ void sel_unit(LAS char* lds, int b, int u, const bf16_t* QI, const bf16_t* KIDX, const float* WIDX, unsigned long long* MASK) {
;     ...
;     for (int j = 0; j < 8; ++j) {
;         if (j < nj) {
;             int t = wid + 8 * j; asm volatile("" : "+s"(t));
; #pragma unroll
;             for (int kh = 0; kh < 2; ++kh) {
;             bf16x8 kf[2][2];
; #pragma unroll
;             for (int kb = 0; kb < 2; ++kb)
; #pragma unroll
;                 for (int ks = 0; ks < 2; ++ks) kf[kb][ks] = *(const bf16x8*)(KIDX + (rowbase + 64 * t + 32 * kh + 16 * kb + q16) * 64 + 32 * ks + 8 * kg);
; #pragma unroll
;             for (int kb = 0; kb < 2; ++kb) {
;                 f32x4 s = (f32x4){0.f, 0.f, 0.f, 0.f};
; #pragma unroll
;                 for (int hh = 0; hh < 8; ++hh) {
;                     f32x4 a = (f32x4){0.f, 0.f, 0.f, 0.f};
; #pragma unroll
;                     for (int ks = 0; ks < 2; ++ks) {
;                         const bf16x8 qv = *(const LAS bf16x8*)(lds + L_QI + q16 * 1024 + (((hh * 8 + 4 * ks + kg) ^ q16) << 4));
;                         a = __builtin_amdgcn_mfma_f32_16x16x32_bf16(kf[kb][ks], qv, a, 0, 0, 0);
;                     }
;                     const float wh = wl[hh * 16];
; #pragma unroll
;                     for (int i = 0; i < 4; ++i) s[i] += wh * fmaxf(a[i], 0.f);
;                 }
;                 u32x4 kk; kk.x = fkey(s[0]); kk.y = fkey(s[1]); kk.z = fkey(s[2]); kk.w = fkey(s[3]);
;                 sc[j][2 * kh + kb] = kk;
; #pragma unroll
;                 for (int i = 0; i < 4; ++i) SEL_HADD((kk[i] >> 24) * 16 + q16);
;                 __builtin_amdgcn_sched_barrier(0);
	v_mfma_f32_16x16x32_bf16 v[206:209], v[26:29], v[238:241], 0
	v_mfma_f32_16x16x32_bf16 v[210:213], v[34:37], v[238:241], 0
	v_mfma_f32_16x16x32_bf16 v[206:209], v[30:33], v[242:245], v[206:209]
	v_mfma_f32_16x16x32_bf16 v[210:213], v[38:41], v[242:245], v[210:213]
	ds_read_b128 v[230:233], v158
	ds_read_b128 v[234:237], v157
	ds_read_b32 v7, v137 offset:576
	v_max_f32_e32 v9, 0, v246
	v_max_f32_e32 v200, 0, v247
	v_max_f32_e32 v201, 0, v248
	v_max_f32_e32 v216, 0, v249
	v_fmac_f32_e32 v110, v217, v9
	v_fmac_f32_e32 v109, v217, v200
	v_fmac_f32_e32 v112, v217, v201
	v_fmac_f32_e32 v111, v217, v216
	v_max_f32_e32 v9, 0, v250
	v_max_f32_e32 v200, 0, v251
	v_max_f32_e32 v201, 0, v252
	v_max_f32_e32 v216, 0, v253
	v_fmac_f32_e32 v114, v217, v9
	v_fmac_f32_e32 v113, v217, v200
	v_fmac_f32_e32 v116, v217, v201
	v_fmac_f32_e32 v115, v217, v216
	s_waitcnt lgkmcnt(1)
	v_mfma_f32_16x16x32_bf16 v[246:249], v[26:29], v[230:233], 0
	v_mfma_f32_16x16x32_bf16 v[250:253], v[34:37], v[230:233], 0
	v_mfma_f32_16x16x32_bf16 v[246:249], v[30:33], v[234:237], v[246:249]
	v_mfma_f32_16x16x32_bf16 v[250:253], v[38:41], v[234:237], v[250:253]
	ds_read_b128 v[238:241], v156
	ds_read_b128 v[242:245], v155
	ds_read_b32 v217, v137 offset:640
	v_max_f32_e32 v9, 0, v206
	v_max_f32_e32 v200, 0, v207
	v_max_f32_e32 v201, 0, v208
	v_max_f32_e32 v216, 0, v209
	v_fmac_f32_e32 v110, v6, v9
	v_fmac_f32_e32 v109, v6, v200
	v_fmac_f32_e32 v112, v6, v201
	v_fmac_f32_e32 v111, v6, v216
	v_max_f32_e32 v9, 0, v210
	v_max_f32_e32 v200, 0, v211
	v_max_f32_e32 v201, 0, v212
	v_max_f32_e32 v216, 0, v213
	v_fmac_f32_e32 v114, v6, v9
	v_fmac_f32_e32 v113, v6, v200
	v_fmac_f32_e32 v116, v6, v201
	v_fmac_f32_e32 v115, v6, v216
	s_waitcnt lgkmcnt(1)
	v_mfma_f32_16x16x32_bf16 v[206:209], v[26:29], v[238:241], 0
	v_mfma_f32_16x16x32_bf16 v[210:213], v[34:37], v[238:241], 0
	v_mfma_f32_16x16x32_bf16 v[206:209], v[30:33], v[242:245], v[206:209]
	v_mfma_f32_16x16x32_bf16 v[210:213], v[38:41], v[242:245], v[210:213]
	ds_read_b128 v[230:233], v154
	ds_read_b128 v[234:237], v153
	ds_read_b32 v6, v137 offset:704
	v_max_f32_e32 v9, 0, v246
	v_max_f32_e32 v200, 0, v247
	v_max_f32_e32 v201, 0, v248
	v_max_f32_e32 v216, 0, v249
	v_fmac_f32_e32 v110, v7, v9
	v_fmac_f32_e32 v109, v7, v200
	v_fmac_f32_e32 v112, v7, v201
	v_fmac_f32_e32 v111, v7, v216
	v_max_f32_e32 v9, 0, v250
	v_max_f32_e32 v200, 0, v251
	v_max_f32_e32 v201, 0, v252
	v_max_f32_e32 v216, 0, v253
	v_fmac_f32_e32 v114, v7, v9
	v_fmac_f32_e32 v113, v7, v200
	v_fmac_f32_e32 v116, v7, v201
	v_fmac_f32_e32 v115, v7, v216
	s_waitcnt lgkmcnt(1)
	v_mfma_f32_16x16x32_bf16 v[246:249], v[26:29], v[230:233], 0
	v_mfma_f32_16x16x32_bf16 v[250:253], v[34:37], v[230:233], 0
	v_mfma_f32_16x16x32_bf16 v[246:249], v[30:33], v[234:237], v[246:249]
	v_mfma_f32_16x16x32_bf16 v[250:253], v[38:41], v[234:237], v[250:253]
	ds_read_b128 v[238:241], v152
	ds_read_b128 v[242:245], v151
	ds_read_b32 v7, v137 offset:768
	v_max_f32_e32 v9, 0, v206
	v_max_f32_e32 v200, 0, v207
	v_max_f32_e32 v201, 0, v208
	v_max_f32_e32 v216, 0, v209
	v_fmac_f32_e32 v110, v217, v9
	v_fmac_f32_e32 v109, v217, v200
	v_fmac_f32_e32 v112, v217, v201
	v_fmac_f32_e32 v111, v217, v216
	v_max_f32_e32 v9, 0, v210
	v_max_f32_e32 v200, 0, v211
	v_max_f32_e32 v201, 0, v212
	v_max_f32_e32 v216, 0, v213
	v_fmac_f32_e32 v114, v217, v9
	v_fmac_f32_e32 v113, v217, v200
	v_fmac_f32_e32 v116, v217, v201
	v_fmac_f32_e32 v115, v217, v216
	s_waitcnt lgkmcnt(1)
	v_mfma_f32_16x16x32_bf16 v[206:209], v[26:29], v[238:241], 0
	v_mfma_f32_16x16x32_bf16 v[210:213], v[34:37], v[238:241], 0
	v_mfma_f32_16x16x32_bf16 v[206:209], v[30:33], v[242:245], v[206:209]
	v_mfma_f32_16x16x32_bf16 v[210:213], v[38:41], v[242:245], v[210:213]
	v_max_f32_e32 v9, 0, v246
	v_max_f32_e32 v200, 0, v247
	v_max_f32_e32 v201, 0, v248
	v_max_f32_e32 v216, 0, v249
	v_fmac_f32_e32 v110, v6, v9
	v_fmac_f32_e32 v109, v6, v200
	v_fmac_f32_e32 v112, v6, v201
	v_fmac_f32_e32 v111, v6, v216
	v_max_f32_e32 v9, 0, v250
	v_max_f32_e32 v200, 0, v251
	v_max_f32_e32 v201, 0, v252
	v_max_f32_e32 v216, 0, v253
	v_fmac_f32_e32 v114, v6, v9
	v_fmac_f32_e32 v113, v6, v200
	v_fmac_f32_e32 v116, v6, v201
	v_fmac_f32_e32 v115, v6, v216
	s_waitcnt lgkmcnt(0)
	v_max_f32_e32 v9, 0, v206
	v_max_f32_e32 v200, 0, v207
	v_max_f32_e32 v201, 0, v208
	v_max_f32_e32 v216, 0, v209
	v_fmac_f32_e32 v110, v7, v9
	v_fmac_f32_e32 v109, v7, v200
	v_fmac_f32_e32 v112, v7, v201
	v_fmac_f32_e32 v111, v7, v216
	v_max_f32_e32 v9, 0, v210
	v_max_f32_e32 v200, 0, v211
	v_max_f32_e32 v201, 0, v212
	v_max_f32_e32 v216, 0, v213
	v_fmac_f32_e32 v114, v7, v9
	v_fmac_f32_e32 v113, v7, v200
	v_fmac_f32_e32 v116, v7, v201
	v_fmac_f32_e32 v115, v7, v216
	v_ashrrev_i32_e32 v9, 31, v110
	v_bitop3_b32 v110, v9, v110, v8 bitop3:0x36
	v_ashrrev_i32_e32 v200, 31, v109
	v_bitop3_b32 v109, v200, v109, v8 bitop3:0x36
	v_ashrrev_i32_e32 v201, 31, v112
	v_bitop3_b32 v112, v201, v112, v8 bitop3:0x36
	v_ashrrev_i32_e32 v216, 31, v111
	v_bitop3_b32 v111, v216, v111, v8 bitop3:0x36
	v_ashrrev_i32_e32 v9, 31, v114
	v_bitop3_b32 v114, v9, v114, v8 bitop3:0x36
	v_ashrrev_i32_e32 v200, 31, v113
	v_bitop3_b32 v113, v200, v113, v8 bitop3:0x36
	v_ashrrev_i32_e32 v201, 31, v116
	v_bitop3_b32 v116, v201, v116, v8 bitop3:0x36
	v_ashrrev_i32_e32 v216, 31, v115
	v_bitop3_b32 v115, v216, v115, v8 bitop3:0x36
	v_lshrrev_b32_e32 v9, 24, v110
	v_lshl_add_u32 v9, v9, 6, v0
	ds_add_u32 v9, v205 offset:16384
	v_lshrrev_b32_e32 v200, 24, v109
	v_lshl_add_u32 v200, v200, 6, v0
	ds_add_u32 v200, v205 offset:16384
	v_lshrrev_b32_e32 v201, 24, v112
	v_lshl_add_u32 v201, v201, 6, v0
	ds_add_u32 v201, v205 offset:16384
	v_lshrrev_b32_e32 v216, 24, v111
	v_lshl_add_u32 v216, v216, 6, v0
	ds_add_u32 v216, v205 offset:16384
	v_lshrrev_b32_e32 v9, 24, v114
	v_lshl_add_u32 v9, v9, 6, v0
	ds_add_u32 v9, v205 offset:16384
	v_lshrrev_b32_e32 v200, 24, v113
	v_lshl_add_u32 v200, v200, 6, v0
	ds_add_u32 v200, v205 offset:16384
	v_lshrrev_b32_e32 v201, 24, v116
	v_lshl_add_u32 v201, v201, 6, v0
	ds_add_u32 v201, v205 offset:16384
	v_lshrrev_b32_e32 v216, 24, v115
	v_lshl_add_u32 v216, v216, 6, v0
	ds_add_u32 v216, v205 offset:16384
	ds_read_b128 v[230:233], v182
	ds_read_b128 v[234:237], v183
	ds_read_b32 v6, v137 offset:320
	s_waitcnt vmcnt(0)
	s_cmp_lt_i32 s4, 5
	s_cbranch_scc1 .Lp0_nopf_3
	v_add_co_u32_e32 v22, vcc, 0xf000, v22
	s_nop 1
	v_addc_co_u32_e32 v23, vcc, 0, v23, vcc
	global_load_dwordx4 v[26:29], v[22:23], off
	global_load_dwordx4 v[30:33], v[22:23], off offset:64
	global_load_dwordx4 v[34:37], v[22:23], off offset:2048
	global_load_dwordx4 v[38:41], v[22:23], off offset:2112
; #define LAS __attribute__((address_space(3)))
; __device__ __forceinline__ unsigned fkey(float f) { const unsigned u = __float_as_uint(f); return (u & 0x80000000u) ? ~u : (u | 0x80000000u); }
; #define SEL_HADD(idx_) __hip_atomic_fetch_add(&hist[(idx_)], 1u, __ATOMIC_RELAXED, __HIP_MEMORY_SCOPE_WORKGROUP)
; __device__ __forceinline__ void sel_unit(LAS char* lds, int b, int u, const bf16_t* QI, const bf16_t* KIDX, const float* WIDX, unsigned long long* MASK) {
;     ...
;     for (int j = 0; j < 8; ++j) {
;         if (j < nj) {
;             int t = wid + 8 * j; asm volatile("" : "+s"(t));
; #pragma unroll
;             for (int kh = 0; kh < 2; ++kh) {
;             bf16x8 kf[2][2];
; #pragma unroll
;             for (int kb = 0; kb < 2; ++kb)
; #pragma unroll
;                 for (int ks = 0; ks < 2; ++ks) kf[kb][ks] = *(const bf16x8*)(KIDX + (rowbase + 64 * t + 32 * kh + 16 * kb + q16) * 64 + 32 * ks + 8 * kg);
; #pragma unroll
;             for (int kb = 0; kb < 2; ++kb) {
;                 f32x4 s = (f32x4){0.f, 0.f, 0.f, 0.f};
; #pragma unroll
;                 for (int hh = 0; hh < 8; ++hh) {
;                     f32x4 a = (f32x4){0.f, 0.f, 0.f, 0.f};
; #pragma unroll
;                     for (int ks = 0; ks < 2; ++ks) {
;                         const bf16x8 qv = *(const LAS bf16x8*)(lds + L_QI + q16 * 1024 + (((hh * 8 + 4 * ks + kg) ^ q16) << 4));
;                         a = __builtin_amdgcn_mfma_f32_16x16x32_bf16(kf[kb][ks], qv, a, 0, 0, 0);
;                     }
;                     const float wh = wl[hh * 16];
; #pragma unroll
;                     for (int i = 0; i < 4; ++i) s[i] += wh * fmaxf(a[i], 0.f);
;                 }
;                 u32x4 kk; kk.x = fkey(s[0]); kk.y = fkey(s[1]); kk.z = fkey(s[2]); kk.w = fkey(s[3]);
;                 sc[j][2 * kh + kb] = kk;
; #pragma unroll
;                 for (int i = 0; i < 4; ++i) SEL_HADD((kk[i] >> 24) * 16 + q16);
;                 __builtin_amdgcn_sched_barrier(0);
.Lp0_nopf_3:
	s_waitcnt lgkmcnt(1)
	v_mfma_f32_16x16x32_bf16 v[246:249], v[42:45], v[230:233], 0
	v_mfma_f32_16x16x32_bf16 v[250:253], v[50:53], v[230:233], 0
	v_mfma_f32_16x16x32_bf16 v[246:249], v[46:49], v[234:237], v[246:249]
	v_mfma_f32_16x16x32_bf16 v[250:253], v[2:5], v[234:237], v[250:253]
	ds_read_b128 v[238:241], v184
	ds_read_b128 v[242:245], v185
	ds_read_b32 v7, v137 offset:384
	s_waitcnt lgkmcnt(1)
	v_mfma_f32_16x16x32_bf16 v[206:209], v[42:45], v[238:241], 0
	v_mfma_f32_16x16x32_bf16 v[210:213], v[50:53], v[238:241], 0
	v_mfma_f32_16x16x32_bf16 v[206:209], v[46:49], v[242:245], v[206:209]
	v_mfma_f32_16x16x32_bf16 v[210:213], v[2:5], v[242:245], v[210:213]
	ds_read_b128 v[230:233], v179
	ds_read_b128 v[234:237], v180
	ds_read_b32 v217, v137 offset:448
	v_max_f32_e32 v9, 0, v246
	v_max_f32_e32 v200, 0, v247
	v_max_f32_e32 v201, 0, v248
	v_max_f32_e32 v216, 0, v249
	v_fma_f32 v118, v6, v9, 0
	v_fma_f32 v117, v6, v200, 0
	v_fma_f32 v120, v6, v201, 0
	v_fma_f32 v119, v6, v216, 0
	v_max_f32_e32 v9, 0, v250
	v_max_f32_e32 v200, 0, v251
	v_max_f32_e32 v201, 0, v252
	v_max_f32_e32 v216, 0, v253
	v_fma_f32 v122, v6, v9, 0
	v_fma_f32 v121, v6, v200, 0
	v_fma_f32 v124, v6, v201, 0
	v_fma_f32 v123, v6, v216, 0
	s_waitcnt lgkmcnt(1)
	v_mfma_f32_16x16x32_bf16 v[246:249], v[42:45], v[230:233], 0
	v_mfma_f32_16x16x32_bf16 v[250:253], v[50:53], v[230:233], 0
	v_mfma_f32_16x16x32_bf16 v[246:249], v[46:49], v[234:237], v[246:249]
	v_mfma_f32_16x16x32_bf16 v[250:253], v[2:5], v[234:237], v[250:253]
	ds_read_b128 v[238:241], v176
	ds_read_b128 v[242:245], v159
	ds_read_b32 v6, v137 offset:512
	v_max_f32_e32 v9, 0, v206
	v_max_f32_e32 v200, 0, v207
	v_max_f32_e32 v201, 0, v208
	v_max_f32_e32 v216, 0, v209
	v_fmac_f32_e32 v118, v7, v9
	v_fmac_f32_e32 v117, v7, v200
	v_fmac_f32_e32 v120, v7, v201
	v_fmac_f32_e32 v119, v7, v216
	v_max_f32_e32 v9, 0, v210
	v_max_f32_e32 v200, 0, v211
	v_max_f32_e32 v201, 0, v212
	v_max_f32_e32 v216, 0, v213
	v_fmac_f32_e32 v122, v7, v9
	v_fmac_f32_e32 v121, v7, v200
	v_fmac_f32_e32 v124, v7, v201
	v_fmac_f32_e32 v123, v7, v216
	s_waitcnt lgkmcnt(1)
	v_mfma_f32_16x16x32_bf16 v[206:209], v[42:45], v[238:241], 0
	v_mfma_f32_16x16x32_bf16 v[210:213], v[50:53], v[238:241], 0
	v_mfma_f32_16x16x32_bf16 v[206:209], v[46:49], v[242:245], v[206:209]
	v_mfma_f32_16x16x32_bf16 v[210:213], v[2:5], v[242:245], v[210:213]
	ds_read_b128 v[230:233], v158
	ds_read_b128 v[234:237], v157
	ds_read_b32 v7, v137 offset:576
	v_max_f32_e32 v9, 0, v246
	v_max_f32_e32 v200, 0, v247
	v_max_f32_e32 v201, 0, v248
	v_max_f32_e32 v216, 0, v249
	v_fmac_f32_e32 v118, v217, v9
	v_fmac_f32_e32 v117, v217, v200
	v_fmac_f32_e32 v120, v217, v201
	v_fmac_f32_e32 v119, v217, v216
	v_max_f32_e32 v9, 0, v250
	v_max_f32_e32 v200, 0, v251
	v_max_f32_e32 v201, 0, v252
	v_max_f32_e32 v216, 0, v253
	v_fmac_f32_e32 v122, v217, v9
	v_fmac_f32_e32 v121, v217, v200
	v_fmac_f32_e32 v124, v217, v201
	v_fmac_f32_e32 v123, v217, v216
	s_waitcnt lgkmcnt(1)
	v_mfma_f32_16x16x32_bf16 v[246:249], v[42:45], v[230:233], 0
	v_mfma_f32_16x16x32_bf16 v[250:253], v[50:53], v[230:233], 0
	v_mfma_f32_16x16x32_bf16 v[246:249], v[46:49], v[234:237], v[246:249]
	v_mfma_f32_16x16x32_bf16 v[250:253], v[2:5], v[234:237], v[250:253]
	ds_read_b128 v[238:241], v156
	ds_read_b128 v[242:245], v155
	ds_read_b32 v217, v137 offset:640
	v_max_f32_e32 v9, 0, v206
	v_max_f32_e32 v200, 0, v207
	v_max_f32_e32 v201, 0, v208
	v_max_f32_e32 v216, 0, v209
	v_fmac_f32_e32 v118, v6, v9
	v_fmac_f32_e32 v117, v6, v200
	v_fmac_f32_e32 v120, v6, v201
	v_fmac_f32_e32 v119, v6, v216
	v_max_f32_e32 v9, 0, v210
	v_max_f32_e32 v200, 0, v211
	v_max_f32_e32 v201, 0, v212
	v_max_f32_e32 v216, 0, v213
	v_fmac_f32_e32 v122, v6, v9
	v_fmac_f32_e32 v121, v6, v200
	v_fmac_f32_e32 v124, v6, v201
	v_fmac_f32_e32 v123, v6, v216
	s_waitcnt lgkmcnt(1)
	v_mfma_f32_16x16x32_bf16 v[206:209], v[42:45], v[238:241], 0
	v_mfma_f32_16x16x32_bf16 v[210:213], v[50:53], v[238:241], 0
	v_mfma_f32_16x16x32_bf16 v[206:209], v[46:49], v[242:245], v[206:209]
	v_mfma_f32_16x16x32_bf16 v[210:213], v[2:5], v[242:245], v[210:213]
	ds_read_b128 v[230:233], v154
	ds_read_b128 v[234:237], v153
	ds_read_b32 v6, v137 offset:704
	v_max_f32_e32 v9, 0, v246
	v_max_f32_e32 v200, 0, v247
	v_max_f32_e32 v201, 0, v248
	v_max_f32_e32 v216, 0, v249
	v_fmac_f32_e32 v118, v7, v9
	v_fmac_f32_e32 v117, v7, v200
	v_fmac_f32_e32 v120, v7, v201
	v_fmac_f32_e32 v119, v7, v216
	v_max_f32_e32 v9, 0, v250
	v_max_f32_e32 v200, 0, v251
	v_max_f32_e32 v201, 0, v252
	v_max_f32_e32 v216, 0, v253
	v_fmac_f32_e32 v122, v7, v9
	v_fmac_f32_e32 v121, v7, v200
	v_fmac_f32_e32 v124, v7, v201
	v_fmac_f32_e32 v123, v7, v216
	s_waitcnt lgkmcnt(1)
	v_mfma_f32_16x16x32_bf16 v[246:249], v[42:45], v[230:233], 0
	v_mfma_f32_16x16x32_bf16 v[250:253], v[50:53], v[230:233], 0
	v_mfma_f32_16x16x32_bf16 v[246:249], v[46:49], v[234:237], v[246:249]
	v_mfma_f32_16x16x32_bf16 v[250:253], v[2:5], v[234:237], v[250:253]
	ds_read_b128 v[238:241], v152
	ds_read_b128 v[242:245], v151
	ds_read_b32 v7, v137 offset:768
	v_max_f32_e32 v9, 0, v206
	v_max_f32_e32 v200, 0, v207
	v_max_f32_e32 v201, 0, v208
	v_max_f32_e32 v216, 0, v209
	v_fmac_f32_e32 v118, v217, v9
	v_fmac_f32_e32 v117, v217, v200
	v_fmac_f32_e32 v120, v217, v201
	v_fmac_f32_e32 v119, v217, v216
	v_max_f32_e32 v9, 0, v210
	v_max_f32_e32 v200, 0, v211
	v_max_f32_e32 v201, 0, v212
	v_max_f32_e32 v216, 0, v213
	v_fmac_f32_e32 v122, v217, v9
	v_fmac_f32_e32 v121, v217, v200
	v_fmac_f32_e32 v124, v217, v201
	v_fmac_f32_e32 v123, v217, v216
	s_waitcnt lgkmcnt(1)
; #define LAS __attribute__((address_space(3)))
; __device__ __forceinline__ unsigned fkey(float f) { const unsigned u = __float_as_uint(f); return (u & 0x80000000u) ? ~u : (u | 0x80000000u); }
; #define SEL_HADD(idx_) __hip_atomic_fetch_add(&hist[(idx_)], 1u, __ATOMIC_RELAXED, __HIP_MEMORY_SCOPE_WORKGROUP)
; __device__ __forceinline__ void sel_unit(LAS char* lds, int b, int u, const bf16_t* QI, const bf16_t* KIDX, const float* WIDX, unsigned long long* MASK) {
;     ...
;     for (int j = 0; j < 8; ++j) {
;         if (j < nj) {
;             int t = wid + 8 * j; asm volatile("" : "+s"(t));
; #pragma unroll
;             for (int kh = 0; kh < 2; ++kh) {
;             bf16x8 kf[2][2];
; #pragma unroll
;             for (int kb = 0; kb < 2; ++kb)
; #pragma unroll
;                 for (int ks = 0; ks < 2; ++ks) kf[kb][ks] = *(const bf16x8*)(KIDX + (rowbase + 64 * t + 32 * kh + 16 * kb + q16) * 64 + 32 * ks + 8 * kg);
; #pragma unroll
;             for (int kb = 0; kb < 2; ++kb) {
;                 f32x4 s = (f32x4){0.f, 0.f, 0.f, 0.f};
; #pragma unroll
;                 for (int hh = 0; hh < 8; ++hh) {
;                     f32x4 a = (f32x4){0.f, 0.f, 0.f, 0.f};
; #pragma unroll
;                     for (int ks = 0; ks < 2; ++ks) {
;                         const bf16x8 qv = *(const LAS bf16x8*)(lds + L_QI + q16 * 1024 + (((hh * 8 + 4 * ks + kg) ^ q16) << 4));
;                         a = __builtin_amdgcn_mfma_f32_16x16x32_bf16(kf[kb][ks], qv, a, 0, 0, 0);
;                     }
;                     const float wh = wl[hh * 16];
; #pragma unroll
;                     for (int i = 0; i < 4; ++i) s[i] += wh * fmaxf(a[i], 0.f);
;                 }
;                 u32x4 kk; kk.x = fkey(s[0]); kk.y = fkey(s[1]); kk.z = fkey(s[2]); kk.w = fkey(s[3]);
;                 sc[j][2 * kh + kb] = kk;
; #pragma unroll
;                 for (int i = 0; i < 4; ++i) SEL_HADD((kk[i] >> 24) * 16 + q16);
;                 __builtin_amdgcn_sched_barrier(0);
	v_mfma_f32_16x16x32_bf16 v[206:209], v[42:45], v[238:241], 0
	v_mfma_f32_16x16x32_bf16 v[210:213], v[50:53], v[238:241], 0
	v_mfma_f32_16x16x32_bf16 v[206:209], v[46:49], v[242:245], v[206:209]
	v_mfma_f32_16x16x32_bf16 v[210:213], v[2:5], v[242:245], v[210:213]
	v_max_f32_e32 v9, 0, v246
	v_max_f32_e32 v200, 0, v247
	v_max_f32_e32 v201, 0, v248
	v_max_f32_e32 v216, 0, v249
	v_fmac_f32_e32 v118, v6, v9
	v_fmac_f32_e32 v117, v6, v200
	v_fmac_f32_e32 v120, v6, v201
	v_fmac_f32_e32 v119, v6, v216
	v_max_f32_e32 v9, 0, v250
	v_max_f32_e32 v200, 0, v251
	v_max_f32_e32 v201, 0, v252
	v_max_f32_e32 v216, 0, v253
	v_fmac_f32_e32 v122, v6, v9
	v_fmac_f32_e32 v121, v6, v200
	v_fmac_f32_e32 v124, v6, v201
	v_fmac_f32_e32 v123, v6, v216
	s_waitcnt lgkmcnt(0)
	v_max_f32_e32 v9, 0, v206
	v_max_f32_e32 v200, 0, v207
	v_max_f32_e32 v201, 0, v208
	v_max_f32_e32 v216, 0, v209
	v_fmac_f32_e32 v118, v7, v9
	v_fmac_f32_e32 v117, v7, v200
	v_fmac_f32_e32 v120, v7, v201
	v_fmac_f32_e32 v119, v7, v216
	v_max_f32_e32 v9, 0, v210
	v_max_f32_e32 v200, 0, v211
	v_max_f32_e32 v201, 0, v212
	v_max_f32_e32 v216, 0, v213
	v_fmac_f32_e32 v122, v7, v9
	v_fmac_f32_e32 v121, v7, v200
	v_fmac_f32_e32 v124, v7, v201
	v_fmac_f32_e32 v123, v7, v216
	v_ashrrev_i32_e32 v9, 31, v118
	v_bitop3_b32 v118, v9, v118, v8 bitop3:0x36
	v_ashrrev_i32_e32 v200, 31, v117
	v_bitop3_b32 v117, v200, v117, v8 bitop3:0x36
	v_ashrrev_i32_e32 v201, 31, v120
	v_bitop3_b32 v120, v201, v120, v8 bitop3:0x36
	v_ashrrev_i32_e32 v216, 31, v119
	v_bitop3_b32 v119, v216, v119, v8 bitop3:0x36
	v_ashrrev_i32_e32 v9, 31, v122
	v_bitop3_b32 v122, v9, v122, v8 bitop3:0x36
	v_ashrrev_i32_e32 v200, 31, v121
	v_bitop3_b32 v121, v200, v121, v8 bitop3:0x36
	v_ashrrev_i32_e32 v201, 31, v124
	v_bitop3_b32 v124, v201, v124, v8 bitop3:0x36
	v_ashrrev_i32_e32 v216, 31, v123
	v_bitop3_b32 v123, v216, v123, v8 bitop3:0x36
	v_lshrrev_b32_e32 v9, 24, v118
	v_lshl_add_u32 v9, v9, 6, v0
	ds_add_u32 v9, v205 offset:16384
	v_lshrrev_b32_e32 v200, 24, v117
	v_lshl_add_u32 v200, v200, 6, v0
	ds_add_u32 v200, v205 offset:16384
	v_lshrrev_b32_e32 v201, 24, v120
	v_lshl_add_u32 v201, v201, 6, v0
	ds_add_u32 v201, v205 offset:16384
	v_lshrrev_b32_e32 v216, 24, v119
	v_lshl_add_u32 v216, v216, 6, v0
	ds_add_u32 v216, v205 offset:16384
	v_lshrrev_b32_e32 v9, 24, v122
	v_lshl_add_u32 v9, v9, 6, v0
	ds_add_u32 v9, v205 offset:16384
	v_lshrrev_b32_e32 v200, 24, v121
	v_lshl_add_u32 v200, v200, 6, v0
	ds_add_u32 v200, v205 offset:16384
	v_lshrrev_b32_e32 v201, 24, v124
	v_lshl_add_u32 v201, v201, 6, v0
	ds_add_u32 v201, v205 offset:16384
	v_lshrrev_b32_e32 v216, 24, v123
	v_lshl_add_u32 v216, v216, 6, v0
	ds_add_u32 v216, v205 offset:16384
.LBB0_664:
	s_cmp_gt_i32 s4, 4
	s_cselect_b64 s[24:25], -1, 0
	s_cmp_lt_i32 s4, 5
	s_cbranch_scc1 .LBB0_666
	ds_read_b128 v[230:233], v182
	ds_read_b128 v[234:237], v183
	ds_read_b32 v6, v137 offset:320
	s_waitcnt vmcnt(0)
	v_add_co_u32_e32 v22, vcc, s96, v22
	s_nop 1
	v_addc_co_u32_e32 v23, vcc, 0, v23, vcc
	global_load_dwordx4 v[42:45], v[22:23], off
	global_load_dwordx4 v[46:49], v[22:23], off offset:64
	global_load_dwordx4 v[50:53], v[22:23], off offset:2048
	global_load_dwordx4 v[2:5], v[22:23], off offset:2112
	s_waitcnt lgkmcnt(1)
	v_mfma_f32_16x16x32_bf16 v[246:249], v[26:29], v[230:233], 0
	v_mfma_f32_16x16x32_bf16 v[250:253], v[34:37], v[230:233], 0
	v_mfma_f32_16x16x32_bf16 v[246:249], v[30:33], v[234:237], v[246:249]
	v_mfma_f32_16x16x32_bf16 v[250:253], v[38:41], v[234:237], v[250:253]
	ds_read_b128 v[238:241], v184
	ds_read_b128 v[242:245], v185
	ds_read_b32 v7, v137 offset:384
	s_waitcnt lgkmcnt(1)
	v_mfma_f32_16x16x32_bf16 v[206:209], v[26:29], v[238:241], 0
	v_mfma_f32_16x16x32_bf16 v[210:213], v[34:37], v[238:241], 0
	v_mfma_f32_16x16x32_bf16 v[206:209], v[30:33], v[242:245], v[206:209]
	v_mfma_f32_16x16x32_bf16 v[210:213], v[38:41], v[242:245], v[210:213]
	ds_read_b128 v[230:233], v179
	ds_read_b128 v[234:237], v180
	ds_read_b32 v217, v137 offset:448
	v_max_f32_e32 v9, 0, v246
	v_max_f32_e32 v200, 0, v247
	v_max_f32_e32 v201, 0, v248
	v_max_f32_e32 v216, 0, v249
	v_fma_f32 v126, v6, v9, 0
	v_fma_f32 v125, v6, v200, 0
	v_fma_f32 v128, v6, v201, 0
	v_fma_f32 v127, v6, v216, 0
	v_max_f32_e32 v9, 0, v250
	v_max_f32_e32 v200, 0, v251
	v_max_f32_e32 v201, 0, v252
	v_max_f32_e32 v216, 0, v253
	v_fma_f32 v130, v6, v9, 0
	v_fma_f32 v129, v6, v200, 0
	v_fma_f32 v132, v6, v201, 0
	v_fma_f32 v131, v6, v216, 0
	s_waitcnt lgkmcnt(1)
	v_mfma_f32_16x16x32_bf16 v[246:249], v[26:29], v[230:233], 0
	v_mfma_f32_16x16x32_bf16 v[250:253], v[34:37], v[230:233], 0
	v_mfma_f32_16x16x32_bf16 v[246:249], v[30:33], v[234:237], v[246:249]
	v_mfma_f32_16x16x32_bf16 v[250:253], v[38:41], v[234:237], v[250:253]
	ds_read_b128 v[238:241], v176
	ds_read_b128 v[242:245], v159
	ds_read_b32 v6, v137 offset:512
	v_max_f32_e32 v9, 0, v206
	v_max_f32_e32 v200, 0, v207
	v_max_f32_e32 v201, 0, v208
	v_max_f32_e32 v216, 0, v209
	v_fmac_f32_e32 v126, v7, v9
	v_fmac_f32_e32 v125, v7, v200
	v_fmac_f32_e32 v128, v7, v201
	v_fmac_f32_e32 v127, v7, v216
	v_max_f32_e32 v9, 0, v210
	v_max_f32_e32 v200, 0, v211
	v_max_f32_e32 v201, 0, v212
	v_max_f32_e32 v216, 0, v213
	v_fmac_f32_e32 v130, v7, v9
	v_fmac_f32_e32 v129, v7, v200
	v_fmac_f32_e32 v132, v7, v201
	v_fmac_f32_e32 v131, v7, v216
	s_waitcnt lgkmcnt(1)
; #define LAS __attribute__((address_space(3)))
; __device__ __forceinline__ unsigned fkey(float f) { const unsigned u = __float_as_uint(f); return (u & 0x80000000u) ? ~u : (u | 0x80000000u); }
; #define SEL_HADD(idx_) __hip_atomic_fetch_add(&hist[(idx_)], 1u, __ATOMIC_RELAXED, __HIP_MEMORY_SCOPE_WORKGROUP)
; __device__ __forceinline__ void sel_unit(LAS char* lds, int b, int u, const bf16_t* QI, const bf16_t* KIDX, const float* WIDX, unsigned long long* MASK) {
;     ...
;     for (int j = 0; j < 8; ++j) {
;         if (j < nj) {
;             int t = wid + 8 * j; asm volatile("" : "+s"(t));
; #pragma unroll
;             for (int kh = 0; kh < 2; ++kh) {
;             bf16x8 kf[2][2];
; #pragma unroll
;             for (int kb = 0; kb < 2; ++kb)
; #pragma unroll
;                 for (int ks = 0; ks < 2; ++ks) kf[kb][ks] = *(const bf16x8*)(KIDX + (rowbase + 64 * t + 32 * kh + 16 * kb + q16) * 64 + 32 * ks + 8 * kg);
; #pragma unroll
;             for (int kb = 0; kb < 2; ++kb) {
;                 f32x4 s = (f32x4){0.f, 0.f, 0.f, 0.f};
; #pragma unroll
;                 for (int hh = 0; hh < 8; ++hh) {
;                     f32x4 a = (f32x4){0.f, 0.f, 0.f, 0.f};
; #pragma unroll
;                     for (int ks = 0; ks < 2; ++ks) {
;                         const bf16x8 qv = *(const LAS bf16x8*)(lds + L_QI + q16 * 1024 + (((hh * 8 + 4 * ks + kg) ^ q16) << 4));
;                         a = __builtin_amdgcn_mfma_f32_16x16x32_bf16(kf[kb][ks], qv, a, 0, 0, 0);
;                     }
;                     const float wh = wl[hh * 16];
; #pragma unroll
;                     for (int i = 0; i < 4; ++i) s[i] += wh * fmaxf(a[i], 0.f);
;                 }
;                 u32x4 kk; kk.x = fkey(s[0]); kk.y = fkey(s[1]); kk.z = fkey(s[2]); kk.w = fkey(s[3]);
;                 sc[j][2 * kh + kb] = kk;
; #pragma unroll
;                 for (int i = 0; i < 4; ++i) SEL_HADD((kk[i] >> 24) * 16 + q16);
;                 __builtin_amdgcn_sched_barrier(0);
	v_mfma_f32_16x16x32_bf16 v[206:209], v[26:29], v[238:241], 0
	v_mfma_f32_16x16x32_bf16 v[210:213], v[34:37], v[238:241], 0
	v_mfma_f32_16x16x32_bf16 v[206:209], v[30:33], v[242:245], v[206:209]
	v_mfma_f32_16x16x32_bf16 v[210:213], v[38:41], v[242:245], v[210:213]
	ds_read_b128 v[230:233], v158
	ds_read_b128 v[234:237], v157
	ds_read_b32 v7, v137 offset:576
	v_max_f32_e32 v9, 0, v246
	v_max_f32_e32 v200, 0, v247
	v_max_f32_e32 v201, 0, v248
	v_max_f32_e32 v216, 0, v249
	v_fmac_f32_e32 v126, v217, v9
	v_fmac_f32_e32 v125, v217, v200
	v_fmac_f32_e32 v128, v217, v201
	v_fmac_f32_e32 v127, v217, v216
	v_max_f32_e32 v9, 0, v250
	v_max_f32_e32 v200, 0, v251
	v_max_f32_e32 v201, 0, v252
	v_max_f32_e32 v216, 0, v253
	v_fmac_f32_e32 v130, v217, v9
	v_fmac_f32_e32 v129, v217, v200
	v_fmac_f32_e32 v132, v217, v201
	v_fmac_f32_e32 v131, v217, v216
	s_waitcnt lgkmcnt(1)
	v_mfma_f32_16x16x32_bf16 v[246:249], v[26:29], v[230:233], 0
	v_mfma_f32_16x16x32_bf16 v[250:253], v[34:37], v[230:233], 0
	v_mfma_f32_16x16x32_bf16 v[246:249], v[30:33], v[234:237], v[246:249]
	v_mfma_f32_16x16x32_bf16 v[250:253], v[38:41], v[234:237], v[250:253]
	ds_read_b128 v[238:241], v156
	ds_read_b128 v[242:245], v155
	ds_read_b32 v217, v137 offset:640
	v_max_f32_e32 v9, 0, v206
	v_max_f32_e32 v200, 0, v207
	v_max_f32_e32 v201, 0, v208
	v_max_f32_e32 v216, 0, v209
	v_fmac_f32_e32 v126, v6, v9
	v_fmac_f32_e32 v125, v6, v200
	v_fmac_f32_e32 v128, v6, v201
	v_fmac_f32_e32 v127, v6, v216
	v_max_f32_e32 v9, 0, v210
	v_max_f32_e32 v200, 0, v211
	v_max_f32_e32 v201, 0, v212
	v_max_f32_e32 v216, 0, v213
	v_fmac_f32_e32 v130, v6, v9
	v_fmac_f32_e32 v129, v6, v200
	v_fmac_f32_e32 v132, v6, v201
	v_fmac_f32_e32 v131, v6, v216
	s_waitcnt lgkmcnt(1)
	v_mfma_f32_16x16x32_bf16 v[206:209], v[26:29], v[238:241], 0
	v_mfma_f32_16x16x32_bf16 v[210:213], v[34:37], v[238:241], 0
	v_mfma_f32_16x16x32_bf16 v[206:209], v[30:33], v[242:245], v[206:209]
	v_mfma_f32_16x16x32_bf16 v[210:213], v[38:41], v[242:245], v[210:213]
	ds_read_b128 v[230:233], v154
	ds_read_b128 v[234:237], v153
	ds_read_b32 v6, v137 offset:704
	v_max_f32_e32 v9, 0, v246
	v_max_f32_e32 v200, 0, v247
	v_max_f32_e32 v201, 0, v248
	v_max_f32_e32 v216, 0, v249
	v_fmac_f32_e32 v126, v7, v9
	v_fmac_f32_e32 v125, v7, v200
	v_fmac_f32_e32 v128, v7, v201
	v_fmac_f32_e32 v127, v7, v216
	v_max_f32_e32 v9, 0, v250
	v_max_f32_e32 v200, 0, v251
	v_max_f32_e32 v201, 0, v252
	v_max_f32_e32 v216, 0, v253
	v_fmac_f32_e32 v130, v7, v9
	v_fmac_f32_e32 v129, v7, v200
	v_fmac_f32_e32 v132, v7, v201
	v_fmac_f32_e32 v131, v7, v216
	s_waitcnt lgkmcnt(1)
	v_mfma_f32_16x16x32_bf16 v[246:249], v[26:29], v[230:233], 0
	v_mfma_f32_16x16x32_bf16 v[250:253], v[34:37], v[230:233], 0
	v_mfma_f32_16x16x32_bf16 v[246:249], v[30:33], v[234:237], v[246:249]
	v_mfma_f32_16x16x32_bf16 v[250:253], v[38:41], v[234:237], v[250:253]
	ds_read_b128 v[238:241], v152
	ds_read_b128 v[242:245], v151
	ds_read_b32 v7, v137 offset:768
	v_max_f32_e32 v9, 0, v206
	v_max_f32_e32 v200, 0, v207
	v_max_f32_e32 v201, 0, v208
	v_max_f32_e32 v216, 0, v209
	v_fmac_f32_e32 v126, v217, v9
	v_fmac_f32_e32 v125, v217, v200
	v_fmac_f32_e32 v128, v217, v201
	v_fmac_f32_e32 v127, v217, v216
	v_max_f32_e32 v9, 0, v210
	v_max_f32_e32 v200, 0, v211
	v_max_f32_e32 v201, 0, v212
	v_max_f32_e32 v216, 0, v213
	v_fmac_f32_e32 v130, v217, v9
	v_fmac_f32_e32 v129, v217, v200
	v_fmac_f32_e32 v132, v217, v201
	v_fmac_f32_e32 v131, v217, v216
	s_waitcnt lgkmcnt(1)
	v_mfma_f32_16x16x32_bf16 v[206:209], v[26:29], v[238:241], 0
	v_mfma_f32_16x16x32_bf16 v[210:213], v[34:37], v[238:241], 0
	v_mfma_f32_16x16x32_bf16 v[206:209], v[30:33], v[242:245], v[206:209]
	v_mfma_f32_16x16x32_bf16 v[210:213], v[38:41], v[242:245], v[210:213]
	v_max_f32_e32 v9, 0, v246
	v_max_f32_e32 v200, 0, v247
	v_max_f32_e32 v201, 0, v248
	v_max_f32_e32 v216, 0, v249
	v_fmac_f32_e32 v126, v6, v9
	v_fmac_f32_e32 v125, v6, v200
	v_fmac_f32_e32 v128, v6, v201
	v_fmac_f32_e32 v127, v6, v216
	v_max_f32_e32 v9, 0, v250
	v_max_f32_e32 v200, 0, v251
	v_max_f32_e32 v201, 0, v252
	v_max_f32_e32 v216, 0, v253
	v_fmac_f32_e32 v130, v6, v9
	v_fmac_f32_e32 v129, v6, v200
	v_fmac_f32_e32 v132, v6, v201
	v_fmac_f32_e32 v131, v6, v216
	s_waitcnt lgkmcnt(0)
	v_max_f32_e32 v9, 0, v206
	v_max_f32_e32 v200, 0, v207
	v_max_f32_e32 v201, 0, v208
	v_max_f32_e32 v216, 0, v209
	v_fmac_f32_e32 v126, v7, v9
	v_fmac_f32_e32 v125, v7, v200
	v_fmac_f32_e32 v128, v7, v201
	v_fmac_f32_e32 v127, v7, v216
	v_max_f32_e32 v9, 0, v210
	v_max_f32_e32 v200, 0, v211
	v_max_f32_e32 v201, 0, v212
	v_max_f32_e32 v216, 0, v213
	v_fmac_f32_e32 v130, v7, v9
	v_fmac_f32_e32 v129, v7, v200
	v_fmac_f32_e32 v132, v7, v201
	v_fmac_f32_e32 v131, v7, v216
	v_ashrrev_i32_e32 v9, 31, v126
	v_bitop3_b32 v126, v9, v126, v8 bitop3:0x36
	v_ashrrev_i32_e32 v200, 31, v125
	v_bitop3_b32 v125, v200, v125, v8 bitop3:0x36
	v_ashrrev_i32_e32 v201, 31, v128
	v_bitop3_b32 v128, v201, v128, v8 bitop3:0x36
	v_ashrrev_i32_e32 v216, 31, v127
	v_bitop3_b32 v127, v216, v127, v8 bitop3:0x36
	v_ashrrev_i32_e32 v9, 31, v130
	v_bitop3_b32 v130, v9, v130, v8 bitop3:0x36
	v_ashrrev_i32_e32 v200, 31, v129
	v_bitop3_b32 v129, v200, v129, v8 bitop3:0x36
	v_ashrrev_i32_e32 v201, 31, v132
	v_bitop3_b32 v132, v201, v132, v8 bitop3:0x36
	v_ashrrev_i32_e32 v216, 31, v131
	v_bitop3_b32 v131, v216, v131, v8 bitop3:0x36
	v_lshrrev_b32_e32 v9, 24, v126
	v_lshl_add_u32 v9, v9, 6, v0
	ds_add_u32 v9, v205 offset:16384
	v_lshrrev_b32_e32 v200, 24, v125
	v_lshl_add_u32 v200, v200, 6, v0
	ds_add_u32 v200, v205 offset:16384
	v_lshrrev_b32_e32 v201, 24, v128
	v_lshl_add_u32 v201, v201, 6, v0
	ds_add_u32 v201, v205 offset:16384
	v_lshrrev_b32_e32 v216, 24, v127
	v_lshl_add_u32 v216, v216, 6, v0
	ds_add_u32 v216, v205 offset:16384
	v_lshrrev_b32_e32 v9, 24, v130
	v_lshl_add_u32 v9, v9, 6, v0
	ds_add_u32 v9, v205 offset:16384
	v_lshrrev_b32_e32 v200, 24, v129
	v_lshl_add_u32 v200, v200, 6, v0
	ds_add_u32 v200, v205 offset:16384
	v_lshrrev_b32_e32 v201, 24, v132
	v_lshl_add_u32 v201, v201, 6, v0
	ds_add_u32 v201, v205 offset:16384
	v_lshrrev_b32_e32 v216, 24, v131
	v_lshl_add_u32 v216, v216, 6, v0
	ds_add_u32 v216, v205 offset:16384
	ds_read_b128 v[230:233], v182
	ds_read_b128 v[234:237], v183
	ds_read_b32 v6, v137 offset:320
	s_waitcnt vmcnt(0)
	s_cmp_lt_i32 s4, 6
	s_cbranch_scc1 .Lp0_nopf_4
	v_add_co_u32_e32 v22, vcc, 0xf000, v22
	s_nop 1
	v_addc_co_u32_e32 v23, vcc, 0, v23, vcc
	global_load_dwordx4 v[26:29], v[22:23], off
	global_load_dwordx4 v[30:33], v[22:23], off offset:64
	global_load_dwordx4 v[34:37], v[22:23], off offset:2048
	global_load_dwordx4 v[38:41], v[22:23], off offset:2112
; #define LAS __attribute__((address_space(3)))
; __device__ __forceinline__ unsigned fkey(float f) { const unsigned u = __float_as_uint(f); return (u & 0x80000000u) ? ~u : (u | 0x80000000u); }
; #define SEL_HADD(idx_) __hip_atomic_fetch_add(&hist[(idx_)], 1u, __ATOMIC_RELAXED, __HIP_MEMORY_SCOPE_WORKGROUP)
; __device__ __forceinline__ void sel_unit(LAS char* lds, int b, int u, const bf16_t* QI, const bf16_t* KIDX, const float* WIDX, unsigned long long* MASK) {
;     ...
;     for (int j = 0; j < 8; ++j) {
;         if (j < nj) {
;             int t = wid + 8 * j; asm volatile("" : "+s"(t));
; #pragma unroll
;             for (int kh = 0; kh < 2; ++kh) {
;             bf16x8 kf[2][2];
; #pragma unroll
;             for (int kb = 0; kb < 2; ++kb)
; #pragma unroll
;                 for (int ks = 0; ks < 2; ++ks) kf[kb][ks] = *(const bf16x8*)(KIDX + (rowbase + 64 * t + 32 * kh + 16 * kb + q16) * 64 + 32 * ks + 8 * kg);
; #pragma unroll
;             for (int kb = 0; kb < 2; ++kb) {
;                 f32x4 s = (f32x4){0.f, 0.f, 0.f, 0.f};
; #pragma unroll
;                 for (int hh = 0; hh < 8; ++hh) {
;                     f32x4 a = (f32x4){0.f, 0.f, 0.f, 0.f};
; #pragma unroll
;                     for (int ks = 0; ks < 2; ++ks) {
;                         const bf16x8 qv = *(const LAS bf16x8*)(lds + L_QI + q16 * 1024 + (((hh * 8 + 4 * ks + kg) ^ q16) << 4));
;                         a = __builtin_amdgcn_mfma_f32_16x16x32_bf16(kf[kb][ks], qv, a, 0, 0, 0);
;                     }
;                     const float wh = wl[hh * 16];
; #pragma unroll
;                     for (int i = 0; i < 4; ++i) s[i] += wh * fmaxf(a[i], 0.f);
;                 }
;                 u32x4 kk; kk.x = fkey(s[0]); kk.y = fkey(s[1]); kk.z = fkey(s[2]); kk.w = fkey(s[3]);
;                 sc[j][2 * kh + kb] = kk;
; #pragma unroll
;                 for (int i = 0; i < 4; ++i) SEL_HADD((kk[i] >> 24) * 16 + q16);
;                 __builtin_amdgcn_sched_barrier(0);
.Lp0_nopf_4:
	s_waitcnt lgkmcnt(1)
	v_mfma_f32_16x16x32_bf16 v[246:249], v[42:45], v[230:233], 0
	v_mfma_f32_16x16x32_bf16 v[250:253], v[50:53], v[230:233], 0
	v_mfma_f32_16x16x32_bf16 v[246:249], v[46:49], v[234:237], v[246:249]
	v_mfma_f32_16x16x32_bf16 v[250:253], v[2:5], v[234:237], v[250:253]
	ds_read_b128 v[238:241], v184
	ds_read_b128 v[242:245], v185
	ds_read_b32 v7, v137 offset:384
	s_waitcnt lgkmcnt(1)
	v_mfma_f32_16x16x32_bf16 v[206:209], v[42:45], v[238:241], 0
	v_mfma_f32_16x16x32_bf16 v[210:213], v[50:53], v[238:241], 0
	v_mfma_f32_16x16x32_bf16 v[206:209], v[46:49], v[242:245], v[206:209]
	v_mfma_f32_16x16x32_bf16 v[210:213], v[2:5], v[242:245], v[210:213]
	ds_read_b128 v[230:233], v179
	ds_read_b128 v[234:237], v180
	ds_read_b32 v217, v137 offset:448
	v_max_f32_e32 v9, 0, v246
	v_max_f32_e32 v200, 0, v247
	v_max_f32_e32 v201, 0, v248
	v_max_f32_e32 v216, 0, v249
	v_fma_f32 v134, v6, v9, 0
	v_fma_f32 v133, v6, v200, 0
	v_fma_f32 v136, v6, v201, 0
	v_fma_f32 v135, v6, v216, 0
	v_max_f32_e32 v9, 0, v250
	v_max_f32_e32 v200, 0, v251
	v_max_f32_e32 v201, 0, v252
	v_max_f32_e32 v216, 0, v253
	v_fma_f32 v139, v6, v9, 0
	v_fma_f32 v138, v6, v200, 0
	v_fma_f32 v141, v6, v201, 0
	v_fma_f32 v140, v6, v216, 0
	s_waitcnt lgkmcnt(1)
	v_mfma_f32_16x16x32_bf16 v[246:249], v[42:45], v[230:233], 0
	v_mfma_f32_16x16x32_bf16 v[250:253], v[50:53], v[230:233], 0
	v_mfma_f32_16x16x32_bf16 v[246:249], v[46:49], v[234:237], v[246:249]
	v_mfma_f32_16x16x32_bf16 v[250:253], v[2:5], v[234:237], v[250:253]
	ds_read_b128 v[238:241], v176
	ds_read_b128 v[242:245], v159
	ds_read_b32 v6, v137 offset:512
	v_max_f32_e32 v9, 0, v206
	v_max_f32_e32 v200, 0, v207
	v_max_f32_e32 v201, 0, v208
	v_max_f32_e32 v216, 0, v209
	v_fmac_f32_e32 v134, v7, v9
	v_fmac_f32_e32 v133, v7, v200
	v_fmac_f32_e32 v136, v7, v201
	v_fmac_f32_e32 v135, v7, v216
	v_max_f32_e32 v9, 0, v210
	v_max_f32_e32 v200, 0, v211
	v_max_f32_e32 v201, 0, v212
	v_max_f32_e32 v216, 0, v213
	v_fmac_f32_e32 v139, v7, v9
	v_fmac_f32_e32 v138, v7, v200
	v_fmac_f32_e32 v141, v7, v201
	v_fmac_f32_e32 v140, v7, v216
	s_waitcnt lgkmcnt(1)
	v_mfma_f32_16x16x32_bf16 v[206:209], v[42:45], v[238:241], 0
	v_mfma_f32_16x16x32_bf16 v[210:213], v[50:53], v[238:241], 0
	v_mfma_f32_16x16x32_bf16 v[206:209], v[46:49], v[242:245], v[206:209]
	v_mfma_f32_16x16x32_bf16 v[210:213], v[2:5], v[242:245], v[210:213]
	ds_read_b128 v[230:233], v158
	ds_read_b128 v[234:237], v157
	ds_read_b32 v7, v137 offset:576
	v_max_f32_e32 v9, 0, v246
	v_max_f32_e32 v200, 0, v247
	v_max_f32_e32 v201, 0, v248
	v_max_f32_e32 v216, 0, v249
	v_fmac_f32_e32 v134, v217, v9
	v_fmac_f32_e32 v133, v217, v200
	v_fmac_f32_e32 v136, v217, v201
	v_fmac_f32_e32 v135, v217, v216
	v_max_f32_e32 v9, 0, v250
	v_max_f32_e32 v200, 0, v251
	v_max_f32_e32 v201, 0, v252
	v_max_f32_e32 v216, 0, v253
	v_fmac_f32_e32 v139, v217, v9
	v_fmac_f32_e32 v138, v217, v200
	v_fmac_f32_e32 v141, v217, v201
	v_fmac_f32_e32 v140, v217, v216
	s_waitcnt lgkmcnt(1)
	v_mfma_f32_16x16x32_bf16 v[246:249], v[42:45], v[230:233], 0
	v_mfma_f32_16x16x32_bf16 v[250:253], v[50:53], v[230:233], 0
	v_mfma_f32_16x16x32_bf16 v[246:249], v[46:49], v[234:237], v[246:249]
	v_mfma_f32_16x16x32_bf16 v[250:253], v[2:5], v[234:237], v[250:253]
	ds_read_b128 v[238:241], v156
	ds_read_b128 v[242:245], v155
	ds_read_b32 v217, v137 offset:640
	v_max_f32_e32 v9, 0, v206
	v_max_f32_e32 v200, 0, v207
	v_max_f32_e32 v201, 0, v208
	v_max_f32_e32 v216, 0, v209
	v_fmac_f32_e32 v134, v6, v9
	v_fmac_f32_e32 v133, v6, v200
	v_fmac_f32_e32 v136, v6, v201
	v_fmac_f32_e32 v135, v6, v216
	v_max_f32_e32 v9, 0, v210
	v_max_f32_e32 v200, 0, v211
	v_max_f32_e32 v201, 0, v212
	v_max_f32_e32 v216, 0, v213
	v_fmac_f32_e32 v139, v6, v9
	v_fmac_f32_e32 v138, v6, v200
	v_fmac_f32_e32 v141, v6, v201
	v_fmac_f32_e32 v140, v6, v216
	s_waitcnt lgkmcnt(1)
	v_mfma_f32_16x16x32_bf16 v[206:209], v[42:45], v[238:241], 0
	v_mfma_f32_16x16x32_bf16 v[210:213], v[50:53], v[238:241], 0
	v_mfma_f32_16x16x32_bf16 v[206:209], v[46:49], v[242:245], v[206:209]
	v_mfma_f32_16x16x32_bf16 v[210:213], v[2:5], v[242:245], v[210:213]
	ds_read_b128 v[230:233], v154
	ds_read_b128 v[234:237], v153
	ds_read_b32 v6, v137 offset:704
	v_max_f32_e32 v9, 0, v246
	v_max_f32_e32 v200, 0, v247
	v_max_f32_e32 v201, 0, v248
	v_max_f32_e32 v216, 0, v249
	v_fmac_f32_e32 v134, v7, v9
	v_fmac_f32_e32 v133, v7, v200
	v_fmac_f32_e32 v136, v7, v201
	v_fmac_f32_e32 v135, v7, v216
	v_max_f32_e32 v9, 0, v250
	v_max_f32_e32 v200, 0, v251
	v_max_f32_e32 v201, 0, v252
	v_max_f32_e32 v216, 0, v253
	v_fmac_f32_e32 v139, v7, v9
	v_fmac_f32_e32 v138, v7, v200
	v_fmac_f32_e32 v141, v7, v201
	v_fmac_f32_e32 v140, v7, v216
	s_waitcnt lgkmcnt(1)
	v_mfma_f32_16x16x32_bf16 v[246:249], v[42:45], v[230:233], 0
	v_mfma_f32_16x16x32_bf16 v[250:253], v[50:53], v[230:233], 0
	v_mfma_f32_16x16x32_bf16 v[246:249], v[46:49], v[234:237], v[246:249]
	v_mfma_f32_16x16x32_bf16 v[250:253], v[2:5], v[234:237], v[250:253]
	ds_read_b128 v[238:241], v152
	ds_read_b128 v[242:245], v151
	ds_read_b32 v7, v137 offset:768
	v_max_f32_e32 v9, 0, v206
	v_max_f32_e32 v200, 0, v207
	v_max_f32_e32 v201, 0, v208
	v_max_f32_e32 v216, 0, v209
	v_fmac_f32_e32 v134, v217, v9
	v_fmac_f32_e32 v133, v217, v200
	v_fmac_f32_e32 v136, v217, v201
	v_fmac_f32_e32 v135, v217, v216
	v_max_f32_e32 v9, 0, v210
	v_max_f32_e32 v200, 0, v211
	v_max_f32_e32 v201, 0, v212
	v_max_f32_e32 v216, 0, v213
	v_fmac_f32_e32 v139, v217, v9
	v_fmac_f32_e32 v138, v217, v200
	v_fmac_f32_e32 v141, v217, v201
	v_fmac_f32_e32 v140, v217, v216
	s_waitcnt lgkmcnt(1)
; #define LAS __attribute__((address_space(3)))
; __device__ __forceinline__ unsigned fkey(float f) { const unsigned u = __float_as_uint(f); return (u & 0x80000000u) ? ~u : (u | 0x80000000u); }
; #define SEL_HADD(idx_) __hip_atomic_fetch_add(&hist[(idx_)], 1u, __ATOMIC_RELAXED, __HIP_MEMORY_SCOPE_WORKGROUP)
; __device__ __forceinline__ void sel_unit(LAS char* lds, int b, int u, const bf16_t* QI, const bf16_t* KIDX, const float* WIDX, unsigned long long* MASK) {
;     ...
;     for (int j = 0; j < 8; ++j) {
;         if (j < nj) {
;             int t = wid + 8 * j; asm volatile("" : "+s"(t));
; #pragma unroll
;             for (int kh = 0; kh < 2; ++kh) {
;             bf16x8 kf[2][2];
; #pragma unroll
;             for (int kb = 0; kb < 2; ++kb)
; #pragma unroll
;                 for (int ks = 0; ks < 2; ++ks) kf[kb][ks] = *(const bf16x8*)(KIDX + (rowbase + 64 * t + 32 * kh + 16 * kb + q16) * 64 + 32 * ks + 8 * kg);
; #pragma unroll
;             for (int kb = 0; kb < 2; ++kb) {
;                 f32x4 s = (f32x4){0.f, 0.f, 0.f, 0.f};
; #pragma unroll
;                 for (int hh = 0; hh < 8; ++hh) {
;                     f32x4 a = (f32x4){0.f, 0.f, 0.f, 0.f};
; #pragma unroll
;                     for (int ks = 0; ks < 2; ++ks) {
;                         const bf16x8 qv = *(const LAS bf16x8*)(lds + L_QI + q16 * 1024 + (((hh * 8 + 4 * ks + kg) ^ q16) << 4));
;                         a = __builtin_amdgcn_mfma_f32_16x16x32_bf16(kf[kb][ks], qv, a, 0, 0, 0);
;                     }
;                     const float wh = wl[hh * 16];
; #pragma unroll
;                     for (int i = 0; i < 4; ++i) s[i] += wh * fmaxf(a[i], 0.f);
;                 }
;                 u32x4 kk; kk.x = fkey(s[0]); kk.y = fkey(s[1]); kk.z = fkey(s[2]); kk.w = fkey(s[3]);
;                 sc[j][2 * kh + kb] = kk;
; #pragma unroll
;                 for (int i = 0; i < 4; ++i) SEL_HADD((kk[i] >> 24) * 16 + q16);
;                 __builtin_amdgcn_sched_barrier(0);
	v_mfma_f32_16x16x32_bf16 v[206:209], v[42:45], v[238:241], 0
	v_mfma_f32_16x16x32_bf16 v[210:213], v[50:53], v[238:241], 0
	v_mfma_f32_16x16x32_bf16 v[206:209], v[46:49], v[242:245], v[206:209]
	v_mfma_f32_16x16x32_bf16 v[210:213], v[2:5], v[242:245], v[210:213]
	v_max_f32_e32 v9, 0, v246
	v_max_f32_e32 v200, 0, v247
	v_max_f32_e32 v201, 0, v248
	v_max_f32_e32 v216, 0, v249
	v_fmac_f32_e32 v134, v6, v9
	v_fmac_f32_e32 v133, v6, v200
	v_fmac_f32_e32 v136, v6, v201
	v_fmac_f32_e32 v135, v6, v216
	v_max_f32_e32 v9, 0, v250
	v_max_f32_e32 v200, 0, v251
	v_max_f32_e32 v201, 0, v252
	v_max_f32_e32 v216, 0, v253
	v_fmac_f32_e32 v139, v6, v9
	v_fmac_f32_e32 v138, v6, v200
	v_fmac_f32_e32 v141, v6, v201
	v_fmac_f32_e32 v140, v6, v216
	s_waitcnt lgkmcnt(0)
	v_max_f32_e32 v9, 0, v206
	v_max_f32_e32 v200, 0, v207
	v_max_f32_e32 v201, 0, v208
	v_max_f32_e32 v216, 0, v209
	v_fmac_f32_e32 v134, v7, v9
	v_fmac_f32_e32 v133, v7, v200
	v_fmac_f32_e32 v136, v7, v201
	v_fmac_f32_e32 v135, v7, v216
	v_max_f32_e32 v9, 0, v210
	v_max_f32_e32 v200, 0, v211
	v_max_f32_e32 v201, 0, v212
	v_max_f32_e32 v216, 0, v213
	v_fmac_f32_e32 v139, v7, v9
	v_fmac_f32_e32 v138, v7, v200
	v_fmac_f32_e32 v141, v7, v201
	v_fmac_f32_e32 v140, v7, v216
	v_ashrrev_i32_e32 v9, 31, v134
	v_bitop3_b32 v134, v9, v134, v8 bitop3:0x36
	v_ashrrev_i32_e32 v200, 31, v133
	v_bitop3_b32 v133, v200, v133, v8 bitop3:0x36
	v_ashrrev_i32_e32 v201, 31, v136
	v_bitop3_b32 v136, v201, v136, v8 bitop3:0x36
	v_ashrrev_i32_e32 v216, 31, v135
	v_bitop3_b32 v135, v216, v135, v8 bitop3:0x36
	v_ashrrev_i32_e32 v9, 31, v139
	v_bitop3_b32 v139, v9, v139, v8 bitop3:0x36
	v_ashrrev_i32_e32 v200, 31, v138
	v_bitop3_b32 v138, v200, v138, v8 bitop3:0x36
	v_ashrrev_i32_e32 v201, 31, v141
	v_bitop3_b32 v141, v201, v141, v8 bitop3:0x36
	v_ashrrev_i32_e32 v216, 31, v140
	v_bitop3_b32 v140, v216, v140, v8 bitop3:0x36
	v_lshrrev_b32_e32 v9, 24, v134
	v_lshl_add_u32 v9, v9, 6, v0
	ds_add_u32 v9, v205 offset:16384
	v_lshrrev_b32_e32 v200, 24, v133
	v_lshl_add_u32 v200, v200, 6, v0
	ds_add_u32 v200, v205 offset:16384
	v_lshrrev_b32_e32 v201, 24, v136
	v_lshl_add_u32 v201, v201, 6, v0
	ds_add_u32 v201, v205 offset:16384
	v_lshrrev_b32_e32 v216, 24, v135
	v_lshl_add_u32 v216, v216, 6, v0
	ds_add_u32 v216, v205 offset:16384
	v_lshrrev_b32_e32 v9, 24, v139
	v_lshl_add_u32 v9, v9, 6, v0
	ds_add_u32 v9, v205 offset:16384
	v_lshrrev_b32_e32 v200, 24, v138
	v_lshl_add_u32 v200, v200, 6, v0
	ds_add_u32 v200, v205 offset:16384
	v_lshrrev_b32_e32 v201, 24, v141
	v_lshl_add_u32 v201, v201, 6, v0
	ds_add_u32 v201, v205 offset:16384
	v_lshrrev_b32_e32 v216, 24, v140
	v_lshl_add_u32 v216, v216, 6, v0
	ds_add_u32 v216, v205 offset:16384
.LBB0_666:
	s_cmp_gt_i32 s4, 5
	s_cselect_b64 s[48:49], -1, 0
	s_cmp_lt_i32 s4, 6
	s_cbranch_scc1 .LBB0_668
	ds_read_b128 v[230:233], v182
	ds_read_b128 v[234:237], v183
	ds_read_b32 v6, v137 offset:320
	s_waitcnt vmcnt(0)
	v_add_co_u32_e32 v22, vcc, s96, v22
	s_nop 1
	v_addc_co_u32_e32 v23, vcc, 0, v23, vcc
	global_load_dwordx4 v[42:45], v[22:23], off
	global_load_dwordx4 v[46:49], v[22:23], off offset:64
	global_load_dwordx4 v[50:53], v[22:23], off offset:2048
	global_load_dwordx4 v[2:5], v[22:23], off offset:2112
	s_waitcnt lgkmcnt(1)
	v_mfma_f32_16x16x32_bf16 v[246:249], v[26:29], v[230:233], 0
	v_mfma_f32_16x16x32_bf16 v[250:253], v[34:37], v[230:233], 0
	v_mfma_f32_16x16x32_bf16 v[246:249], v[30:33], v[234:237], v[246:249]
	v_mfma_f32_16x16x32_bf16 v[250:253], v[38:41], v[234:237], v[250:253]
	ds_read_b128 v[238:241], v184
	ds_read_b128 v[242:245], v185
	ds_read_b32 v7, v137 offset:384
	s_waitcnt lgkmcnt(1)
	v_mfma_f32_16x16x32_bf16 v[206:209], v[26:29], v[238:241], 0
	v_mfma_f32_16x16x32_bf16 v[210:213], v[34:37], v[238:241], 0
	v_mfma_f32_16x16x32_bf16 v[206:209], v[30:33], v[242:245], v[206:209]
	v_mfma_f32_16x16x32_bf16 v[210:213], v[38:41], v[242:245], v[210:213]
	ds_read_b128 v[230:233], v179
	ds_read_b128 v[234:237], v180
	ds_read_b32 v217, v137 offset:448
	v_max_f32_e32 v9, 0, v246
	v_max_f32_e32 v200, 0, v247
	v_max_f32_e32 v201, 0, v248
	v_max_f32_e32 v216, 0, v249
	v_fma_f32 v143, v6, v9, 0
	v_fma_f32 v142, v6, v200, 0
	v_fma_f32 v145, v6, v201, 0
	v_fma_f32 v144, v6, v216, 0
	v_max_f32_e32 v9, 0, v250
	v_max_f32_e32 v200, 0, v251
	v_max_f32_e32 v201, 0, v252
	v_max_f32_e32 v216, 0, v253
	v_fma_f32 v147, v6, v9, 0
	v_fma_f32 v146, v6, v200, 0
	v_fma_f32 v149, v6, v201, 0
	v_fma_f32 v148, v6, v216, 0
	s_waitcnt lgkmcnt(1)
	v_mfma_f32_16x16x32_bf16 v[246:249], v[26:29], v[230:233], 0
	v_mfma_f32_16x16x32_bf16 v[250:253], v[34:37], v[230:233], 0
	v_mfma_f32_16x16x32_bf16 v[246:249], v[30:33], v[234:237], v[246:249]
	v_mfma_f32_16x16x32_bf16 v[250:253], v[38:41], v[234:237], v[250:253]
	ds_read_b128 v[238:241], v176
	ds_read_b128 v[242:245], v159
	ds_read_b32 v6, v137 offset:512
	v_max_f32_e32 v9, 0, v206
	v_max_f32_e32 v200, 0, v207
	v_max_f32_e32 v201, 0, v208
	v_max_f32_e32 v216, 0, v209
	v_fmac_f32_e32 v143, v7, v9
	v_fmac_f32_e32 v142, v7, v200
	v_fmac_f32_e32 v145, v7, v201
	v_fmac_f32_e32 v144, v7, v216
	v_max_f32_e32 v9, 0, v210
	v_max_f32_e32 v200, 0, v211
	v_max_f32_e32 v201, 0, v212
	v_max_f32_e32 v216, 0, v213
	v_fmac_f32_e32 v147, v7, v9
	v_fmac_f32_e32 v146, v7, v200
	v_fmac_f32_e32 v149, v7, v201
	v_fmac_f32_e32 v148, v7, v216
	s_waitcnt lgkmcnt(1)
; #define LAS __attribute__((address_space(3)))
; __device__ __forceinline__ unsigned fkey(float f) { const unsigned u = __float_as_uint(f); return (u & 0x80000000u) ? ~u : (u | 0x80000000u); }
; #define SEL_HADD(idx_) __hip_atomic_fetch_add(&hist[(idx_)], 1u, __ATOMIC_RELAXED, __HIP_MEMORY_SCOPE_WORKGROUP)
; __device__ __forceinline__ void sel_unit(LAS char* lds, int b, int u, const bf16_t* QI, const bf16_t* KIDX, const float* WIDX, unsigned long long* MASK) {
;     ...
;     for (int j = 0; j < 8; ++j) {
;         if (j < nj) {
;             int t = wid + 8 * j; asm volatile("" : "+s"(t));
; #pragma unroll
;             for (int kh = 0; kh < 2; ++kh) {
;             bf16x8 kf[2][2];
; #pragma unroll
;             for (int kb = 0; kb < 2; ++kb)
; #pragma unroll
;                 for (int ks = 0; ks < 2; ++ks) kf[kb][ks] = *(const bf16x8*)(KIDX + (rowbase + 64 * t + 32 * kh + 16 * kb + q16) * 64 + 32 * ks + 8 * kg);
; #pragma unroll
;             for (int kb = 0; kb < 2; ++kb) {
;                 f32x4 s = (f32x4){0.f, 0.f, 0.f, 0.f};
; #pragma unroll
;                 for (int hh = 0; hh < 8; ++hh) {
;                     f32x4 a = (f32x4){0.f, 0.f, 0.f, 0.f};
; #pragma unroll
;                     for (int ks = 0; ks < 2; ++ks) {
;                         const bf16x8 qv = *(const LAS bf16x8*)(lds + L_QI + q16 * 1024 + (((hh * 8 + 4 * ks + kg) ^ q16) << 4));
;                         a = __builtin_amdgcn_mfma_f32_16x16x32_bf16(kf[kb][ks], qv, a, 0, 0, 0);
;                     }
;                     const float wh = wl[hh * 16];
; #pragma unroll
;                     for (int i = 0; i < 4; ++i) s[i] += wh * fmaxf(a[i], 0.f);
;                 }
;                 u32x4 kk; kk.x = fkey(s[0]); kk.y = fkey(s[1]); kk.z = fkey(s[2]); kk.w = fkey(s[3]);
;                 sc[j][2 * kh + kb] = kk;
; #pragma unroll
;                 for (int i = 0; i < 4; ++i) SEL_HADD((kk[i] >> 24) * 16 + q16);
;                 __builtin_amdgcn_sched_barrier(0);
	v_mfma_f32_16x16x32_bf16 v[206:209], v[26:29], v[238:241], 0
	v_mfma_f32_16x16x32_bf16 v[210:213], v[34:37], v[238:241], 0
	v_mfma_f32_16x16x32_bf16 v[206:209], v[30:33], v[242:245], v[206:209]
	v_mfma_f32_16x16x32_bf16 v[210:213], v[38:41], v[242:245], v[210:213]
	ds_read_b128 v[230:233], v158
	ds_read_b128 v[234:237], v157
	ds_read_b32 v7, v137 offset:576
	v_max_f32_e32 v9, 0, v246
	v_max_f32_e32 v200, 0, v247
	v_max_f32_e32 v201, 0, v248
	v_max_f32_e32 v216, 0, v249
	v_fmac_f32_e32 v143, v217, v9
	v_fmac_f32_e32 v142, v217, v200
	v_fmac_f32_e32 v145, v217, v201
	v_fmac_f32_e32 v144, v217, v216
	v_max_f32_e32 v9, 0, v250
	v_max_f32_e32 v200, 0, v251
	v_max_f32_e32 v201, 0, v252
	v_max_f32_e32 v216, 0, v253
	v_fmac_f32_e32 v147, v217, v9
	v_fmac_f32_e32 v146, v217, v200
	v_fmac_f32_e32 v149, v217, v201
	v_fmac_f32_e32 v148, v217, v216
	s_waitcnt lgkmcnt(1)
	v_mfma_f32_16x16x32_bf16 v[246:249], v[26:29], v[230:233], 0
	v_mfma_f32_16x16x32_bf16 v[250:253], v[34:37], v[230:233], 0
	v_mfma_f32_16x16x32_bf16 v[246:249], v[30:33], v[234:237], v[246:249]
	v_mfma_f32_16x16x32_bf16 v[250:253], v[38:41], v[234:237], v[250:253]
	ds_read_b128 v[238:241], v156
	ds_read_b128 v[242:245], v155
	ds_read_b32 v217, v137 offset:640
	v_max_f32_e32 v9, 0, v206
	v_max_f32_e32 v200, 0, v207
	v_max_f32_e32 v201, 0, v208
	v_max_f32_e32 v216, 0, v209
	v_fmac_f32_e32 v143, v6, v9
	v_fmac_f32_e32 v142, v6, v200
	v_fmac_f32_e32 v145, v6, v201
	v_fmac_f32_e32 v144, v6, v216
	v_max_f32_e32 v9, 0, v210
	v_max_f32_e32 v200, 0, v211
	v_max_f32_e32 v201, 0, v212
	v_max_f32_e32 v216, 0, v213
	v_fmac_f32_e32 v147, v6, v9
	v_fmac_f32_e32 v146, v6, v200
	v_fmac_f32_e32 v149, v6, v201
	v_fmac_f32_e32 v148, v6, v216
	s_waitcnt lgkmcnt(1)
	v_mfma_f32_16x16x32_bf16 v[206:209], v[26:29], v[238:241], 0
	v_mfma_f32_16x16x32_bf16 v[210:213], v[34:37], v[238:241], 0
	v_mfma_f32_16x16x32_bf16 v[206:209], v[30:33], v[242:245], v[206:209]
	v_mfma_f32_16x16x32_bf16 v[210:213], v[38:41], v[242:245], v[210:213]
	ds_read_b128 v[230:233], v154
	ds_read_b128 v[234:237], v153
	ds_read_b32 v6, v137 offset:704
	v_max_f32_e32 v9, 0, v246
	v_max_f32_e32 v200, 0, v247
	v_max_f32_e32 v201, 0, v248
	v_max_f32_e32 v216, 0, v249
	v_fmac_f32_e32 v143, v7, v9
	v_fmac_f32_e32 v142, v7, v200
	v_fmac_f32_e32 v145, v7, v201
	v_fmac_f32_e32 v144, v7, v216
	v_max_f32_e32 v9, 0, v250
	v_max_f32_e32 v200, 0, v251
	v_max_f32_e32 v201, 0, v252
	v_max_f32_e32 v216, 0, v253
	v_fmac_f32_e32 v147, v7, v9
	v_fmac_f32_e32 v146, v7, v200
	v_fmac_f32_e32 v149, v7, v201
	v_fmac_f32_e32 v148, v7, v216
	s_waitcnt lgkmcnt(1)
	v_mfma_f32_16x16x32_bf16 v[246:249], v[26:29], v[230:233], 0
	v_mfma_f32_16x16x32_bf16 v[250:253], v[34:37], v[230:233], 0
	v_mfma_f32_16x16x32_bf16 v[246:249], v[30:33], v[234:237], v[246:249]
	v_mfma_f32_16x16x32_bf16 v[250:253], v[38:41], v[234:237], v[250:253]
	ds_read_b128 v[238:241], v152
	ds_read_b128 v[242:245], v151
	ds_read_b32 v7, v137 offset:768
	v_max_f32_e32 v9, 0, v206
	v_max_f32_e32 v200, 0, v207
	v_max_f32_e32 v201, 0, v208
	v_max_f32_e32 v216, 0, v209
	v_fmac_f32_e32 v143, v217, v9
	v_fmac_f32_e32 v142, v217, v200
	v_fmac_f32_e32 v145, v217, v201
	v_fmac_f32_e32 v144, v217, v216
	v_max_f32_e32 v9, 0, v210
	v_max_f32_e32 v200, 0, v211
	v_max_f32_e32 v201, 0, v212
	v_max_f32_e32 v216, 0, v213
	v_fmac_f32_e32 v147, v217, v9
	v_fmac_f32_e32 v146, v217, v200
	v_fmac_f32_e32 v149, v217, v201
	v_fmac_f32_e32 v148, v217, v216
	s_waitcnt lgkmcnt(1)
	v_mfma_f32_16x16x32_bf16 v[206:209], v[26:29], v[238:241], 0
	v_mfma_f32_16x16x32_bf16 v[210:213], v[34:37], v[238:241], 0
	v_mfma_f32_16x16x32_bf16 v[206:209], v[30:33], v[242:245], v[206:209]
	v_mfma_f32_16x16x32_bf16 v[210:213], v[38:41], v[242:245], v[210:213]
	v_max_f32_e32 v9, 0, v246
	v_max_f32_e32 v200, 0, v247
	v_max_f32_e32 v201, 0, v248
	v_max_f32_e32 v216, 0, v249
	v_fmac_f32_e32 v143, v6, v9
	v_fmac_f32_e32 v142, v6, v200
	v_fmac_f32_e32 v145, v6, v201
	v_fmac_f32_e32 v144, v6, v216
	v_max_f32_e32 v9, 0, v250
	v_max_f32_e32 v200, 0, v251
	v_max_f32_e32 v201, 0, v252
	v_max_f32_e32 v216, 0, v253
	v_fmac_f32_e32 v147, v6, v9
	v_fmac_f32_e32 v146, v6, v200
	v_fmac_f32_e32 v149, v6, v201
	v_fmac_f32_e32 v148, v6, v216
	s_waitcnt lgkmcnt(0)
	v_max_f32_e32 v9, 0, v206
	v_max_f32_e32 v200, 0, v207
	v_max_f32_e32 v201, 0, v208
	v_max_f32_e32 v216, 0, v209
	v_fmac_f32_e32 v143, v7, v9
	v_fmac_f32_e32 v142, v7, v200
	v_fmac_f32_e32 v145, v7, v201
	v_fmac_f32_e32 v144, v7, v216
	v_max_f32_e32 v9, 0, v210
	v_max_f32_e32 v200, 0, v211
	v_max_f32_e32 v201, 0, v212
	v_max_f32_e32 v216, 0, v213
	v_fmac_f32_e32 v147, v7, v9
	v_fmac_f32_e32 v146, v7, v200
	v_fmac_f32_e32 v149, v7, v201
	v_fmac_f32_e32 v148, v7, v216
	v_ashrrev_i32_e32 v9, 31, v143
	v_bitop3_b32 v143, v9, v143, v8 bitop3:0x36
	v_ashrrev_i32_e32 v200, 31, v142
	v_bitop3_b32 v142, v200, v142, v8 bitop3:0x36
	v_ashrrev_i32_e32 v201, 31, v145
	v_bitop3_b32 v145, v201, v145, v8 bitop3:0x36
	v_ashrrev_i32_e32 v216, 31, v144
	v_bitop3_b32 v144, v216, v144, v8 bitop3:0x36
	v_ashrrev_i32_e32 v9, 31, v147
	v_bitop3_b32 v147, v9, v147, v8 bitop3:0x36
	v_ashrrev_i32_e32 v200, 31, v146
	v_bitop3_b32 v146, v200, v146, v8 bitop3:0x36
	v_ashrrev_i32_e32 v201, 31, v149
	v_bitop3_b32 v149, v201, v149, v8 bitop3:0x36
	v_ashrrev_i32_e32 v216, 31, v148
	v_bitop3_b32 v148, v216, v148, v8 bitop3:0x36
	v_lshrrev_b32_e32 v9, 24, v143
	v_lshl_add_u32 v9, v9, 6, v0
	ds_add_u32 v9, v205 offset:16384
	v_lshrrev_b32_e32 v200, 24, v142
	v_lshl_add_u32 v200, v200, 6, v0
	ds_add_u32 v200, v205 offset:16384
	v_lshrrev_b32_e32 v201, 24, v145
	v_lshl_add_u32 v201, v201, 6, v0
	ds_add_u32 v201, v205 offset:16384
	v_lshrrev_b32_e32 v216, 24, v144
	v_lshl_add_u32 v216, v216, 6, v0
	ds_add_u32 v216, v205 offset:16384
	v_lshrrev_b32_e32 v9, 24, v147
	v_lshl_add_u32 v9, v9, 6, v0
	ds_add_u32 v9, v205 offset:16384
	v_lshrrev_b32_e32 v200, 24, v146
	v_lshl_add_u32 v200, v200, 6, v0
	ds_add_u32 v200, v205 offset:16384
	v_lshrrev_b32_e32 v201, 24, v149
	v_lshl_add_u32 v201, v201, 6, v0
	ds_add_u32 v201, v205 offset:16384
	v_lshrrev_b32_e32 v216, 24, v148
	v_lshl_add_u32 v216, v216, 6, v0
	ds_add_u32 v216, v205 offset:16384
	ds_read_b128 v[230:233], v182
	ds_read_b128 v[234:237], v183
	ds_read_b32 v6, v137 offset:320
	s_waitcnt vmcnt(0)
	s_cmp_lt_i32 s4, 7
	s_cbranch_scc1 .Lp0_nopf_5
	v_add_co_u32_e32 v22, vcc, 0xf000, v22
	s_nop 1
	v_addc_co_u32_e32 v23, vcc, 0, v23, vcc
	global_load_dwordx4 v[26:29], v[22:23], off
	global_load_dwordx4 v[30:33], v[22:23], off offset:64
	global_load_dwordx4 v[34:37], v[22:23], off offset:2048
	global_load_dwordx4 v[38:41], v[22:23], off offset:2112
; #define LAS __attribute__((address_space(3)))
; __device__ __forceinline__ unsigned fkey(float f) { const unsigned u = __float_as_uint(f); return (u & 0x80000000u) ? ~u : (u | 0x80000000u); }
; #define SEL_HADD(idx_) __hip_atomic_fetch_add(&hist[(idx_)], 1u, __ATOMIC_RELAXED, __HIP_MEMORY_SCOPE_WORKGROUP)
; __device__ __forceinline__ void sel_unit(LAS char* lds, int b, int u, const bf16_t* QI, const bf16_t* KIDX, const float* WIDX, unsigned long long* MASK) {
;     ...
;     for (int j = 0; j < 8; ++j) {
;         if (j < nj) {
;             int t = wid + 8 * j; asm volatile("" : "+s"(t));
; #pragma unroll
;             for (int kh = 0; kh < 2; ++kh) {
;             bf16x8 kf[2][2];
; #pragma unroll
;             for (int kb = 0; kb < 2; ++kb)
; #pragma unroll
;                 for (int ks = 0; ks < 2; ++ks) kf[kb][ks] = *(const bf16x8*)(KIDX + (rowbase + 64 * t + 32 * kh + 16 * kb + q16) * 64 + 32 * ks + 8 * kg);
; #pragma unroll
;             for (int kb = 0; kb < 2; ++kb) {
;                 f32x4 s = (f32x4){0.f, 0.f, 0.f, 0.f};
; #pragma unroll
;                 for (int hh = 0; hh < 8; ++hh) {
;                     f32x4 a = (f32x4){0.f, 0.f, 0.f, 0.f};
; #pragma unroll
;                     for (int ks = 0; ks < 2; ++ks) {
;                         const bf16x8 qv = *(const LAS bf16x8*)(lds + L_QI + q16 * 1024 + (((hh * 8 + 4 * ks + kg) ^ q16) << 4));
;                         a = __builtin_amdgcn_mfma_f32_16x16x32_bf16(kf[kb][ks], qv, a, 0, 0, 0);
;                     }
;                     const float wh = wl[hh * 16];
; #pragma unroll
;                     for (int i = 0; i < 4; ++i) s[i] += wh * fmaxf(a[i], 0.f);
;                 }
;                 u32x4 kk; kk.x = fkey(s[0]); kk.y = fkey(s[1]); kk.z = fkey(s[2]); kk.w = fkey(s[3]);
;                 sc[j][2 * kh + kb] = kk;
; #pragma unroll
;                 for (int i = 0; i < 4; ++i) SEL_HADD((kk[i] >> 24) * 16 + q16);
;                 __builtin_amdgcn_sched_barrier(0);
.Lp0_nopf_5:
	s_waitcnt lgkmcnt(1)
	v_mfma_f32_16x16x32_bf16 v[246:249], v[42:45], v[230:233], 0
	v_mfma_f32_16x16x32_bf16 v[250:253], v[50:53], v[230:233], 0
	v_mfma_f32_16x16x32_bf16 v[246:249], v[46:49], v[234:237], v[246:249]
	v_mfma_f32_16x16x32_bf16 v[250:253], v[2:5], v[234:237], v[250:253]
	ds_read_b128 v[238:241], v184
	ds_read_b128 v[242:245], v185
	ds_read_b32 v7, v137 offset:384
	s_waitcnt lgkmcnt(1)
	v_mfma_f32_16x16x32_bf16 v[206:209], v[42:45], v[238:241], 0
	v_mfma_f32_16x16x32_bf16 v[210:213], v[50:53], v[238:241], 0
	v_mfma_f32_16x16x32_bf16 v[206:209], v[46:49], v[242:245], v[206:209]
	v_mfma_f32_16x16x32_bf16 v[210:213], v[2:5], v[242:245], v[210:213]
	ds_read_b128 v[230:233], v179
	ds_read_b128 v[234:237], v180
	ds_read_b32 v217, v137 offset:448
	v_max_f32_e32 v9, 0, v246
	v_max_f32_e32 v200, 0, v247
	v_max_f32_e32 v201, 0, v248
	v_max_f32_e32 v216, 0, v249
	v_fma_f32 v178, v6, v9, 0
	v_fma_f32 v177, v6, v200, 0
	v_fma_f32 v186, v6, v201, 0
	v_fma_f32 v181, v6, v216, 0
	v_max_f32_e32 v9, 0, v250
	v_max_f32_e32 v200, 0, v251
	v_max_f32_e32 v201, 0, v252
	v_max_f32_e32 v216, 0, v253
	v_fma_f32 v188, v6, v9, 0
	v_fma_f32 v187, v6, v200, 0
	v_fma_f32 v190, v6, v201, 0
	v_fma_f32 v189, v6, v216, 0
	s_waitcnt lgkmcnt(1)
	v_mfma_f32_16x16x32_bf16 v[246:249], v[42:45], v[230:233], 0
	v_mfma_f32_16x16x32_bf16 v[250:253], v[50:53], v[230:233], 0
	v_mfma_f32_16x16x32_bf16 v[246:249], v[46:49], v[234:237], v[246:249]
	v_mfma_f32_16x16x32_bf16 v[250:253], v[2:5], v[234:237], v[250:253]
	ds_read_b128 v[238:241], v176
	ds_read_b128 v[242:245], v159
	ds_read_b32 v6, v137 offset:512
	v_max_f32_e32 v9, 0, v206
	v_max_f32_e32 v200, 0, v207
	v_max_f32_e32 v201, 0, v208
	v_max_f32_e32 v216, 0, v209
	v_fmac_f32_e32 v178, v7, v9
	v_fmac_f32_e32 v177, v7, v200
	v_fmac_f32_e32 v186, v7, v201
	v_fmac_f32_e32 v181, v7, v216
	v_max_f32_e32 v9, 0, v210
	v_max_f32_e32 v200, 0, v211
	v_max_f32_e32 v201, 0, v212
	v_max_f32_e32 v216, 0, v213
	v_fmac_f32_e32 v188, v7, v9
	v_fmac_f32_e32 v187, v7, v200
	v_fmac_f32_e32 v190, v7, v201
	v_fmac_f32_e32 v189, v7, v216
	s_waitcnt lgkmcnt(1)
	v_mfma_f32_16x16x32_bf16 v[206:209], v[42:45], v[238:241], 0
	v_mfma_f32_16x16x32_bf16 v[210:213], v[50:53], v[238:241], 0
	v_mfma_f32_16x16x32_bf16 v[206:209], v[46:49], v[242:245], v[206:209]
	v_mfma_f32_16x16x32_bf16 v[210:213], v[2:5], v[242:245], v[210:213]
	ds_read_b128 v[230:233], v158
	ds_read_b128 v[234:237], v157
	ds_read_b32 v7, v137 offset:576
	v_max_f32_e32 v9, 0, v246
	v_max_f32_e32 v200, 0, v247
	v_max_f32_e32 v201, 0, v248
	v_max_f32_e32 v216, 0, v249
	v_fmac_f32_e32 v178, v217, v9
	v_fmac_f32_e32 v177, v217, v200
	v_fmac_f32_e32 v186, v217, v201
	v_fmac_f32_e32 v181, v217, v216
	v_max_f32_e32 v9, 0, v250
	v_max_f32_e32 v200, 0, v251
	v_max_f32_e32 v201, 0, v252
	v_max_f32_e32 v216, 0, v253
	v_fmac_f32_e32 v188, v217, v9
	v_fmac_f32_e32 v187, v217, v200
	v_fmac_f32_e32 v190, v217, v201
	v_fmac_f32_e32 v189, v217, v216
	s_waitcnt lgkmcnt(1)
	v_mfma_f32_16x16x32_bf16 v[246:249], v[42:45], v[230:233], 0
	v_mfma_f32_16x16x32_bf16 v[250:253], v[50:53], v[230:233], 0
	v_mfma_f32_16x16x32_bf16 v[246:249], v[46:49], v[234:237], v[246:249]
	v_mfma_f32_16x16x32_bf16 v[250:253], v[2:5], v[234:237], v[250:253]
	ds_read_b128 v[238:241], v156
	ds_read_b128 v[242:245], v155
	ds_read_b32 v217, v137 offset:640
	v_max_f32_e32 v9, 0, v206
	v_max_f32_e32 v200, 0, v207
	v_max_f32_e32 v201, 0, v208
	v_max_f32_e32 v216, 0, v209
	v_fmac_f32_e32 v178, v6, v9
	v_fmac_f32_e32 v177, v6, v200
	v_fmac_f32_e32 v186, v6, v201
	v_fmac_f32_e32 v181, v6, v216
	v_max_f32_e32 v9, 0, v210
	v_max_f32_e32 v200, 0, v211
	v_max_f32_e32 v201, 0, v212
	v_max_f32_e32 v216, 0, v213
	v_fmac_f32_e32 v188, v6, v9
	v_fmac_f32_e32 v187, v6, v200
	v_fmac_f32_e32 v190, v6, v201
	v_fmac_f32_e32 v189, v6, v216
	s_waitcnt lgkmcnt(1)
	v_mfma_f32_16x16x32_bf16 v[206:209], v[42:45], v[238:241], 0
	v_mfma_f32_16x16x32_bf16 v[210:213], v[50:53], v[238:241], 0
	v_mfma_f32_16x16x32_bf16 v[206:209], v[46:49], v[242:245], v[206:209]
	v_mfma_f32_16x16x32_bf16 v[210:213], v[2:5], v[242:245], v[210:213]
	ds_read_b128 v[230:233], v154
	ds_read_b128 v[234:237], v153
	ds_read_b32 v6, v137 offset:704
	v_max_f32_e32 v9, 0, v246
	v_max_f32_e32 v200, 0, v247
	v_max_f32_e32 v201, 0, v248
	v_max_f32_e32 v216, 0, v249
	v_fmac_f32_e32 v178, v7, v9
	v_fmac_f32_e32 v177, v7, v200
	v_fmac_f32_e32 v186, v7, v201
	v_fmac_f32_e32 v181, v7, v216
	v_max_f32_e32 v9, 0, v250
	v_max_f32_e32 v200, 0, v251
	v_max_f32_e32 v201, 0, v252
	v_max_f32_e32 v216, 0, v253
	v_fmac_f32_e32 v188, v7, v9
	v_fmac_f32_e32 v187, v7, v200
	v_fmac_f32_e32 v190, v7, v201
	v_fmac_f32_e32 v189, v7, v216
	s_waitcnt lgkmcnt(1)
	v_mfma_f32_16x16x32_bf16 v[246:249], v[42:45], v[230:233], 0
	v_mfma_f32_16x16x32_bf16 v[250:253], v[50:53], v[230:233], 0
	v_mfma_f32_16x16x32_bf16 v[246:249], v[46:49], v[234:237], v[246:249]
	v_mfma_f32_16x16x32_bf16 v[250:253], v[2:5], v[234:237], v[250:253]
	ds_read_b128 v[238:241], v152
	ds_read_b128 v[242:245], v151
	ds_read_b32 v7, v137 offset:768
	v_max_f32_e32 v9, 0, v206
	v_max_f32_e32 v200, 0, v207
	v_max_f32_e32 v201, 0, v208
	v_max_f32_e32 v216, 0, v209
	v_fmac_f32_e32 v178, v217, v9
	v_fmac_f32_e32 v177, v217, v200
	v_fmac_f32_e32 v186, v217, v201
	v_fmac_f32_e32 v181, v217, v216
	v_max_f32_e32 v9, 0, v210
	v_max_f32_e32 v200, 0, v211
	v_max_f32_e32 v201, 0, v212
	v_max_f32_e32 v216, 0, v213
	v_fmac_f32_e32 v188, v217, v9
	v_fmac_f32_e32 v187, v217, v200
	v_fmac_f32_e32 v190, v217, v201
	v_fmac_f32_e32 v189, v217, v216
	s_waitcnt lgkmcnt(1)
; #define LAS __attribute__((address_space(3)))
; __device__ __forceinline__ unsigned fkey(float f) { const unsigned u = __float_as_uint(f); return (u & 0x80000000u) ? ~u : (u | 0x80000000u); }
; #define SEL_HADD(idx_) __hip_atomic_fetch_add(&hist[(idx_)], 1u, __ATOMIC_RELAXED, __HIP_MEMORY_SCOPE_WORKGROUP)
; __device__ __forceinline__ void sel_unit(LAS char* lds, int b, int u, const bf16_t* QI, const bf16_t* KIDX, const float* WIDX, unsigned long long* MASK) {
;     ...
;     for (int j = 0; j < 8; ++j) {
;         if (j < nj) {
;             int t = wid + 8 * j; asm volatile("" : "+s"(t));
; #pragma unroll
;             for (int kh = 0; kh < 2; ++kh) {
;             bf16x8 kf[2][2];
; #pragma unroll
;             for (int kb = 0; kb < 2; ++kb)
; #pragma unroll
;                 for (int ks = 0; ks < 2; ++ks) kf[kb][ks] = *(const bf16x8*)(KIDX + (rowbase + 64 * t + 32 * kh + 16 * kb + q16) * 64 + 32 * ks + 8 * kg);
; #pragma unroll
;             for (int kb = 0; kb < 2; ++kb) {
;                 f32x4 s = (f32x4){0.f, 0.f, 0.f, 0.f};
; #pragma unroll
;                 for (int hh = 0; hh < 8; ++hh) {
;                     f32x4 a = (f32x4){0.f, 0.f, 0.f, 0.f};
; #pragma unroll
;                     for (int ks = 0; ks < 2; ++ks) {
;                         const bf16x8 qv = *(const LAS bf16x8*)(lds + L_QI + q16 * 1024 + (((hh * 8 + 4 * ks + kg) ^ q16) << 4));
;                         a = __builtin_amdgcn_mfma_f32_16x16x32_bf16(kf[kb][ks], qv, a, 0, 0, 0);
;                     }
;                     const float wh = wl[hh * 16];
; #pragma unroll
;                     for (int i = 0; i < 4; ++i) s[i] += wh * fmaxf(a[i], 0.f);
;                 }
;                 u32x4 kk; kk.x = fkey(s[0]); kk.y = fkey(s[1]); kk.z = fkey(s[2]); kk.w = fkey(s[3]);
;                 sc[j][2 * kh + kb] = kk;
; #pragma unroll
;                 for (int i = 0; i < 4; ++i) SEL_HADD((kk[i] >> 24) * 16 + q16);
;                 __builtin_amdgcn_sched_barrier(0);
	v_mfma_f32_16x16x32_bf16 v[206:209], v[42:45], v[238:241], 0
	v_mfma_f32_16x16x32_bf16 v[210:213], v[50:53], v[238:241], 0
	v_mfma_f32_16x16x32_bf16 v[206:209], v[46:49], v[242:245], v[206:209]
	v_mfma_f32_16x16x32_bf16 v[210:213], v[2:5], v[242:245], v[210:213]
	v_max_f32_e32 v9, 0, v246
	v_max_f32_e32 v200, 0, v247
	v_max_f32_e32 v201, 0, v248
	v_max_f32_e32 v216, 0, v249
	v_fmac_f32_e32 v178, v6, v9
	v_fmac_f32_e32 v177, v6, v200
	v_fmac_f32_e32 v186, v6, v201
	v_fmac_f32_e32 v181, v6, v216
	v_max_f32_e32 v9, 0, v250
	v_max_f32_e32 v200, 0, v251
	v_max_f32_e32 v201, 0, v252
	v_max_f32_e32 v216, 0, v253
	v_fmac_f32_e32 v188, v6, v9
	v_fmac_f32_e32 v187, v6, v200
	v_fmac_f32_e32 v190, v6, v201
	v_fmac_f32_e32 v189, v6, v216
	s_waitcnt lgkmcnt(0)
	v_max_f32_e32 v9, 0, v206
	v_max_f32_e32 v200, 0, v207
	v_max_f32_e32 v201, 0, v208
	v_max_f32_e32 v216, 0, v209
	v_fmac_f32_e32 v178, v7, v9
	v_fmac_f32_e32 v177, v7, v200
	v_fmac_f32_e32 v186, v7, v201
	v_fmac_f32_e32 v181, v7, v216
	v_max_f32_e32 v9, 0, v210
	v_max_f32_e32 v200, 0, v211
	v_max_f32_e32 v201, 0, v212
	v_max_f32_e32 v216, 0, v213
	v_fmac_f32_e32 v188, v7, v9
	v_fmac_f32_e32 v187, v7, v200
	v_fmac_f32_e32 v190, v7, v201
	v_fmac_f32_e32 v189, v7, v216
	v_ashrrev_i32_e32 v9, 31, v178
	v_bitop3_b32 v178, v9, v178, v8 bitop3:0x36
	v_ashrrev_i32_e32 v200, 31, v177
	v_bitop3_b32 v177, v200, v177, v8 bitop3:0x36
	v_ashrrev_i32_e32 v201, 31, v186
	v_bitop3_b32 v186, v201, v186, v8 bitop3:0x36
	v_ashrrev_i32_e32 v216, 31, v181
	v_bitop3_b32 v181, v216, v181, v8 bitop3:0x36
	v_ashrrev_i32_e32 v9, 31, v188
	v_bitop3_b32 v188, v9, v188, v8 bitop3:0x36
	v_ashrrev_i32_e32 v200, 31, v187
	v_bitop3_b32 v187, v200, v187, v8 bitop3:0x36
	v_ashrrev_i32_e32 v201, 31, v190
	v_bitop3_b32 v190, v201, v190, v8 bitop3:0x36
	v_ashrrev_i32_e32 v216, 31, v189
	v_bitop3_b32 v189, v216, v189, v8 bitop3:0x36
	v_lshrrev_b32_e32 v9, 24, v178
	v_lshl_add_u32 v9, v9, 6, v0
	ds_add_u32 v9, v205 offset:16384
	v_lshrrev_b32_e32 v200, 24, v177
	v_lshl_add_u32 v200, v200, 6, v0
	ds_add_u32 v200, v205 offset:16384
	v_lshrrev_b32_e32 v201, 24, v186
	v_lshl_add_u32 v201, v201, 6, v0
	ds_add_u32 v201, v205 offset:16384
	v_lshrrev_b32_e32 v216, 24, v181
	v_lshl_add_u32 v216, v216, 6, v0
	ds_add_u32 v216, v205 offset:16384
	v_lshrrev_b32_e32 v9, 24, v188
	v_lshl_add_u32 v9, v9, 6, v0
	ds_add_u32 v9, v205 offset:16384
	v_lshrrev_b32_e32 v200, 24, v187
	v_lshl_add_u32 v200, v200, 6, v0
	ds_add_u32 v200, v205 offset:16384
	v_lshrrev_b32_e32 v201, 24, v190
	v_lshl_add_u32 v201, v201, 6, v0
	ds_add_u32 v201, v205 offset:16384
	v_lshrrev_b32_e32 v216, 24, v189
	v_lshl_add_u32 v216, v216, 6, v0
	ds_add_u32 v216, v205 offset:16384
.LBB0_668:
	s_cmp_gt_i32 s4, 6
	s_cselect_b64 s[0:1], -1, 0
	s_cmp_lt_i32 s4, 7
	s_cbranch_scc1 .LBB0_670
	ds_read_b128 v[230:233], v182
	ds_read_b128 v[234:237], v183
	ds_read_b32 v6, v137 offset:320
	s_waitcnt vmcnt(0)
	v_add_co_u32_e32 v22, vcc, s96, v22
	s_nop 1
	v_addc_co_u32_e32 v23, vcc, 0, v23, vcc
	global_load_dwordx4 v[42:45], v[22:23], off
	global_load_dwordx4 v[46:49], v[22:23], off offset:64
	global_load_dwordx4 v[50:53], v[22:23], off offset:2048
	global_load_dwordx4 v[2:5], v[22:23], off offset:2112
	s_waitcnt lgkmcnt(1)
	v_mfma_f32_16x16x32_bf16 v[246:249], v[26:29], v[230:233], 0
	v_mfma_f32_16x16x32_bf16 v[250:253], v[34:37], v[230:233], 0
	v_mfma_f32_16x16x32_bf16 v[246:249], v[30:33], v[234:237], v[246:249]
	v_mfma_f32_16x16x32_bf16 v[250:253], v[38:41], v[234:237], v[250:253]
	ds_read_b128 v[238:241], v184
	ds_read_b128 v[242:245], v185
	ds_read_b32 v7, v137 offset:384
	s_waitcnt lgkmcnt(1)
	v_mfma_f32_16x16x32_bf16 v[206:209], v[26:29], v[238:241], 0
	v_mfma_f32_16x16x32_bf16 v[210:213], v[34:37], v[238:241], 0
	v_mfma_f32_16x16x32_bf16 v[206:209], v[30:33], v[242:245], v[206:209]
	v_mfma_f32_16x16x32_bf16 v[210:213], v[38:41], v[242:245], v[210:213]
	ds_read_b128 v[230:233], v179
	ds_read_b128 v[234:237], v180
	ds_read_b32 v217, v137 offset:448
	v_max_f32_e32 v9, 0, v246
	v_max_f32_e32 v200, 0, v247
	v_max_f32_e32 v201, 0, v248
	v_max_f32_e32 v216, 0, v249
	v_fma_f32 v192, v6, v9, 0
	v_fma_f32 v191, v6, v200, 0
	v_fma_f32 v194, v6, v201, 0
	v_fma_f32 v193, v6, v216, 0
	v_max_f32_e32 v9, 0, v250
	v_max_f32_e32 v200, 0, v251
	v_max_f32_e32 v201, 0, v252
	v_max_f32_e32 v216, 0, v253
	v_fma_f32 v196, v6, v9, 0
	v_fma_f32 v195, v6, v200, 0
	v_fma_f32 v198, v6, v201, 0
	v_fma_f32 v197, v6, v216, 0
	s_waitcnt lgkmcnt(1)
	v_mfma_f32_16x16x32_bf16 v[246:249], v[26:29], v[230:233], 0
	v_mfma_f32_16x16x32_bf16 v[250:253], v[34:37], v[230:233], 0
	v_mfma_f32_16x16x32_bf16 v[246:249], v[30:33], v[234:237], v[246:249]
	v_mfma_f32_16x16x32_bf16 v[250:253], v[38:41], v[234:237], v[250:253]
	ds_read_b128 v[238:241], v176
	ds_read_b128 v[242:245], v159
	ds_read_b32 v6, v137 offset:512
	v_max_f32_e32 v9, 0, v206
	v_max_f32_e32 v200, 0, v207
	v_max_f32_e32 v201, 0, v208
	v_max_f32_e32 v216, 0, v209
	v_fmac_f32_e32 v192, v7, v9
	v_fmac_f32_e32 v191, v7, v200
	v_fmac_f32_e32 v194, v7, v201
	v_fmac_f32_e32 v193, v7, v216
	v_max_f32_e32 v9, 0, v210
	v_max_f32_e32 v200, 0, v211
	v_max_f32_e32 v201, 0, v212
	v_max_f32_e32 v216, 0, v213
	v_fmac_f32_e32 v196, v7, v9
	v_fmac_f32_e32 v195, v7, v200
	v_fmac_f32_e32 v198, v7, v201
	v_fmac_f32_e32 v197, v7, v216
	s_waitcnt lgkmcnt(1)
; #define LAS __attribute__((address_space(3)))
; __device__ __forceinline__ unsigned fkey(float f) { const unsigned u = __float_as_uint(f); return (u & 0x80000000u) ? ~u : (u | 0x80000000u); }
; #define SEL_HADD(idx_) __hip_atomic_fetch_add(&hist[(idx_)], 1u, __ATOMIC_RELAXED, __HIP_MEMORY_SCOPE_WORKGROUP)
; __device__ __forceinline__ void sel_unit(LAS char* lds, int b, int u, const bf16_t* QI, const bf16_t* KIDX, const float* WIDX, unsigned long long* MASK) {
;     ...
;     for (int j = 0; j < 8; ++j) {
;         if (j < nj) {
;             int t = wid + 8 * j; asm volatile("" : "+s"(t));
; #pragma unroll
;             for (int kh = 0; kh < 2; ++kh) {
;             bf16x8 kf[2][2];
; #pragma unroll
;             for (int kb = 0; kb < 2; ++kb)
; #pragma unroll
;                 for (int ks = 0; ks < 2; ++ks) kf[kb][ks] = *(const bf16x8*)(KIDX + (rowbase + 64 * t + 32 * kh + 16 * kb + q16) * 64 + 32 * ks + 8 * kg);
; #pragma unroll
;             for (int kb = 0; kb < 2; ++kb) {
;                 f32x4 s = (f32x4){0.f, 0.f, 0.f, 0.f};
; #pragma unroll
;                 for (int hh = 0; hh < 8; ++hh) {
;                     f32x4 a = (f32x4){0.f, 0.f, 0.f, 0.f};
; #pragma unroll
;                     for (int ks = 0; ks < 2; ++ks) {
;                         const bf16x8 qv = *(const LAS bf16x8*)(lds + L_QI + q16 * 1024 + (((hh * 8 + 4 * ks + kg) ^ q16) << 4));
;                         a = __builtin_amdgcn_mfma_f32_16x16x32_bf16(kf[kb][ks], qv, a, 0, 0, 0);
;                     }
;                     const float wh = wl[hh * 16];
; #pragma unroll
;                     for (int i = 0; i < 4; ++i) s[i] += wh * fmaxf(a[i], 0.f);
;                 }
;                 u32x4 kk; kk.x = fkey(s[0]); kk.y = fkey(s[1]); kk.z = fkey(s[2]); kk.w = fkey(s[3]);
;                 sc[j][2 * kh + kb] = kk;
; #pragma unroll
;                 for (int i = 0; i < 4; ++i) SEL_HADD((kk[i] >> 24) * 16 + q16);
;                 __builtin_amdgcn_sched_barrier(0);
	v_mfma_f32_16x16x32_bf16 v[206:209], v[26:29], v[238:241], 0
	v_mfma_f32_16x16x32_bf16 v[210:213], v[34:37], v[238:241], 0
	v_mfma_f32_16x16x32_bf16 v[206:209], v[30:33], v[242:245], v[206:209]
	v_mfma_f32_16x16x32_bf16 v[210:213], v[38:41], v[242:245], v[210:213]
	ds_read_b128 v[230:233], v158
	ds_read_b128 v[234:237], v157
	ds_read_b32 v7, v137 offset:576
	v_max_f32_e32 v9, 0, v246
	v_max_f32_e32 v200, 0, v247
	v_max_f32_e32 v201, 0, v248
	v_max_f32_e32 v216, 0, v249
	v_fmac_f32_e32 v192, v217, v9
	v_fmac_f32_e32 v191, v217, v200
	v_fmac_f32_e32 v194, v217, v201
	v_fmac_f32_e32 v193, v217, v216
	v_max_f32_e32 v9, 0, v250
	v_max_f32_e32 v200, 0, v251
	v_max_f32_e32 v201, 0, v252
	v_max_f32_e32 v216, 0, v253
	v_fmac_f32_e32 v196, v217, v9
	v_fmac_f32_e32 v195, v217, v200
	v_fmac_f32_e32 v198, v217, v201
	v_fmac_f32_e32 v197, v217, v216
	s_waitcnt lgkmcnt(1)
	v_mfma_f32_16x16x32_bf16 v[246:249], v[26:29], v[230:233], 0
	v_mfma_f32_16x16x32_bf16 v[250:253], v[34:37], v[230:233], 0
	v_mfma_f32_16x16x32_bf16 v[246:249], v[30:33], v[234:237], v[246:249]
	v_mfma_f32_16x16x32_bf16 v[250:253], v[38:41], v[234:237], v[250:253]
	ds_read_b128 v[238:241], v156
	ds_read_b128 v[242:245], v155
	ds_read_b32 v217, v137 offset:640
	v_max_f32_e32 v9, 0, v206
	v_max_f32_e32 v200, 0, v207
	v_max_f32_e32 v201, 0, v208
	v_max_f32_e32 v216, 0, v209
	v_fmac_f32_e32 v192, v6, v9
	v_fmac_f32_e32 v191, v6, v200
	v_fmac_f32_e32 v194, v6, v201
	v_fmac_f32_e32 v193, v6, v216
	v_max_f32_e32 v9, 0, v210
	v_max_f32_e32 v200, 0, v211
	v_max_f32_e32 v201, 0, v212
	v_max_f32_e32 v216, 0, v213
	v_fmac_f32_e32 v196, v6, v9
	v_fmac_f32_e32 v195, v6, v200
	v_fmac_f32_e32 v198, v6, v201
	v_fmac_f32_e32 v197, v6, v216
	s_waitcnt lgkmcnt(1)
	v_mfma_f32_16x16x32_bf16 v[206:209], v[26:29], v[238:241], 0
	v_mfma_f32_16x16x32_bf16 v[210:213], v[34:37], v[238:241], 0
	v_mfma_f32_16x16x32_bf16 v[206:209], v[30:33], v[242:245], v[206:209]
	v_mfma_f32_16x16x32_bf16 v[210:213], v[38:41], v[242:245], v[210:213]
	ds_read_b128 v[230:233], v154
	ds_read_b128 v[234:237], v153
	ds_read_b32 v6, v137 offset:704
	v_max_f32_e32 v9, 0, v246
	v_max_f32_e32 v200, 0, v247
	v_max_f32_e32 v201, 0, v248
	v_max_f32_e32 v216, 0, v249
	v_fmac_f32_e32 v192, v7, v9
	v_fmac_f32_e32 v191, v7, v200
	v_fmac_f32_e32 v194, v7, v201
	v_fmac_f32_e32 v193, v7, v216
	v_max_f32_e32 v9, 0, v250
	v_max_f32_e32 v200, 0, v251
	v_max_f32_e32 v201, 0, v252
	v_max_f32_e32 v216, 0, v253
	v_fmac_f32_e32 v196, v7, v9
	v_fmac_f32_e32 v195, v7, v200
	v_fmac_f32_e32 v198, v7, v201
	v_fmac_f32_e32 v197, v7, v216
	s_waitcnt lgkmcnt(1)
	v_mfma_f32_16x16x32_bf16 v[246:249], v[26:29], v[230:233], 0
	v_mfma_f32_16x16x32_bf16 v[250:253], v[34:37], v[230:233], 0
	v_mfma_f32_16x16x32_bf16 v[246:249], v[30:33], v[234:237], v[246:249]
	v_mfma_f32_16x16x32_bf16 v[250:253], v[38:41], v[234:237], v[250:253]
	ds_read_b128 v[238:241], v152
	ds_read_b128 v[242:245], v151
	ds_read_b32 v7, v137 offset:768
	v_max_f32_e32 v9, 0, v206
	v_max_f32_e32 v200, 0, v207
	v_max_f32_e32 v201, 0, v208
	v_max_f32_e32 v216, 0, v209
	v_fmac_f32_e32 v192, v217, v9
	v_fmac_f32_e32 v191, v217, v200
	v_fmac_f32_e32 v194, v217, v201
	v_fmac_f32_e32 v193, v217, v216
	v_max_f32_e32 v9, 0, v210
	v_max_f32_e32 v200, 0, v211
	v_max_f32_e32 v201, 0, v212
	v_max_f32_e32 v216, 0, v213
	v_fmac_f32_e32 v196, v217, v9
	v_fmac_f32_e32 v195, v217, v200
	v_fmac_f32_e32 v198, v217, v201
	v_fmac_f32_e32 v197, v217, v216
	s_waitcnt lgkmcnt(1)
	v_mfma_f32_16x16x32_bf16 v[206:209], v[26:29], v[238:241], 0
	v_mfma_f32_16x16x32_bf16 v[210:213], v[34:37], v[238:241], 0
	v_mfma_f32_16x16x32_bf16 v[206:209], v[30:33], v[242:245], v[206:209]
	v_mfma_f32_16x16x32_bf16 v[210:213], v[38:41], v[242:245], v[210:213]
	v_max_f32_e32 v9, 0, v246
	v_max_f32_e32 v200, 0, v247
	v_max_f32_e32 v201, 0, v248
	v_max_f32_e32 v216, 0, v249
	v_fmac_f32_e32 v192, v6, v9
	v_fmac_f32_e32 v191, v6, v200
	v_fmac_f32_e32 v194, v6, v201
	v_fmac_f32_e32 v193, v6, v216
	v_max_f32_e32 v9, 0, v250
	v_max_f32_e32 v200, 0, v251
	v_max_f32_e32 v201, 0, v252
	v_max_f32_e32 v216, 0, v253
	v_fmac_f32_e32 v196, v6, v9
	v_fmac_f32_e32 v195, v6, v200
	v_fmac_f32_e32 v198, v6, v201
	v_fmac_f32_e32 v197, v6, v216
	s_waitcnt lgkmcnt(0)
	v_max_f32_e32 v9, 0, v206
	v_max_f32_e32 v200, 0, v207
	v_max_f32_e32 v201, 0, v208
	v_max_f32_e32 v216, 0, v209
	v_fmac_f32_e32 v192, v7, v9
	v_fmac_f32_e32 v191, v7, v200
	v_fmac_f32_e32 v194, v7, v201
	v_fmac_f32_e32 v193, v7, v216
	v_max_f32_e32 v9, 0, v210
	v_max_f32_e32 v200, 0, v211
	v_max_f32_e32 v201, 0, v212
	v_max_f32_e32 v216, 0, v213
	v_fmac_f32_e32 v196, v7, v9
	v_fmac_f32_e32 v195, v7, v200
	v_fmac_f32_e32 v198, v7, v201
	v_fmac_f32_e32 v197, v7, v216
	v_ashrrev_i32_e32 v9, 31, v192
	v_bitop3_b32 v192, v9, v192, v8 bitop3:0x36
	v_ashrrev_i32_e32 v200, 31, v191
	v_bitop3_b32 v191, v200, v191, v8 bitop3:0x36
	v_ashrrev_i32_e32 v201, 31, v194
	v_bitop3_b32 v194, v201, v194, v8 bitop3:0x36
	v_ashrrev_i32_e32 v216, 31, v193
	v_bitop3_b32 v193, v216, v193, v8 bitop3:0x36
	v_ashrrev_i32_e32 v9, 31, v196
	v_bitop3_b32 v196, v9, v196, v8 bitop3:0x36
	v_ashrrev_i32_e32 v200, 31, v195
	v_bitop3_b32 v195, v200, v195, v8 bitop3:0x36
	v_ashrrev_i32_e32 v201, 31, v198
	v_bitop3_b32 v198, v201, v198, v8 bitop3:0x36
	v_ashrrev_i32_e32 v216, 31, v197
	v_bitop3_b32 v197, v216, v197, v8 bitop3:0x36
	v_lshrrev_b32_e32 v9, 24, v192
	v_lshl_add_u32 v9, v9, 6, v0
	ds_add_u32 v9, v205 offset:16384
	v_lshrrev_b32_e32 v200, 24, v191
	v_lshl_add_u32 v200, v200, 6, v0
	ds_add_u32 v200, v205 offset:16384
	v_lshrrev_b32_e32 v201, 24, v194
	v_lshl_add_u32 v201, v201, 6, v0
	ds_add_u32 v201, v205 offset:16384
	v_lshrrev_b32_e32 v216, 24, v193
	v_lshl_add_u32 v216, v216, 6, v0
	ds_add_u32 v216, v205 offset:16384
	v_lshrrev_b32_e32 v9, 24, v196
	v_lshl_add_u32 v9, v9, 6, v0
	ds_add_u32 v9, v205 offset:16384
	v_lshrrev_b32_e32 v200, 24, v195
	v_lshl_add_u32 v200, v200, 6, v0
	ds_add_u32 v200, v205 offset:16384
	v_lshrrev_b32_e32 v201, 24, v198
	v_lshl_add_u32 v201, v201, 6, v0
	ds_add_u32 v201, v205 offset:16384
	v_lshrrev_b32_e32 v216, 24, v197
	v_lshl_add_u32 v216, v216, 6, v0
	ds_add_u32 v216, v205 offset:16384
	ds_read_b128 v[230:233], v182
	ds_read_b128 v[234:237], v183
	ds_read_b32 v6, v137 offset:320
	s_waitcnt vmcnt(0)
	s_cmp_lt_i32 s4, 8
	s_cbranch_scc1 .Lp0_nopf_6
	v_add_co_u32_e32 v22, vcc, 0xf000, v22
	s_nop 1
	v_addc_co_u32_e32 v23, vcc, 0, v23, vcc
	global_load_dwordx4 v[26:29], v[22:23], off
	global_load_dwordx4 v[30:33], v[22:23], off offset:64
	global_load_dwordx4 v[34:37], v[22:23], off offset:2048
	global_load_dwordx4 v[38:41], v[22:23], off offset:2112
; #define LAS __attribute__((address_space(3)))
; __device__ __forceinline__ unsigned fkey(float f) { const unsigned u = __float_as_uint(f); return (u & 0x80000000u) ? ~u : (u | 0x80000000u); }
; #define SEL_HADD(idx_) __hip_atomic_fetch_add(&hist[(idx_)], 1u, __ATOMIC_RELAXED, __HIP_MEMORY_SCOPE_WORKGROUP)
; __device__ __forceinline__ void sel_unit(LAS char* lds, int b, int u, const bf16_t* QI, const bf16_t* KIDX, const float* WIDX, unsigned long long* MASK) {
;     ...
;     for (int j = 0; j < 8; ++j) {
;         if (j < nj) {
;             int t = wid + 8 * j; asm volatile("" : "+s"(t));
; #pragma unroll
;             for (int kh = 0; kh < 2; ++kh) {
;             bf16x8 kf[2][2];
; #pragma unroll
;             for (int kb = 0; kb < 2; ++kb)
; #pragma unroll
;                 for (int ks = 0; ks < 2; ++ks) kf[kb][ks] = *(const bf16x8*)(KIDX + (rowbase + 64 * t + 32 * kh + 16 * kb + q16) * 64 + 32 * ks + 8 * kg);
; #pragma unroll
;             for (int kb = 0; kb < 2; ++kb) {
;                 f32x4 s = (f32x4){0.f, 0.f, 0.f, 0.f};
; #pragma unroll
;                 for (int hh = 0; hh < 8; ++hh) {
;                     f32x4 a = (f32x4){0.f, 0.f, 0.f, 0.f};
; #pragma unroll
;                     for (int ks = 0; ks < 2; ++ks) {
;                         const bf16x8 qv = *(const LAS bf16x8*)(lds + L_QI + q16 * 1024 + (((hh * 8 + 4 * ks + kg) ^ q16) << 4));
;                         a = __builtin_amdgcn_mfma_f32_16x16x32_bf16(kf[kb][ks], qv, a, 0, 0, 0);
;                     }
;                     const float wh = wl[hh * 16];
; #pragma unroll
;                     for (int i = 0; i < 4; ++i) s[i] += wh * fmaxf(a[i], 0.f);
;                 }
;                 u32x4 kk; kk.x = fkey(s[0]); kk.y = fkey(s[1]); kk.z = fkey(s[2]); kk.w = fkey(s[3]);
;                 sc[j][2 * kh + kb] = kk;
; #pragma unroll
;                 for (int i = 0; i < 4; ++i) SEL_HADD((kk[i] >> 24) * 16 + q16);
;                 __builtin_amdgcn_sched_barrier(0);
.Lp0_nopf_6:
	s_waitcnt lgkmcnt(1)
	v_mfma_f32_16x16x32_bf16 v[246:249], v[42:45], v[230:233], 0
	v_mfma_f32_16x16x32_bf16 v[250:253], v[50:53], v[230:233], 0
	v_mfma_f32_16x16x32_bf16 v[246:249], v[46:49], v[234:237], v[246:249]
	v_mfma_f32_16x16x32_bf16 v[250:253], v[2:5], v[234:237], v[250:253]
	ds_read_b128 v[238:241], v184
	ds_read_b128 v[242:245], v185
	ds_read_b32 v7, v137 offset:384
	s_waitcnt lgkmcnt(1)
	v_mfma_f32_16x16x32_bf16 v[206:209], v[42:45], v[238:241], 0
	v_mfma_f32_16x16x32_bf16 v[210:213], v[50:53], v[238:241], 0
	v_mfma_f32_16x16x32_bf16 v[206:209], v[46:49], v[242:245], v[206:209]
	v_mfma_f32_16x16x32_bf16 v[210:213], v[2:5], v[242:245], v[210:213]
	ds_read_b128 v[230:233], v179
	ds_read_b128 v[234:237], v180
	ds_read_b32 v217, v137 offset:448
	v_max_f32_e32 v9, 0, v246
	v_max_f32_e32 v200, 0, v247
	v_max_f32_e32 v201, 0, v248
	v_max_f32_e32 v216, 0, v249
	v_fma_f32 v57, v6, v9, 0
	v_fma_f32 v56, v6, v200, 0
	v_fma_f32 v55, v6, v201, 0
	v_fma_f32 v54, v6, v216, 0
	v_max_f32_e32 v9, 0, v250
	v_max_f32_e32 v200, 0, v251
	v_max_f32_e32 v201, 0, v252
	v_max_f32_e32 v216, 0, v253
	v_fma_f32 v218, v6, v9, 0
	v_fma_f32 v199, v6, v200, 0
	v_fma_f32 v220, v6, v201, 0
	v_fma_f32 v219, v6, v216, 0
	s_waitcnt lgkmcnt(1)
	v_mfma_f32_16x16x32_bf16 v[246:249], v[42:45], v[230:233], 0
	v_mfma_f32_16x16x32_bf16 v[250:253], v[50:53], v[230:233], 0
	v_mfma_f32_16x16x32_bf16 v[246:249], v[46:49], v[234:237], v[246:249]
	v_mfma_f32_16x16x32_bf16 v[250:253], v[2:5], v[234:237], v[250:253]
	ds_read_b128 v[238:241], v176
	ds_read_b128 v[242:245], v159
	ds_read_b32 v6, v137 offset:512
	v_max_f32_e32 v9, 0, v206
	v_max_f32_e32 v200, 0, v207
	v_max_f32_e32 v201, 0, v208
	v_max_f32_e32 v216, 0, v209
	v_fmac_f32_e32 v57, v7, v9
	v_fmac_f32_e32 v56, v7, v200
	v_fmac_f32_e32 v55, v7, v201
	v_fmac_f32_e32 v54, v7, v216
	v_max_f32_e32 v9, 0, v210
	v_max_f32_e32 v200, 0, v211
	v_max_f32_e32 v201, 0, v212
	v_max_f32_e32 v216, 0, v213
	v_fmac_f32_e32 v218, v7, v9
	v_fmac_f32_e32 v199, v7, v200
	v_fmac_f32_e32 v220, v7, v201
	v_fmac_f32_e32 v219, v7, v216
	s_waitcnt lgkmcnt(1)
	v_mfma_f32_16x16x32_bf16 v[206:209], v[42:45], v[238:241], 0
	v_mfma_f32_16x16x32_bf16 v[210:213], v[50:53], v[238:241], 0
	v_mfma_f32_16x16x32_bf16 v[206:209], v[46:49], v[242:245], v[206:209]
	v_mfma_f32_16x16x32_bf16 v[210:213], v[2:5], v[242:245], v[210:213]
	ds_read_b128 v[230:233], v158
	ds_read_b128 v[234:237], v157
	ds_read_b32 v7, v137 offset:576
	v_max_f32_e32 v9, 0, v246
	v_max_f32_e32 v200, 0, v247
	v_max_f32_e32 v201, 0, v248
	v_max_f32_e32 v216, 0, v249
	v_fmac_f32_e32 v57, v217, v9
	v_fmac_f32_e32 v56, v217, v200
	v_fmac_f32_e32 v55, v217, v201
	v_fmac_f32_e32 v54, v217, v216
	v_max_f32_e32 v9, 0, v250
	v_max_f32_e32 v200, 0, v251
	v_max_f32_e32 v201, 0, v252
	v_max_f32_e32 v216, 0, v253
	v_fmac_f32_e32 v218, v217, v9
	v_fmac_f32_e32 v199, v217, v200
	v_fmac_f32_e32 v220, v217, v201
	v_fmac_f32_e32 v219, v217, v216
	s_waitcnt lgkmcnt(1)
	v_mfma_f32_16x16x32_bf16 v[246:249], v[42:45], v[230:233], 0
	v_mfma_f32_16x16x32_bf16 v[250:253], v[50:53], v[230:233], 0
	v_mfma_f32_16x16x32_bf16 v[246:249], v[46:49], v[234:237], v[246:249]
	v_mfma_f32_16x16x32_bf16 v[250:253], v[2:5], v[234:237], v[250:253]
	ds_read_b128 v[238:241], v156
	ds_read_b128 v[242:245], v155
	ds_read_b32 v217, v137 offset:640
	v_max_f32_e32 v9, 0, v206
	v_max_f32_e32 v200, 0, v207
	v_max_f32_e32 v201, 0, v208
	v_max_f32_e32 v216, 0, v209
	v_fmac_f32_e32 v57, v6, v9
	v_fmac_f32_e32 v56, v6, v200
	v_fmac_f32_e32 v55, v6, v201
	v_fmac_f32_e32 v54, v6, v216
	v_max_f32_e32 v9, 0, v210
	v_max_f32_e32 v200, 0, v211
	v_max_f32_e32 v201, 0, v212
	v_max_f32_e32 v216, 0, v213
	v_fmac_f32_e32 v218, v6, v9
	v_fmac_f32_e32 v199, v6, v200
	v_fmac_f32_e32 v220, v6, v201
	v_fmac_f32_e32 v219, v6, v216
	s_waitcnt lgkmcnt(1)
	v_mfma_f32_16x16x32_bf16 v[206:209], v[42:45], v[238:241], 0
	v_mfma_f32_16x16x32_bf16 v[210:213], v[50:53], v[238:241], 0
	v_mfma_f32_16x16x32_bf16 v[206:209], v[46:49], v[242:245], v[206:209]
	v_mfma_f32_16x16x32_bf16 v[210:213], v[2:5], v[242:245], v[210:213]
	ds_read_b128 v[230:233], v154
	ds_read_b128 v[234:237], v153
	ds_read_b32 v6, v137 offset:704
	v_max_f32_e32 v9, 0, v246
	v_max_f32_e32 v200, 0, v247
	v_max_f32_e32 v201, 0, v248
	v_max_f32_e32 v216, 0, v249
	v_fmac_f32_e32 v57, v7, v9
	v_fmac_f32_e32 v56, v7, v200
	v_fmac_f32_e32 v55, v7, v201
	v_fmac_f32_e32 v54, v7, v216
	v_max_f32_e32 v9, 0, v250
	v_max_f32_e32 v200, 0, v251
	v_max_f32_e32 v201, 0, v252
	v_max_f32_e32 v216, 0, v253
	v_fmac_f32_e32 v218, v7, v9
	v_fmac_f32_e32 v199, v7, v200
	v_fmac_f32_e32 v220, v7, v201
	v_fmac_f32_e32 v219, v7, v216
	s_waitcnt lgkmcnt(1)
	v_mfma_f32_16x16x32_bf16 v[246:249], v[42:45], v[230:233], 0
	v_mfma_f32_16x16x32_bf16 v[250:253], v[50:53], v[230:233], 0
	v_mfma_f32_16x16x32_bf16 v[246:249], v[46:49], v[234:237], v[246:249]
	v_mfma_f32_16x16x32_bf16 v[250:253], v[2:5], v[234:237], v[250:253]
	ds_read_b128 v[238:241], v152
	ds_read_b128 v[242:245], v151
	ds_read_b32 v7, v137 offset:768
	v_max_f32_e32 v9, 0, v206
	v_max_f32_e32 v200, 0, v207
	v_max_f32_e32 v201, 0, v208
	v_max_f32_e32 v216, 0, v209
	v_fmac_f32_e32 v57, v217, v9
	v_fmac_f32_e32 v56, v217, v200
	v_fmac_f32_e32 v55, v217, v201
	v_fmac_f32_e32 v54, v217, v216
	v_max_f32_e32 v9, 0, v210
	v_max_f32_e32 v200, 0, v211
	v_max_f32_e32 v201, 0, v212
	v_max_f32_e32 v216, 0, v213
	v_fmac_f32_e32 v218, v217, v9
	v_fmac_f32_e32 v199, v217, v200
	v_fmac_f32_e32 v220, v217, v201
	v_fmac_f32_e32 v219, v217, v216
	s_waitcnt lgkmcnt(1)
; #define LAS __attribute__((address_space(3)))
; __device__ __forceinline__ unsigned fkey(float f) { const unsigned u = __float_as_uint(f); return (u & 0x80000000u) ? ~u : (u | 0x80000000u); }
; #define SEL_HADD(idx_) __hip_atomic_fetch_add(&hist[(idx_)], 1u, __ATOMIC_RELAXED, __HIP_MEMORY_SCOPE_WORKGROUP)
; __device__ __forceinline__ void sel_unit(LAS char* lds, int b, int u, const bf16_t* QI, const bf16_t* KIDX, const float* WIDX, unsigned long long* MASK) {
;     ...
;     for (int j = 0; j < 8; ++j) {
;         if (j < nj) {
;             int t = wid + 8 * j; asm volatile("" : "+s"(t));
; #pragma unroll
;             for (int kh = 0; kh < 2; ++kh) {
;             bf16x8 kf[2][2];
; #pragma unroll
;             for (int kb = 0; kb < 2; ++kb)
; #pragma unroll
;                 for (int ks = 0; ks < 2; ++ks) kf[kb][ks] = *(const bf16x8*)(KIDX + (rowbase + 64 * t + 32 * kh + 16 * kb + q16) * 64 + 32 * ks + 8 * kg);
; #pragma unroll
;             for (int kb = 0; kb < 2; ++kb) {
;                 f32x4 s = (f32x4){0.f, 0.f, 0.f, 0.f};
; #pragma unroll
;                 for (int hh = 0; hh < 8; ++hh) {
;                     f32x4 a = (f32x4){0.f, 0.f, 0.f, 0.f};
; #pragma unroll
;                     for (int ks = 0; ks < 2; ++ks) {
;                         const bf16x8 qv = *(const LAS bf16x8*)(lds + L_QI + q16 * 1024 + (((hh * 8 + 4 * ks + kg) ^ q16) << 4));
;                         a = __builtin_amdgcn_mfma_f32_16x16x32_bf16(kf[kb][ks], qv, a, 0, 0, 0);
;                     }
;                     const float wh = wl[hh * 16];
; #pragma unroll
;                     for (int i = 0; i < 4; ++i) s[i] += wh * fmaxf(a[i], 0.f);
;                 }
;                 u32x4 kk; kk.x = fkey(s[0]); kk.y = fkey(s[1]); kk.z = fkey(s[2]); kk.w = fkey(s[3]);
;                 sc[j][2 * kh + kb] = kk;
; #pragma unroll
;                 for (int i = 0; i < 4; ++i) SEL_HADD((kk[i] >> 24) * 16 + q16);
;                 __builtin_amdgcn_sched_barrier(0);
	v_mfma_f32_16x16x32_bf16 v[206:209], v[42:45], v[238:241], 0
	v_mfma_f32_16x16x32_bf16 v[210:213], v[50:53], v[238:241], 0
	v_mfma_f32_16x16x32_bf16 v[206:209], v[46:49], v[242:245], v[206:209]
	v_mfma_f32_16x16x32_bf16 v[210:213], v[2:5], v[242:245], v[210:213]
	v_max_f32_e32 v9, 0, v246
	v_max_f32_e32 v200, 0, v247
	v_max_f32_e32 v201, 0, v248
	v_max_f32_e32 v216, 0, v249
	v_fmac_f32_e32 v57, v6, v9
	v_fmac_f32_e32 v56, v6, v200
	v_fmac_f32_e32 v55, v6, v201
	v_fmac_f32_e32 v54, v6, v216
	v_max_f32_e32 v9, 0, v250
	v_max_f32_e32 v200, 0, v251
	v_max_f32_e32 v201, 0, v252
	v_max_f32_e32 v216, 0, v253
	v_fmac_f32_e32 v218, v6, v9
	v_fmac_f32_e32 v199, v6, v200
	v_fmac_f32_e32 v220, v6, v201
	v_fmac_f32_e32 v219, v6, v216
	s_waitcnt lgkmcnt(0)
	v_max_f32_e32 v9, 0, v206
	v_max_f32_e32 v200, 0, v207
	v_max_f32_e32 v201, 0, v208
	v_max_f32_e32 v216, 0, v209
	v_fmac_f32_e32 v57, v7, v9
	v_fmac_f32_e32 v56, v7, v200
	v_fmac_f32_e32 v55, v7, v201
	v_fmac_f32_e32 v54, v7, v216
	v_max_f32_e32 v9, 0, v210
	v_max_f32_e32 v200, 0, v211
	v_max_f32_e32 v201, 0, v212
	v_max_f32_e32 v216, 0, v213
	v_fmac_f32_e32 v218, v7, v9
	v_fmac_f32_e32 v199, v7, v200
	v_fmac_f32_e32 v220, v7, v201
	v_fmac_f32_e32 v219, v7, v216
	v_ashrrev_i32_e32 v9, 31, v57
	v_bitop3_b32 v57, v9, v57, v8 bitop3:0x36
	v_ashrrev_i32_e32 v200, 31, v56
	v_bitop3_b32 v56, v200, v56, v8 bitop3:0x36
	v_ashrrev_i32_e32 v201, 31, v55
	v_bitop3_b32 v55, v201, v55, v8 bitop3:0x36
	v_ashrrev_i32_e32 v216, 31, v54
	v_bitop3_b32 v54, v216, v54, v8 bitop3:0x36
	v_ashrrev_i32_e32 v9, 31, v218
	v_bitop3_b32 v218, v9, v218, v8 bitop3:0x36
	v_ashrrev_i32_e32 v200, 31, v199
	v_bitop3_b32 v199, v200, v199, v8 bitop3:0x36
	v_ashrrev_i32_e32 v201, 31, v220
	v_bitop3_b32 v220, v201, v220, v8 bitop3:0x36
	v_ashrrev_i32_e32 v216, 31, v219
	v_bitop3_b32 v219, v216, v219, v8 bitop3:0x36
	v_lshrrev_b32_e32 v9, 24, v57
	v_lshl_add_u32 v9, v9, 6, v0
	ds_add_u32 v9, v205 offset:16384
	v_lshrrev_b32_e32 v200, 24, v56
	v_lshl_add_u32 v200, v200, 6, v0
	ds_add_u32 v200, v205 offset:16384
	v_lshrrev_b32_e32 v201, 24, v55
	v_lshl_add_u32 v201, v201, 6, v0
	ds_add_u32 v201, v205 offset:16384
	v_lshrrev_b32_e32 v216, 24, v54
	v_lshl_add_u32 v216, v216, 6, v0
	ds_add_u32 v216, v205 offset:16384
	v_lshrrev_b32_e32 v9, 24, v218
	v_lshl_add_u32 v9, v9, 6, v0
	ds_add_u32 v9, v205 offset:16384
	v_lshrrev_b32_e32 v200, 24, v199
	v_lshl_add_u32 v200, v200, 6, v0
	ds_add_u32 v200, v205 offset:16384
	v_lshrrev_b32_e32 v201, 24, v220
	v_lshl_add_u32 v201, v201, 6, v0
	ds_add_u32 v201, v205 offset:16384
	v_lshrrev_b32_e32 v216, 24, v219
	v_lshl_add_u32 v216, v216, 6, v0
	ds_add_u32 v216, v205 offset:16384
.LBB0_670:
	s_cmp_gt_i32 s4, 7
	s_cselect_b64 s[26:27], -1, 0
	s_cmp_lt_i32 s4, 8
	s_cbranch_scc1 .LBB0_672
	ds_read_b128 v[230:233], v182
	ds_read_b128 v[234:237], v183
	ds_read_b32 v6, v137 offset:320
	s_waitcnt vmcnt(0)
	v_add_co_u32_e32 v22, vcc, s96, v22
	s_nop 1
	v_addc_co_u32_e32 v23, vcc, 0, v23, vcc
	global_load_dwordx4 v[42:45], v[22:23], off
	global_load_dwordx4 v[46:49], v[22:23], off offset:64
	global_load_dwordx4 v[50:53], v[22:23], off offset:2048
	global_load_dwordx4 v[2:5], v[22:23], off offset:2112
	s_waitcnt lgkmcnt(1)
	v_mfma_f32_16x16x32_bf16 v[246:249], v[26:29], v[230:233], 0
	v_mfma_f32_16x16x32_bf16 v[250:253], v[34:37], v[230:233], 0
	v_mfma_f32_16x16x32_bf16 v[246:249], v[30:33], v[234:237], v[246:249]
	v_mfma_f32_16x16x32_bf16 v[250:253], v[38:41], v[234:237], v[250:253]
	ds_read_b128 v[238:241], v184
	ds_read_b128 v[242:245], v185
	ds_read_b32 v7, v137 offset:384
	s_waitcnt lgkmcnt(1)
	v_mfma_f32_16x16x32_bf16 v[206:209], v[26:29], v[238:241], 0
	v_mfma_f32_16x16x32_bf16 v[210:213], v[34:37], v[238:241], 0
	v_mfma_f32_16x16x32_bf16 v[206:209], v[30:33], v[242:245], v[206:209]
	v_mfma_f32_16x16x32_bf16 v[210:213], v[38:41], v[242:245], v[210:213]
	ds_read_b128 v[230:233], v179
	ds_read_b128 v[234:237], v180
	ds_read_b32 v217, v137 offset:448
	v_max_f32_e32 v9, 0, v246
	v_max_f32_e32 v200, 0, v247
	v_max_f32_e32 v201, 0, v248
	v_max_f32_e32 v216, 0, v249
	v_fma_f32 v222, v6, v9, 0
	v_fma_f32 v221, v6, v200, 0
	v_fma_f32 v224, v6, v201, 0
	v_fma_f32 v223, v6, v216, 0
	v_max_f32_e32 v9, 0, v250
	v_max_f32_e32 v200, 0, v251
	v_max_f32_e32 v201, 0, v252
	v_max_f32_e32 v216, 0, v253
	v_fma_f32 v226, v6, v9, 0
	v_fma_f32 v225, v6, v200, 0
	v_fma_f32 v228, v6, v201, 0
	v_fma_f32 v227, v6, v216, 0
	s_waitcnt lgkmcnt(1)
	v_mfma_f32_16x16x32_bf16 v[246:249], v[26:29], v[230:233], 0
	v_mfma_f32_16x16x32_bf16 v[250:253], v[34:37], v[230:233], 0
	v_mfma_f32_16x16x32_bf16 v[246:249], v[30:33], v[234:237], v[246:249]
	v_mfma_f32_16x16x32_bf16 v[250:253], v[38:41], v[234:237], v[250:253]
	ds_read_b128 v[238:241], v176
	ds_read_b128 v[242:245], v159
	ds_read_b32 v6, v137 offset:512
	v_max_f32_e32 v9, 0, v206
	v_max_f32_e32 v200, 0, v207
	v_max_f32_e32 v201, 0, v208
	v_max_f32_e32 v216, 0, v209
	v_fmac_f32_e32 v222, v7, v9
	v_fmac_f32_e32 v221, v7, v200
	v_fmac_f32_e32 v224, v7, v201
	v_fmac_f32_e32 v223, v7, v216
	v_max_f32_e32 v9, 0, v210
	v_max_f32_e32 v200, 0, v211
	v_max_f32_e32 v201, 0, v212
	v_max_f32_e32 v216, 0, v213
	v_fmac_f32_e32 v226, v7, v9
	v_fmac_f32_e32 v225, v7, v200
	v_fmac_f32_e32 v228, v7, v201
	v_fmac_f32_e32 v227, v7, v216
	s_waitcnt lgkmcnt(1)
; #define LAS __attribute__((address_space(3)))
; __device__ __forceinline__ unsigned fkey(float f) { const unsigned u = __float_as_uint(f); return (u & 0x80000000u) ? ~u : (u | 0x80000000u); }
; #define SEL_HADD(idx_) __hip_atomic_fetch_add(&hist[(idx_)], 1u, __ATOMIC_RELAXED, __HIP_MEMORY_SCOPE_WORKGROUP)
; __device__ __forceinline__ void sel_unit(LAS char* lds, int b, int u, const bf16_t* QI, const bf16_t* KIDX, const float* WIDX, unsigned long long* MASK) {
;     ...
;     for (int j = 0; j < 8; ++j) {
;         if (j < nj) {
;             int t = wid + 8 * j; asm volatile("" : "+s"(t));
; #pragma unroll
;             for (int kh = 0; kh < 2; ++kh) {
;             bf16x8 kf[2][2];
; #pragma unroll
;             for (int kb = 0; kb < 2; ++kb)
; #pragma unroll
;                 for (int ks = 0; ks < 2; ++ks) kf[kb][ks] = *(const bf16x8*)(KIDX + (rowbase + 64 * t + 32 * kh + 16 * kb + q16) * 64 + 32 * ks + 8 * kg);
; #pragma unroll
;             for (int kb = 0; kb < 2; ++kb) {
;                 f32x4 s = (f32x4){0.f, 0.f, 0.f, 0.f};
; #pragma unroll
;                 for (int hh = 0; hh < 8; ++hh) {
;                     f32x4 a = (f32x4){0.f, 0.f, 0.f, 0.f};
; #pragma unroll
;                     for (int ks = 0; ks < 2; ++ks) {
;                         const bf16x8 qv = *(const LAS bf16x8*)(lds + L_QI + q16 * 1024 + (((hh * 8 + 4 * ks + kg) ^ q16) << 4));
;                         a = __builtin_amdgcn_mfma_f32_16x16x32_bf16(kf[kb][ks], qv, a, 0, 0, 0);
;                     }
;                     const float wh = wl[hh * 16];
; #pragma unroll
;                     for (int i = 0; i < 4; ++i) s[i] += wh * fmaxf(a[i], 0.f);
;                 }
;                 u32x4 kk; kk.x = fkey(s[0]); kk.y = fkey(s[1]); kk.z = fkey(s[2]); kk.w = fkey(s[3]);
;                 sc[j][2 * kh + kb] = kk;
; #pragma unroll
;                 for (int i = 0; i < 4; ++i) SEL_HADD((kk[i] >> 24) * 16 + q16);
;                 __builtin_amdgcn_sched_barrier(0);
	v_mfma_f32_16x16x32_bf16 v[206:209], v[26:29], v[238:241], 0
	v_mfma_f32_16x16x32_bf16 v[210:213], v[34:37], v[238:241], 0
	v_mfma_f32_16x16x32_bf16 v[206:209], v[30:33], v[242:245], v[206:209]
	v_mfma_f32_16x16x32_bf16 v[210:213], v[38:41], v[242:245], v[210:213]
	ds_read_b128 v[230:233], v158
	ds_read_b128 v[234:237], v157
	ds_read_b32 v7, v137 offset:576
	v_max_f32_e32 v9, 0, v246
	v_max_f32_e32 v200, 0, v247
	v_max_f32_e32 v201, 0, v248
	v_max_f32_e32 v216, 0, v249
	v_fmac_f32_e32 v222, v217, v9
	v_fmac_f32_e32 v221, v217, v200
	v_fmac_f32_e32 v224, v217, v201
	v_fmac_f32_e32 v223, v217, v216
	v_max_f32_e32 v9, 0, v250
	v_max_f32_e32 v200, 0, v251
	v_max_f32_e32 v201, 0, v252
	v_max_f32_e32 v216, 0, v253
	v_fmac_f32_e32 v226, v217, v9
	v_fmac_f32_e32 v225, v217, v200
	v_fmac_f32_e32 v228, v217, v201
	v_fmac_f32_e32 v227, v217, v216
	s_waitcnt lgkmcnt(1)
	v_mfma_f32_16x16x32_bf16 v[246:249], v[26:29], v[230:233], 0
	v_mfma_f32_16x16x32_bf16 v[250:253], v[34:37], v[230:233], 0
	v_mfma_f32_16x16x32_bf16 v[246:249], v[30:33], v[234:237], v[246:249]
	v_mfma_f32_16x16x32_bf16 v[250:253], v[38:41], v[234:237], v[250:253]
	ds_read_b128 v[238:241], v156
	ds_read_b128 v[242:245], v155
	ds_read_b32 v217, v137 offset:640
	v_max_f32_e32 v9, 0, v206
	v_max_f32_e32 v200, 0, v207
	v_max_f32_e32 v201, 0, v208
	v_max_f32_e32 v216, 0, v209
	v_fmac_f32_e32 v222, v6, v9
	v_fmac_f32_e32 v221, v6, v200
	v_fmac_f32_e32 v224, v6, v201
	v_fmac_f32_e32 v223, v6, v216
	v_max_f32_e32 v9, 0, v210
	v_max_f32_e32 v200, 0, v211
	v_max_f32_e32 v201, 0, v212
	v_max_f32_e32 v216, 0, v213
	v_fmac_f32_e32 v226, v6, v9
	v_fmac_f32_e32 v225, v6, v200
	v_fmac_f32_e32 v228, v6, v201
	v_fmac_f32_e32 v227, v6, v216
	s_waitcnt lgkmcnt(1)
	v_mfma_f32_16x16x32_bf16 v[206:209], v[26:29], v[238:241], 0
	v_mfma_f32_16x16x32_bf16 v[210:213], v[34:37], v[238:241], 0
	v_mfma_f32_16x16x32_bf16 v[206:209], v[30:33], v[242:245], v[206:209]
	v_mfma_f32_16x16x32_bf16 v[210:213], v[38:41], v[242:245], v[210:213]
	ds_read_b128 v[230:233], v154
	ds_read_b128 v[234:237], v153
	ds_read_b32 v6, v137 offset:704
	v_max_f32_e32 v9, 0, v246
	v_max_f32_e32 v200, 0, v247
	v_max_f32_e32 v201, 0, v248
	v_max_f32_e32 v216, 0, v249
	v_fmac_f32_e32 v222, v7, v9
	v_fmac_f32_e32 v221, v7, v200
	v_fmac_f32_e32 v224, v7, v201
	v_fmac_f32_e32 v223, v7, v216
	v_max_f32_e32 v9, 0, v250
	v_max_f32_e32 v200, 0, v251
	v_max_f32_e32 v201, 0, v252
	v_max_f32_e32 v216, 0, v253
	v_fmac_f32_e32 v226, v7, v9
	v_fmac_f32_e32 v225, v7, v200
	v_fmac_f32_e32 v228, v7, v201
	v_fmac_f32_e32 v227, v7, v216
	s_waitcnt lgkmcnt(1)
	v_mfma_f32_16x16x32_bf16 v[246:249], v[26:29], v[230:233], 0
	v_mfma_f32_16x16x32_bf16 v[250:253], v[34:37], v[230:233], 0
	v_mfma_f32_16x16x32_bf16 v[246:249], v[30:33], v[234:237], v[246:249]
	v_mfma_f32_16x16x32_bf16 v[250:253], v[38:41], v[234:237], v[250:253]
	ds_read_b128 v[238:241], v152
	ds_read_b128 v[242:245], v151
	ds_read_b32 v7, v137 offset:768
	v_max_f32_e32 v9, 0, v206
	v_max_f32_e32 v200, 0, v207
	v_max_f32_e32 v201, 0, v208
	v_max_f32_e32 v216, 0, v209
	v_fmac_f32_e32 v222, v217, v9
	v_fmac_f32_e32 v221, v217, v200
	v_fmac_f32_e32 v224, v217, v201
	v_fmac_f32_e32 v223, v217, v216
	v_max_f32_e32 v9, 0, v210
	v_max_f32_e32 v200, 0, v211
	v_max_f32_e32 v201, 0, v212
	v_max_f32_e32 v216, 0, v213
	v_fmac_f32_e32 v226, v217, v9
	v_fmac_f32_e32 v225, v217, v200
	v_fmac_f32_e32 v228, v217, v201
	v_fmac_f32_e32 v227, v217, v216
	s_waitcnt lgkmcnt(1)
	v_mfma_f32_16x16x32_bf16 v[206:209], v[26:29], v[238:241], 0
	v_mfma_f32_16x16x32_bf16 v[210:213], v[34:37], v[238:241], 0
	v_mfma_f32_16x16x32_bf16 v[206:209], v[30:33], v[242:245], v[206:209]
	v_mfma_f32_16x16x32_bf16 v[210:213], v[38:41], v[242:245], v[210:213]
	v_max_f32_e32 v9, 0, v246
	v_max_f32_e32 v200, 0, v247
	v_max_f32_e32 v201, 0, v248
	v_max_f32_e32 v216, 0, v249
	v_fmac_f32_e32 v222, v6, v9
	v_fmac_f32_e32 v221, v6, v200
	v_fmac_f32_e32 v224, v6, v201
	v_fmac_f32_e32 v223, v6, v216
	v_max_f32_e32 v9, 0, v250
	v_max_f32_e32 v200, 0, v251
	v_max_f32_e32 v201, 0, v252
	v_max_f32_e32 v216, 0, v253
	v_fmac_f32_e32 v226, v6, v9
	v_fmac_f32_e32 v225, v6, v200
	v_fmac_f32_e32 v228, v6, v201
	v_fmac_f32_e32 v227, v6, v216
	s_waitcnt lgkmcnt(0)
	v_max_f32_e32 v9, 0, v206
	v_max_f32_e32 v200, 0, v207
	v_max_f32_e32 v201, 0, v208
	v_max_f32_e32 v216, 0, v209
	v_fmac_f32_e32 v222, v7, v9
	v_fmac_f32_e32 v221, v7, v200
	v_fmac_f32_e32 v224, v7, v201
	v_fmac_f32_e32 v223, v7, v216
	v_max_f32_e32 v9, 0, v210
	v_max_f32_e32 v200, 0, v211
	v_max_f32_e32 v201, 0, v212
	v_max_f32_e32 v216, 0, v213
	v_fmac_f32_e32 v226, v7, v9
	v_fmac_f32_e32 v225, v7, v200
	v_fmac_f32_e32 v228, v7, v201
	v_fmac_f32_e32 v227, v7, v216
	v_ashrrev_i32_e32 v9, 31, v222
	v_bitop3_b32 v222, v9, v222, v8 bitop3:0x36
	v_ashrrev_i32_e32 v200, 31, v221
	v_bitop3_b32 v221, v200, v221, v8 bitop3:0x36
	v_ashrrev_i32_e32 v201, 31, v224
	v_bitop3_b32 v224, v201, v224, v8 bitop3:0x36
	v_ashrrev_i32_e32 v216, 31, v223
	v_bitop3_b32 v223, v216, v223, v8 bitop3:0x36
	v_ashrrev_i32_e32 v9, 31, v226
	v_bitop3_b32 v226, v9, v226, v8 bitop3:0x36
	v_ashrrev_i32_e32 v200, 31, v225
	v_bitop3_b32 v225, v200, v225, v8 bitop3:0x36
	v_ashrrev_i32_e32 v201, 31, v228
	v_bitop3_b32 v228, v201, v228, v8 bitop3:0x36
	v_ashrrev_i32_e32 v216, 31, v227
	v_bitop3_b32 v227, v216, v227, v8 bitop3:0x36
	v_lshrrev_b32_e32 v9, 24, v222
	v_lshl_add_u32 v9, v9, 6, v0
	ds_add_u32 v9, v205 offset:16384
	v_lshrrev_b32_e32 v200, 24, v221
	v_lshl_add_u32 v200, v200, 6, v0
	ds_add_u32 v200, v205 offset:16384
	v_lshrrev_b32_e32 v201, 24, v224
	v_lshl_add_u32 v201, v201, 6, v0
	ds_add_u32 v201, v205 offset:16384
	v_lshrrev_b32_e32 v216, 24, v223
	v_lshl_add_u32 v216, v216, 6, v0
	ds_add_u32 v216, v205 offset:16384
	v_lshrrev_b32_e32 v9, 24, v226
	v_lshl_add_u32 v9, v9, 6, v0
	ds_add_u32 v9, v205 offset:16384
	v_lshrrev_b32_e32 v200, 24, v225
	v_lshl_add_u32 v200, v200, 6, v0
	ds_add_u32 v200, v205 offset:16384
	v_lshrrev_b32_e32 v201, 24, v228
	v_lshl_add_u32 v201, v201, 6, v0
	ds_add_u32 v201, v205 offset:16384
	v_lshrrev_b32_e32 v216, 24, v227
	v_lshl_add_u32 v216, v216, 6, v0
	ds_add_u32 v216, v205 offset:16384
	ds_read_b128 v[230:233], v182
	ds_read_b128 v[234:237], v183
	ds_read_b32 v6, v137 offset:320
	s_waitcnt vmcnt(0)
; #define LAS __attribute__((address_space(3)))
; __device__ __forceinline__ unsigned fkey(float f) { const unsigned u = __float_as_uint(f); return (u & 0x80000000u) ? ~u : (u | 0x80000000u); }
; #define SEL_HADD(idx_) __hip_atomic_fetch_add(&hist[(idx_)], 1u, __ATOMIC_RELAXED, __HIP_MEMORY_SCOPE_WORKGROUP)
; __device__ __forceinline__ void sel_unit(LAS char* lds, int b, int u, const bf16_t* QI, const bf16_t* KIDX, const float* WIDX, unsigned long long* MASK) {
;     ...
;     for (int j = 0; j < 8; ++j) {
;         if (j < nj) {
;             int t = wid + 8 * j; asm volatile("" : "+s"(t));
; #pragma unroll
;             for (int kh = 0; kh < 2; ++kh) {
;             bf16x8 kf[2][2];
; #pragma unroll
;             for (int kb = 0; kb < 2; ++kb)
; #pragma unroll
;                 for (int ks = 0; ks < 2; ++ks) kf[kb][ks] = *(const bf16x8*)(KIDX + (rowbase + 64 * t + 32 * kh + 16 * kb + q16) * 64 + 32 * ks + 8 * kg);
; #pragma unroll
;             for (int kb = 0; kb < 2; ++kb) {
;                 f32x4 s = (f32x4){0.f, 0.f, 0.f, 0.f};
; #pragma unroll
;                 for (int hh = 0; hh < 8; ++hh) {
;                     f32x4 a = (f32x4){0.f, 0.f, 0.f, 0.f};
; #pragma unroll
;                     for (int ks = 0; ks < 2; ++ks) {
;                         const bf16x8 qv = *(const LAS bf16x8*)(lds + L_QI + q16 * 1024 + (((hh * 8 + 4 * ks + kg) ^ q16) << 4));
;                         a = __builtin_amdgcn_mfma_f32_16x16x32_bf16(kf[kb][ks], qv, a, 0, 0, 0);
;                     }
;                     const float wh = wl[hh * 16];
; #pragma unroll
;                     for (int i = 0; i < 4; ++i) s[i] += wh * fmaxf(a[i], 0.f);
;                 }
;                 u32x4 kk; kk.x = fkey(s[0]); kk.y = fkey(s[1]); kk.z = fkey(s[2]); kk.w = fkey(s[3]);
;                 sc[j][2 * kh + kb] = kk;
; #pragma unroll
;                 for (int i = 0; i < 4; ++i) SEL_HADD((kk[i] >> 24) * 16 + q16);
;                 __builtin_amdgcn_sched_barrier(0);
	s_waitcnt lgkmcnt(1)
	v_mfma_f32_16x16x32_bf16 v[246:249], v[42:45], v[230:233], 0
	v_mfma_f32_16x16x32_bf16 v[250:253], v[50:53], v[230:233], 0
	v_mfma_f32_16x16x32_bf16 v[246:249], v[46:49], v[234:237], v[246:249]
	v_mfma_f32_16x16x32_bf16 v[250:253], v[2:5], v[234:237], v[250:253]
	ds_read_b128 v[238:241], v184
	ds_read_b128 v[242:245], v185
	ds_read_b32 v7, v137 offset:384
	s_waitcnt lgkmcnt(1)
	v_mfma_f32_16x16x32_bf16 v[206:209], v[42:45], v[238:241], 0
	v_mfma_f32_16x16x32_bf16 v[210:213], v[50:53], v[238:241], 0
	v_mfma_f32_16x16x32_bf16 v[206:209], v[46:49], v[242:245], v[206:209]
	v_mfma_f32_16x16x32_bf16 v[210:213], v[2:5], v[242:245], v[210:213]
	ds_read_b128 v[230:233], v179
	ds_read_b128 v[234:237], v180
	ds_read_b32 v217, v137 offset:448
	v_max_f32_e32 v9, 0, v246
	v_max_f32_e32 v200, 0, v247
	v_max_f32_e32 v201, 0, v248
	v_max_f32_e32 v216, 0, v249
	v_fma_f32 v11, v6, v9, 0
	v_fma_f32 v10, v6, v200, 0
	v_fma_f32 v13, v6, v201, 0
	v_fma_f32 v12, v6, v216, 0
	v_max_f32_e32 v9, 0, v250
	v_max_f32_e32 v200, 0, v251
	v_max_f32_e32 v201, 0, v252
	v_max_f32_e32 v216, 0, v253
	v_fma_f32 v15, v6, v9, 0
	v_fma_f32 v14, v6, v200, 0
	v_fma_f32 v17, v6, v201, 0
	v_fma_f32 v16, v6, v216, 0
	s_waitcnt lgkmcnt(1)
	v_mfma_f32_16x16x32_bf16 v[246:249], v[42:45], v[230:233], 0
	v_mfma_f32_16x16x32_bf16 v[250:253], v[50:53], v[230:233], 0
	v_mfma_f32_16x16x32_bf16 v[246:249], v[46:49], v[234:237], v[246:249]
	v_mfma_f32_16x16x32_bf16 v[250:253], v[2:5], v[234:237], v[250:253]
	ds_read_b128 v[238:241], v176
	ds_read_b128 v[242:245], v159
	ds_read_b32 v6, v137 offset:512
	v_max_f32_e32 v9, 0, v206
	v_max_f32_e32 v200, 0, v207
	v_max_f32_e32 v201, 0, v208
	v_max_f32_e32 v216, 0, v209
	v_fmac_f32_e32 v11, v7, v9
	v_fmac_f32_e32 v10, v7, v200
	v_fmac_f32_e32 v13, v7, v201
	v_fmac_f32_e32 v12, v7, v216
	v_max_f32_e32 v9, 0, v210
	v_max_f32_e32 v200, 0, v211
	v_max_f32_e32 v201, 0, v212
	v_max_f32_e32 v216, 0, v213
	v_fmac_f32_e32 v15, v7, v9
	v_fmac_f32_e32 v14, v7, v200
	v_fmac_f32_e32 v17, v7, v201
	v_fmac_f32_e32 v16, v7, v216
	s_waitcnt lgkmcnt(1)
	v_mfma_f32_16x16x32_bf16 v[206:209], v[42:45], v[238:241], 0
	v_mfma_f32_16x16x32_bf16 v[210:213], v[50:53], v[238:241], 0
	v_mfma_f32_16x16x32_bf16 v[206:209], v[46:49], v[242:245], v[206:209]
	v_mfma_f32_16x16x32_bf16 v[210:213], v[2:5], v[242:245], v[210:213]
	ds_read_b128 v[230:233], v158
	ds_read_b128 v[234:237], v157
	ds_read_b32 v7, v137 offset:576
	v_max_f32_e32 v9, 0, v246
	v_max_f32_e32 v200, 0, v247
	v_max_f32_e32 v201, 0, v248
	v_max_f32_e32 v216, 0, v249
	v_fmac_f32_e32 v11, v217, v9
	v_fmac_f32_e32 v10, v217, v200
	v_fmac_f32_e32 v13, v217, v201
	v_fmac_f32_e32 v12, v217, v216
	v_max_f32_e32 v9, 0, v250
	v_max_f32_e32 v200, 0, v251
	v_max_f32_e32 v201, 0, v252
	v_max_f32_e32 v216, 0, v253
	v_fmac_f32_e32 v15, v217, v9
	v_fmac_f32_e32 v14, v217, v200
	v_fmac_f32_e32 v17, v217, v201
	v_fmac_f32_e32 v16, v217, v216
	s_waitcnt lgkmcnt(1)
	v_mfma_f32_16x16x32_bf16 v[246:249], v[42:45], v[230:233], 0
	v_mfma_f32_16x16x32_bf16 v[250:253], v[50:53], v[230:233], 0
	v_mfma_f32_16x16x32_bf16 v[246:249], v[46:49], v[234:237], v[246:249]
	v_mfma_f32_16x16x32_bf16 v[250:253], v[2:5], v[234:237], v[250:253]
	ds_read_b128 v[238:241], v156
	ds_read_b128 v[242:245], v155
	ds_read_b32 v217, v137 offset:640
	v_max_f32_e32 v9, 0, v206
	v_max_f32_e32 v200, 0, v207
	v_max_f32_e32 v201, 0, v208
	v_max_f32_e32 v216, 0, v209
	v_fmac_f32_e32 v11, v6, v9
	v_fmac_f32_e32 v10, v6, v200
	v_fmac_f32_e32 v13, v6, v201
	v_fmac_f32_e32 v12, v6, v216
	v_max_f32_e32 v9, 0, v210
	v_max_f32_e32 v200, 0, v211
	v_max_f32_e32 v201, 0, v212
	v_max_f32_e32 v216, 0, v213
	v_fmac_f32_e32 v15, v6, v9
	v_fmac_f32_e32 v14, v6, v200
	v_fmac_f32_e32 v17, v6, v201
	v_fmac_f32_e32 v16, v6, v216
	s_waitcnt lgkmcnt(1)
; #define LAS __attribute__((address_space(3)))
; __device__ __forceinline__ unsigned fkey(float f) { const unsigned u = __float_as_uint(f); return (u & 0x80000000u) ? ~u : (u | 0x80000000u); }
; #define SEL_HADD(idx_) __hip_atomic_fetch_add(&hist[(idx_)], 1u, __ATOMIC_RELAXED, __HIP_MEMORY_SCOPE_WORKGROUP)
; __device__ __forceinline__ void sel_unit(LAS char* lds, int b, int u, const bf16_t* QI, const bf16_t* KIDX, const float* WIDX, unsigned long long* MASK) {
;     ...
;     for (int j = 0; j < 8; ++j) {
;         if (j < nj) {
;             int t = wid + 8 * j; asm volatile("" : "+s"(t));
; #pragma unroll
;             for (int kh = 0; kh < 2; ++kh) {
;             bf16x8 kf[2][2];
; #pragma unroll
;             for (int kb = 0; kb < 2; ++kb)
; #pragma unroll
;                 for (int ks = 0; ks < 2; ++ks) kf[kb][ks] = *(const bf16x8*)(KIDX + (rowbase + 64 * t + 32 * kh + 16 * kb + q16) * 64 + 32 * ks + 8 * kg);
; #pragma unroll
;             for (int kb = 0; kb < 2; ++kb) {
;                 f32x4 s = (f32x4){0.f, 0.f, 0.f, 0.f};
; #pragma unroll
;                 for (int hh = 0; hh < 8; ++hh) {
;                     f32x4 a = (f32x4){0.f, 0.f, 0.f, 0.f};
; #pragma unroll
;                     for (int ks = 0; ks < 2; ++ks) {
;                         const bf16x8 qv = *(const LAS bf16x8*)(lds + L_QI + q16 * 1024 + (((hh * 8 + 4 * ks + kg) ^ q16) << 4));
;                         a = __builtin_amdgcn_mfma_f32_16x16x32_bf16(kf[kb][ks], qv, a, 0, 0, 0);
;                     }
;                     const float wh = wl[hh * 16];
; #pragma unroll
;                     for (int i = 0; i < 4; ++i) s[i] += wh * fmaxf(a[i], 0.f);
;                 }
;                 u32x4 kk; kk.x = fkey(s[0]); kk.y = fkey(s[1]); kk.z = fkey(s[2]); kk.w = fkey(s[3]);
;                 sc[j][2 * kh + kb] = kk;
; #pragma unroll
;                 for (int i = 0; i < 4; ++i) SEL_HADD((kk[i] >> 24) * 16 + q16);
;                 __builtin_amdgcn_sched_barrier(0);
	v_mfma_f32_16x16x32_bf16 v[206:209], v[42:45], v[238:241], 0
	v_mfma_f32_16x16x32_bf16 v[210:213], v[50:53], v[238:241], 0
	v_mfma_f32_16x16x32_bf16 v[206:209], v[46:49], v[242:245], v[206:209]
	v_mfma_f32_16x16x32_bf16 v[210:213], v[2:5], v[242:245], v[210:213]
	ds_read_b128 v[230:233], v154
	ds_read_b128 v[234:237], v153
	ds_read_b32 v6, v137 offset:704
	v_max_f32_e32 v9, 0, v246
	v_max_f32_e32 v200, 0, v247
	v_max_f32_e32 v201, 0, v248
	v_max_f32_e32 v216, 0, v249
	v_fmac_f32_e32 v11, v7, v9
	v_fmac_f32_e32 v10, v7, v200
	v_fmac_f32_e32 v13, v7, v201
	v_fmac_f32_e32 v12, v7, v216
	v_max_f32_e32 v9, 0, v250
	v_max_f32_e32 v200, 0, v251
	v_max_f32_e32 v201, 0, v252
	v_max_f32_e32 v216, 0, v253
	v_fmac_f32_e32 v15, v7, v9
	v_fmac_f32_e32 v14, v7, v200
	v_fmac_f32_e32 v17, v7, v201
	v_fmac_f32_e32 v16, v7, v216
	s_waitcnt lgkmcnt(1)
	v_mfma_f32_16x16x32_bf16 v[246:249], v[42:45], v[230:233], 0
	v_mfma_f32_16x16x32_bf16 v[250:253], v[50:53], v[230:233], 0
	v_mfma_f32_16x16x32_bf16 v[246:249], v[46:49], v[234:237], v[246:249]
	v_mfma_f32_16x16x32_bf16 v[250:253], v[2:5], v[234:237], v[250:253]
	ds_read_b128 v[238:241], v152
	ds_read_b128 v[242:245], v151
	ds_read_b32 v7, v137 offset:768
	v_max_f32_e32 v9, 0, v206
	v_max_f32_e32 v200, 0, v207
	v_max_f32_e32 v201, 0, v208
	v_max_f32_e32 v216, 0, v209
	v_fmac_f32_e32 v11, v217, v9
	v_fmac_f32_e32 v10, v217, v200
	v_fmac_f32_e32 v13, v217, v201
	v_fmac_f32_e32 v12, v217, v216
	v_max_f32_e32 v9, 0, v210
	v_max_f32_e32 v200, 0, v211
	v_max_f32_e32 v201, 0, v212
	v_max_f32_e32 v216, 0, v213
	v_fmac_f32_e32 v15, v217, v9
	v_fmac_f32_e32 v14, v217, v200
	v_fmac_f32_e32 v17, v217, v201
	v_fmac_f32_e32 v16, v217, v216
	s_waitcnt lgkmcnt(1)
	v_mfma_f32_16x16x32_bf16 v[206:209], v[42:45], v[238:241], 0
	v_mfma_f32_16x16x32_bf16 v[210:213], v[50:53], v[238:241], 0
	v_mfma_f32_16x16x32_bf16 v[206:209], v[46:49], v[242:245], v[206:209]
	v_mfma_f32_16x16x32_bf16 v[210:213], v[2:5], v[242:245], v[210:213]
	v_max_f32_e32 v9, 0, v246
	v_max_f32_e32 v200, 0, v247
	v_max_f32_e32 v201, 0, v248
	v_max_f32_e32 v216, 0, v249
	v_fmac_f32_e32 v11, v6, v9
	v_fmac_f32_e32 v10, v6, v200
	v_fmac_f32_e32 v13, v6, v201
	v_fmac_f32_e32 v12, v6, v216
	v_max_f32_e32 v9, 0, v250
	v_max_f32_e32 v200, 0, v251
	v_max_f32_e32 v201, 0, v252
	v_max_f32_e32 v216, 0, v253
	v_fmac_f32_e32 v15, v6, v9
	v_fmac_f32_e32 v14, v6, v200
	v_fmac_f32_e32 v17, v6, v201
	v_fmac_f32_e32 v16, v6, v216
	s_waitcnt lgkmcnt(0)
	v_max_f32_e32 v9, 0, v206
	v_max_f32_e32 v200, 0, v207
	v_max_f32_e32 v201, 0, v208
	v_max_f32_e32 v216, 0, v209
	v_fmac_f32_e32 v11, v7, v9
	v_fmac_f32_e32 v10, v7, v200
	v_fmac_f32_e32 v13, v7, v201
	v_fmac_f32_e32 v12, v7, v216
	v_max_f32_e32 v9, 0, v210
	v_max_f32_e32 v200, 0, v211
	v_max_f32_e32 v201, 0, v212
	v_max_f32_e32 v216, 0, v213
	v_fmac_f32_e32 v15, v7, v9
	v_fmac_f32_e32 v14, v7, v200
	v_fmac_f32_e32 v17, v7, v201
	v_fmac_f32_e32 v16, v7, v216
	v_ashrrev_i32_e32 v9, 31, v11
	v_bitop3_b32 v11, v9, v11, v8 bitop3:0x36
	v_ashrrev_i32_e32 v200, 31, v10
	v_bitop3_b32 v10, v200, v10, v8 bitop3:0x36
	v_ashrrev_i32_e32 v201, 31, v13
	v_bitop3_b32 v13, v201, v13, v8 bitop3:0x36
	v_ashrrev_i32_e32 v216, 31, v12
	v_bitop3_b32 v12, v216, v12, v8 bitop3:0x36
	v_ashrrev_i32_e32 v9, 31, v15
	v_bitop3_b32 v15, v9, v15, v8 bitop3:0x36
	v_ashrrev_i32_e32 v200, 31, v14
	v_bitop3_b32 v14, v200, v14, v8 bitop3:0x36
	v_ashrrev_i32_e32 v201, 31, v17
	v_bitop3_b32 v17, v201, v17, v8 bitop3:0x36
	v_ashrrev_i32_e32 v216, 31, v16
	v_bitop3_b32 v16, v216, v16, v8 bitop3:0x36
	v_lshrrev_b32_e32 v9, 24, v11
	v_lshl_add_u32 v9, v9, 6, v0
	ds_add_u32 v9, v205 offset:16384
	v_lshrrev_b32_e32 v200, 24, v10
	v_lshl_add_u32 v200, v200, 6, v0
	ds_add_u32 v200, v205 offset:16384
	v_lshrrev_b32_e32 v201, 24, v13
	v_lshl_add_u32 v201, v201, 6, v0
	ds_add_u32 v201, v205 offset:16384
	v_lshrrev_b32_e32 v216, 24, v12
	v_lshl_add_u32 v216, v216, 6, v0
	ds_add_u32 v216, v205 offset:16384
	v_lshrrev_b32_e32 v9, 24, v15
	v_lshl_add_u32 v9, v9, 6, v0
	ds_add_u32 v9, v205 offset:16384
	v_lshrrev_b32_e32 v200, 24, v14
	v_lshl_add_u32 v200, v200, 6, v0
	ds_add_u32 v200, v205 offset:16384
	v_lshrrev_b32_e32 v201, 24, v17
	v_lshl_add_u32 v201, v201, 6, v0
	ds_add_u32 v201, v205 offset:16384
	v_lshrrev_b32_e32 v216, 24, v16
	v_lshl_add_u32 v216, v216, 6, v0
	ds_add_u32 v216, v205 offset:16384
